# P1 epilogue rewritten by hand: 1/rms requested at tile start, rotary table rows loaded in batches of 8 pieces (was one load + wait at a time), in-place scale/rope/pack
# speedup vs baseline: 1.2709x; 1.0123x over previous
.LBB0_164:
	v_readfirstlane_b32 s6, v214
	v_and_b32_e32 v100, 15, v214
	s_lshr_b32 s6, s6, 8
	s_lshl_b32 s6, s6, 6
	s_lshl_b32 s7, s81, 8
	s_add_i32 s6, s6, s7
	v_add_lshl_u32 v100, v100, s6, 2
	global_load_dword v248, v100, s[16:17] offset:0
	global_load_dword v249, v100, s[16:17] offset:64
	global_load_dword v250, v100, s[16:17] offset:128
	global_load_dword v251, v100, s[16:17] offset:192
	global_load_dword v252, v100, s[16:17] offset:512
	global_load_dword v253, v100, s[16:17] offset:576
	global_load_dword v254, v100, s[16:17] offset:640
	global_load_dword v255, v100, s[16:17] offset:704
	s_add_i32 s60, s60, 1
	s_mul_i32 s6, s60, s74
	s_mul_hi_u32 s7, s60, s75
	s_add_i32 s7, s7, s6
	s_mul_i32 s6, s60, s75
	s_add_u32 s42, s6, s2
	s_addc_u32 s43, s7, s76
	v_cmp_gt_i64_e32 vcc, s[42:43], v[150:151]
	v_cmp_lt_i64_e64 s[6:7], s[42:43], v[148:149]
	s_cbranch_vccnz .LBB0_166
	s_ashr_i32 s11, s42, 31
	s_lshr_b32 s11, s11, 29
	s_add_i32 s11, s42, s11
	s_ashr_i32 s20, s11, 3
	s_and_b32 s11, s11, -8
	s_sub_i32 s11, s42, s11
	s_cmp_lt_i32 s11, 0
	s_movk_i32 s21, 0xf1
	s_cselect_b32 s21, s21, 0xf0
	s_mul_i32 s11, s11, s21
	s_add_i32 s11, s11, s20
	s_mul_hi_i32 s20, s11, 0x66666667
	s_lshr_b32 s21, s20, 31
	s_ashr_i32 s20, s20, 5
	s_add_i32 s20, s20, s21
	s_lshl_b32 s21, s20, 3
	s_sub_i32 s24, 0xc0, s21
	s_min_i32 s24, s24, 8
	s_abs_i32 s25, s24
	v_cvt_f32_u32_e32 v0, s25
	s_sub_i32 s40, 0, s25
	s_mulk_i32 s20, 0x50
	s_sub_i32 s11, s11, s20
	v_rcp_iflag_f32_e32 v0, v0
	s_abs_i32 s20, s11
	s_xor_b32 s33, s11, s24
	s_ashr_i32 s33, s33, 31
	v_mul_f32_e32 v0, 0x4f7ffffe, v0
	v_cvt_u32_f32_e32 v0, v0
	s_nop 0
	v_readfirstlane_b32 s41, v0
	s_mul_i32 s40, s40, s41
	s_mul_hi_u32 s40, s41, s40
	s_add_i32 s41, s41, s40
	s_mul_hi_u32 s40, s20, s41
	s_mul_i32 s41, s40, s25
	s_sub_i32 s20, s20, s41
	s_add_i32 s42, s40, 1
	s_sub_i32 s41, s20, s25
	s_cmp_ge_u32 s20, s25
	s_cselect_b32 s40, s42, s40
	s_cselect_b32 s20, s41, s20
	s_add_i32 s41, s40, 1
	s_cmp_ge_u32 s20, s25
	s_cselect_b32 s20, s41, s40
	s_xor_b32 s20, s20, s33
	s_sub_i32 s40, s20, s33
	s_mul_i32 s20, s40, s24
	s_sub_i32 s11, s11, s20
	s_add_i32 s80, s21, s11

.LBB0_170:
	v_readfirstlane_b32 s8, v214
	v_and_b32_e32 v152, 15, v214
	v_bfe_u32 v153, v214, 4, 2
	s_lshr_b32 s8, s8, 6
	s_lshr_b32 s9, s8, 2
	s_and_b32 s8, s8, 3
	s_lshl_b32 s9, s9, 6
	s_lshl_b32 s11, s81, 8
	s_add_i32 s9, s9, s11
	v_add_u32_e32 v154, s9, v152
	s_cmp_lg_u32 s10, 0
	s_cbranch_scc1 .Lp1_qkv
	s_add_u32 s20, s86, 0x8000000
	s_addc_u32 s21, s87, 0
	s_lshl_b32 s9, s8, 6
	v_lshlrev_b32_e32 v155, 9, v154
	v_lshl_add_u32 v155, v153, 4, v155
	v_add_u32_e32 v155, s9, v155
	v_mov_b32_e32 v158, v155
	v_pk_mul_f32 v[124:125], v[124:125], v[248:249] op_sel_hi:[1,0]
	v_pk_mul_f32 v[126:127], v[126:127], v[248:249] op_sel_hi:[1,0]
	v_pk_mul_f32 v[120:121], v[120:121], v[248:249] op_sel_hi:[1,0]
	v_pk_mul_f32 v[122:123], v[122:123], v[248:249] op_sel_hi:[1,0]
	v_pk_mul_f32 v[116:117], v[116:117], v[248:249] op_sel_hi:[1,0]
	v_pk_mul_f32 v[118:119], v[118:119], v[248:249] op_sel_hi:[1,0]
	v_pk_mul_f32 v[112:113], v[112:113], v[248:249] op_sel_hi:[1,0]
	v_pk_mul_f32 v[114:115], v[114:115], v[248:249] op_sel_hi:[1,0]
	v_cvt_pk_bf16_f32 v124, v124, v125
	v_cvt_pk_bf16_f32 v125, v126, v127
	v_cvt_pk_bf16_f32 v126, v120, v121
	v_cvt_pk_bf16_f32 v127, v122, v123
	global_store_dwordx4 v158, v[124:127], s[20:21]
	v_cvt_pk_bf16_f32 v116, v116, v117
	v_cvt_pk_bf16_f32 v117, v118, v119
	v_cvt_pk_bf16_f32 v118, v112, v113
	v_cvt_pk_bf16_f32 v119, v114, v115
	global_store_dwordx4 v158, v[116:119], s[20:21] offset:256
	s_nop 1
	v_add_u32_e32 v158, 0x2000, v155
	v_pk_mul_f32 v[108:109], v[108:109], v[248:249] op_sel:[0,1] op_sel_hi:[1,1]
	v_pk_mul_f32 v[110:111], v[110:111], v[248:249] op_sel:[0,1] op_sel_hi:[1,1]
	v_pk_mul_f32 v[104:105], v[104:105], v[248:249] op_sel:[0,1] op_sel_hi:[1,1]
	v_pk_mul_f32 v[106:107], v[106:107], v[248:249] op_sel:[0,1] op_sel_hi:[1,1]
	v_pk_mul_f32 v[100:101], v[100:101], v[248:249] op_sel:[0,1] op_sel_hi:[1,1]
	v_pk_mul_f32 v[102:103], v[102:103], v[248:249] op_sel:[0,1] op_sel_hi:[1,1]
	v_pk_mul_f32 v[96:97], v[96:97], v[248:249] op_sel:[0,1] op_sel_hi:[1,1]
	v_pk_mul_f32 v[98:99], v[98:99], v[248:249] op_sel:[0,1] op_sel_hi:[1,1]
	v_cvt_pk_bf16_f32 v108, v108, v109
	v_cvt_pk_bf16_f32 v109, v110, v111
	v_cvt_pk_bf16_f32 v110, v104, v105
	v_cvt_pk_bf16_f32 v111, v106, v107
	global_store_dwordx4 v158, v[108:111], s[20:21]
	v_cvt_pk_bf16_f32 v100, v100, v101
	v_cvt_pk_bf16_f32 v101, v102, v103
	v_cvt_pk_bf16_f32 v102, v96, v97
	v_cvt_pk_bf16_f32 v103, v98, v99
	global_store_dwordx4 v158, v[100:103], s[20:21] offset:256
	s_nop 1
	v_add_u32_e32 v158, 0x4000, v155
	v_pk_mul_f32 v[92:93], v[92:93], v[250:251] op_sel_hi:[1,0]
	v_pk_mul_f32 v[94:95], v[94:95], v[250:251] op_sel_hi:[1,0]
	v_pk_mul_f32 v[88:89], v[88:89], v[250:251] op_sel_hi:[1,0]
	v_pk_mul_f32 v[90:91], v[90:91], v[250:251] op_sel_hi:[1,0]
	v_pk_mul_f32 v[80:81], v[80:81], v[250:251] op_sel_hi:[1,0]
	v_pk_mul_f32 v[82:83], v[82:83], v[250:251] op_sel_hi:[1,0]
	v_pk_mul_f32 v[72:73], v[72:73], v[250:251] op_sel_hi:[1,0]
	v_pk_mul_f32 v[74:75], v[74:75], v[250:251] op_sel_hi:[1,0]
	v_cvt_pk_bf16_f32 v92, v92, v93
	v_cvt_pk_bf16_f32 v93, v94, v95
	v_cvt_pk_bf16_f32 v94, v88, v89
	v_cvt_pk_bf16_f32 v95, v90, v91
	global_store_dwordx4 v158, v[92:95], s[20:21]
	v_cvt_pk_bf16_f32 v80, v80, v81
	v_cvt_pk_bf16_f32 v81, v82, v83
	v_cvt_pk_bf16_f32 v82, v72, v73
	v_cvt_pk_bf16_f32 v83, v74, v75
	global_store_dwordx4 v158, v[80:83], s[20:21] offset:256
	s_nop 1
	v_add_u32_e32 v158, 0x6000, v155
	v_pk_mul_f32 v[84:85], v[84:85], v[250:251] op_sel:[0,1] op_sel_hi:[1,1]
	v_pk_mul_f32 v[86:87], v[86:87], v[250:251] op_sel:[0,1] op_sel_hi:[1,1]
	v_pk_mul_f32 v[76:77], v[76:77], v[250:251] op_sel:[0,1] op_sel_hi:[1,1]
	v_pk_mul_f32 v[78:79], v[78:79], v[250:251] op_sel:[0,1] op_sel_hi:[1,1]
	v_pk_mul_f32 v[68:69], v[68:69], v[250:251] op_sel:[0,1] op_sel_hi:[1,1]
	v_pk_mul_f32 v[70:71], v[70:71], v[250:251] op_sel:[0,1] op_sel_hi:[1,1]
	v_pk_mul_f32 v[64:65], v[64:65], v[250:251] op_sel:[0,1] op_sel_hi:[1,1]
	v_pk_mul_f32 v[66:67], v[66:67], v[250:251] op_sel:[0,1] op_sel_hi:[1,1]
	v_cvt_pk_bf16_f32 v84, v84, v85
	v_cvt_pk_bf16_f32 v85, v86, v87
	v_cvt_pk_bf16_f32 v86, v76, v77
	v_cvt_pk_bf16_f32 v87, v78, v79
	global_store_dwordx4 v158, v[84:87], s[20:21]
	v_cvt_pk_bf16_f32 v68, v68, v69
	v_cvt_pk_bf16_f32 v69, v70, v71
	v_cvt_pk_bf16_f32 v70, v64, v65
	v_cvt_pk_bf16_f32 v71, v66, v67
	global_store_dwordx4 v158, v[68:71], s[20:21] offset:256
	s_nop 1
	v_add_u32_e32 v158, 0x10000, v155
	v_pk_mul_f32 v[60:61], v[60:61], v[252:253] op_sel_hi:[1,0]
	v_pk_mul_f32 v[62:63], v[62:63], v[252:253] op_sel_hi:[1,0]
	v_pk_mul_f32 v[56:57], v[56:57], v[252:253] op_sel_hi:[1,0]
	v_pk_mul_f32 v[58:59], v[58:59], v[252:253] op_sel_hi:[1,0]
	v_pk_mul_f32 v[52:53], v[52:53], v[252:253] op_sel_hi:[1,0]
	v_pk_mul_f32 v[54:55], v[54:55], v[252:253] op_sel_hi:[1,0]
	v_pk_mul_f32 v[48:49], v[48:49], v[252:253] op_sel_hi:[1,0]
	v_pk_mul_f32 v[50:51], v[50:51], v[252:253] op_sel_hi:[1,0]
	v_cvt_pk_bf16_f32 v60, v60, v61
	v_cvt_pk_bf16_f32 v61, v62, v63
	v_cvt_pk_bf16_f32 v62, v56, v57
	v_cvt_pk_bf16_f32 v63, v58, v59
	global_store_dwordx4 v158, v[60:63], s[20:21]
	v_cvt_pk_bf16_f32 v52, v52, v53
	v_cvt_pk_bf16_f32 v53, v54, v55
	v_cvt_pk_bf16_f32 v54, v48, v49
	v_cvt_pk_bf16_f32 v55, v50, v51
	global_store_dwordx4 v158, v[52:55], s[20:21] offset:256
	s_nop 1
	v_add_u32_e32 v158, 0x12000, v155
	v_pk_mul_f32 v[44:45], v[44:45], v[252:253] op_sel:[0,1] op_sel_hi:[1,1]
	v_pk_mul_f32 v[46:47], v[46:47], v[252:253] op_sel:[0,1] op_sel_hi:[1,1]
	v_pk_mul_f32 v[40:41], v[40:41], v[252:253] op_sel:[0,1] op_sel_hi:[1,1]
	v_pk_mul_f32 v[42:43], v[42:43], v[252:253] op_sel:[0,1] op_sel_hi:[1,1]
	v_pk_mul_f32 v[36:37], v[36:37], v[252:253] op_sel:[0,1] op_sel_hi:[1,1]
	v_pk_mul_f32 v[38:39], v[38:39], v[252:253] op_sel:[0,1] op_sel_hi:[1,1]
	v_pk_mul_f32 v[32:33], v[32:33], v[252:253] op_sel:[0,1] op_sel_hi:[1,1]
	v_pk_mul_f32 v[34:35], v[34:35], v[252:253] op_sel:[0,1] op_sel_hi:[1,1]
	v_cvt_pk_bf16_f32 v44, v44, v45
	v_cvt_pk_bf16_f32 v45, v46, v47
	v_cvt_pk_bf16_f32 v46, v40, v41
	v_cvt_pk_bf16_f32 v47, v42, v43
	global_store_dwordx4 v158, v[44:47], s[20:21]
	v_cvt_pk_bf16_f32 v36, v36, v37
	v_cvt_pk_bf16_f32 v37, v38, v39
	v_cvt_pk_bf16_f32 v38, v32, v33
	v_cvt_pk_bf16_f32 v39, v34, v35
	global_store_dwordx4 v158, v[36:39], s[20:21] offset:256
	s_nop 1
	v_add_u32_e32 v158, 0x14000, v155
	v_pk_mul_f32 v[28:29], v[28:29], v[254:255] op_sel_hi:[1,0]
	v_pk_mul_f32 v[30:31], v[30:31], v[254:255] op_sel_hi:[1,0]
	v_pk_mul_f32 v[24:25], v[24:25], v[254:255] op_sel_hi:[1,0]
	v_pk_mul_f32 v[26:27], v[26:27], v[254:255] op_sel_hi:[1,0]
	v_pk_mul_f32 v[20:21], v[20:21], v[254:255] op_sel_hi:[1,0]
	v_pk_mul_f32 v[22:23], v[22:23], v[254:255] op_sel_hi:[1,0]
	v_pk_mul_f32 v[16:17], v[16:17], v[254:255] op_sel_hi:[1,0]
	v_pk_mul_f32 v[18:19], v[18:19], v[254:255] op_sel_hi:[1,0]
	v_cvt_pk_bf16_f32 v28, v28, v29
	v_cvt_pk_bf16_f32 v29, v30, v31
	v_cvt_pk_bf16_f32 v30, v24, v25
	v_cvt_pk_bf16_f32 v31, v26, v27
	global_store_dwordx4 v158, v[28:31], s[20:21]
	v_cvt_pk_bf16_f32 v20, v20, v21
	v_cvt_pk_bf16_f32 v21, v22, v23
	v_cvt_pk_bf16_f32 v22, v16, v17
	v_cvt_pk_bf16_f32 v23, v18, v19
	global_store_dwordx4 v158, v[20:23], s[20:21] offset:256
	s_nop 1
	v_add_u32_e32 v158, 0x16000, v155
	v_pk_mul_f32 v[12:13], v[12:13], v[254:255] op_sel:[0,1] op_sel_hi:[1,1]
	v_pk_mul_f32 v[14:15], v[14:15], v[254:255] op_sel:[0,1] op_sel_hi:[1,1]
	v_pk_mul_f32 v[8:9], v[8:9], v[254:255] op_sel:[0,1] op_sel_hi:[1,1]
	v_pk_mul_f32 v[10:11], v[10:11], v[254:255] op_sel:[0,1] op_sel_hi:[1,1]
	v_pk_mul_f32 v[4:5], v[4:5], v[254:255] op_sel:[0,1] op_sel_hi:[1,1]
	v_pk_mul_f32 v[6:7], v[6:7], v[254:255] op_sel:[0,1] op_sel_hi:[1,1]
	v_pk_mul_f32 v[0:1], v[0:1], v[254:255] op_sel:[0,1] op_sel_hi:[1,1]
	v_pk_mul_f32 v[2:3], v[2:3], v[254:255] op_sel:[0,1] op_sel_hi:[1,1]
	v_cvt_pk_bf16_f32 v12, v12, v13
	v_cvt_pk_bf16_f32 v13, v14, v15
	v_cvt_pk_bf16_f32 v14, v8, v9
	v_cvt_pk_bf16_f32 v15, v10, v11
	global_store_dwordx4 v158, v[12:15], s[20:21]
	v_cvt_pk_bf16_f32 v4, v4, v5
	v_cvt_pk_bf16_f32 v5, v6, v7
	v_cvt_pk_bf16_f32 v6, v0, v1
	v_cvt_pk_bf16_f32 v7, v2, v3
	global_store_dwordx4 v158, v[4:7], s[20:21] offset:256
	s_branch .Lp1_done
.Lp1_qkv:
	s_add_i32 s46, s10, -1
	s_mul_i32 s47, s46, 0x5556
	s_lshr_b32 s47, s47, 16
	s_mul_i32 s9, s47, 3
	s_sub_i32 s46, s46, s9
	s_lshl_b32 s46, s46, 2
	s_lshr_b32 s9, s8, 1
	s_add_i32 s46, s46, s9
	s_mul_i32 s46, s46, 0x600000
	s_mul_i32 s9, s47, 0x4800000
	s_add_i32 s46, s46, s9
	s_and_b32 s9, s8, 1
	s_lshl_b32 s9, s9, 6
	s_add_i32 s46, s46, s9
	s_add_u32 s20, s86, 0x9800000
	s_addc_u32 s21, s87, 0
	v_lshlrev_b32_e32 v155, 7, v154
	v_lshl_add_u32 v155, v153, 4, v155
	v_add_u32_e32 v155, s46, v155
	v_add_u32_e32 v156, 0xc00000, v155
	s_cmp_eq_u32 s47, 0
	s_cselect_b32 s9, 0x3e38aa3b, 1.0
	v_mov_b32_e32 v162, s9
	v_mov_b32_e32 v163, s9
	s_and_b32 s9, s8, 1
	s_cmp_lt_u32 s47, 2
	s_cselect_b32 s11, 1, 0
	s_andn2_b32 s11, s11, s9
	s_cmp_eq_u32 s11, 0
	s_cbranch_scc1 .Lp1_norope
	v_cmp_eq_u32_e32 vcc, 0, v153
	s_nop 1
	v_cndmask_b32_e64 v160, 1.0, -1.0, vcc
	v_mov_b32_e32 v161, v160
	v_and_b32_e32 v158, 1, v153
	v_cmp_eq_u32_e64 s[46:47], 1, v158
	v_cmp_gt_u32_e64 s[52:53], 2, v153
	s_movk_i32 s9, 0x3fff
	s_cmp_lt_u32 s81, 64
	s_cselect_b32 s9, 0x7ff, s9
	v_and_b32_e32 v157, s9, v154
	v_lshlrev_b32_e32 v157, 6, v157
	v_mov_b32_e32 v158, v157
	s_mov_b64 s[8:9], exec
	s_mov_b64 exec, s[52:53]
	global_load_dwordx4 v[164:167], v158, s[14:15] offset:0
	global_load_dwordx4 v[168:171], v158, s[14:15] offset:16
	global_load_dwordx4 v[192:195], v158, s[14:15] offset:32
	global_load_dwordx4 v[196:199], v158, s[14:15] offset:48
	global_load_dwordx4 v[200:203], v158, s[14:15] offset:1024
	global_load_dwordx4 v[204:207], v158, s[14:15] offset:1040
	global_load_dwordx4 v[208:211], v158, s[14:15] offset:1056
	global_load_dwordx4 v[232:235], v158, s[14:15] offset:1072
	s_mov_b64 exec, s[8:9]
	v_pk_mul_f32 v[124:125], v[124:125], v[248:249] op_sel_hi:[1,0]
	v_pk_mul_f32 v[126:127], v[126:127], v[248:249] op_sel_hi:[1,0]
	v_pk_mul_f32 v[120:121], v[120:121], v[248:249] op_sel_hi:[1,0]
	v_pk_mul_f32 v[122:123], v[122:123], v[248:249] op_sel_hi:[1,0]
	v_mov_b32_e32 v216, v124
	v_mov_b32_e32 v217, v124
	v_mov_b32_e32 v218, v125
	v_mov_b32_e32 v219, v125
	v_mov_b32_e32 v220, v126
	v_mov_b32_e32 v221, v126
	v_mov_b32_e32 v222, v127
	v_mov_b32_e32 v223, v127
	v_mov_b32_e32 v224, v120
	v_mov_b32_e32 v225, v120
	v_mov_b32_e32 v226, v121
	v_mov_b32_e32 v227, v121
	v_mov_b32_e32 v228, v122
	v_mov_b32_e32 v229, v122
	v_mov_b32_e32 v230, v123
	v_mov_b32_e32 v231, v123
	v_permlane16_swap_b32_e32 v216, v217
	v_permlane16_swap_b32_e32 v218, v219
	v_permlane16_swap_b32_e32 v220, v221
	v_permlane16_swap_b32_e32 v222, v223
	v_permlane16_swap_b32_e32 v224, v225
	v_permlane16_swap_b32_e32 v226, v227
	v_permlane16_swap_b32_e32 v228, v229
	v_permlane16_swap_b32_e32 v230, v231
	v_cndmask_b32_e64 v236, v217, v216, s[46:47]
	v_cndmask_b32_e64 v237, v219, v218, s[46:47]
	v_cndmask_b32_e64 v238, v221, v220, s[46:47]
	v_cndmask_b32_e64 v239, v223, v222, s[46:47]
	v_cndmask_b32_e64 v240, v225, v224, s[46:47]
	v_cndmask_b32_e64 v241, v227, v226, s[46:47]
	v_cndmask_b32_e64 v242, v229, v228, s[46:47]
	v_cndmask_b32_e64 v243, v231, v230, s[46:47]
	s_waitcnt vmcnt(0)
	s_mov_b64 s[8:9], exec
	s_mov_b64 exec, s[52:53]
	v_pk_mul_f32 v[236:237], v[192:193], v[236:237]
	v_pk_mul_f32 v[238:239], v[194:195], v[238:239]
	v_pk_mul_f32 v[240:241], v[196:197], v[240:241]
	v_pk_mul_f32 v[242:243], v[198:199], v[242:243]
	v_pk_mul_f32 v[236:237], v[160:161], v[236:237]
	v_pk_mul_f32 v[238:239], v[160:161], v[238:239]
	v_pk_mul_f32 v[240:241], v[160:161], v[240:241]
	v_pk_mul_f32 v[242:243], v[160:161], v[242:243]
	v_pk_fma_f32 v[124:125], v[124:125], v[164:165], v[236:237]
	v_pk_fma_f32 v[126:127], v[126:127], v[166:167], v[238:239]
	v_pk_fma_f32 v[120:121], v[120:121], v[168:169], v[240:241]
	v_pk_fma_f32 v[122:123], v[122:123], v[170:171], v[242:243]
	s_mov_b64 exec, s[8:9]
	v_pk_mul_f32 v[124:125], v[162:163], v[124:125]
	v_pk_mul_f32 v[126:127], v[162:163], v[126:127]
	v_pk_mul_f32 v[120:121], v[162:163], v[120:121]
	v_pk_mul_f32 v[122:123], v[162:163], v[122:123]
	v_mov_b32_e32 v159, v155
	v_cvt_pk_bf16_f32 v124, v124, v125
	v_cvt_pk_bf16_f32 v125, v126, v127
	v_cvt_pk_bf16_f32 v126, v120, v121
	v_cvt_pk_bf16_f32 v127, v122, v123
	global_store_dwordx4 v159, v[124:127], s[20:21]
	v_pk_mul_f32 v[116:117], v[116:117], v[248:249] op_sel_hi:[1,0]
	v_pk_mul_f32 v[118:119], v[118:119], v[248:249] op_sel_hi:[1,0]
	v_pk_mul_f32 v[112:113], v[112:113], v[248:249] op_sel_hi:[1,0]
	v_pk_mul_f32 v[114:115], v[114:115], v[248:249] op_sel_hi:[1,0]
	v_mov_b32_e32 v216, v116
	v_mov_b32_e32 v217, v116
	v_mov_b32_e32 v218, v117
	v_mov_b32_e32 v219, v117
	v_mov_b32_e32 v220, v118
	v_mov_b32_e32 v221, v118
	v_mov_b32_e32 v222, v119
	v_mov_b32_e32 v223, v119
	v_mov_b32_e32 v224, v112
	v_mov_b32_e32 v225, v112
	v_mov_b32_e32 v226, v113
	v_mov_b32_e32 v227, v113
	v_mov_b32_e32 v228, v114
	v_mov_b32_e32 v229, v114
	v_mov_b32_e32 v230, v115
	v_mov_b32_e32 v231, v115
	v_permlane16_swap_b32_e32 v216, v217
	v_permlane16_swap_b32_e32 v218, v219
	v_permlane16_swap_b32_e32 v220, v221
	v_permlane16_swap_b32_e32 v222, v223
	v_permlane16_swap_b32_e32 v224, v225
	v_permlane16_swap_b32_e32 v226, v227
	v_permlane16_swap_b32_e32 v228, v229
	v_permlane16_swap_b32_e32 v230, v231
	v_cndmask_b32_e64 v236, v217, v216, s[46:47]
	v_cndmask_b32_e64 v237, v219, v218, s[46:47]
	v_cndmask_b32_e64 v238, v221, v220, s[46:47]
	v_cndmask_b32_e64 v239, v223, v222, s[46:47]
	v_cndmask_b32_e64 v240, v225, v224, s[46:47]
	v_cndmask_b32_e64 v241, v227, v226, s[46:47]
	v_cndmask_b32_e64 v242, v229, v228, s[46:47]
	v_cndmask_b32_e64 v243, v231, v230, s[46:47]
	s_mov_b64 s[8:9], exec
	s_mov_b64 exec, s[52:53]
	v_pk_mul_f32 v[236:237], v[192:193], v[236:237]
	v_pk_mul_f32 v[238:239], v[194:195], v[238:239]
	v_pk_mul_f32 v[240:241], v[196:197], v[240:241]
	v_pk_mul_f32 v[242:243], v[198:199], v[242:243]
	v_pk_mul_f32 v[236:237], v[160:161], v[236:237]
	v_pk_mul_f32 v[238:239], v[160:161], v[238:239]
	v_pk_mul_f32 v[240:241], v[160:161], v[240:241]
	v_pk_mul_f32 v[242:243], v[160:161], v[242:243]
	v_pk_fma_f32 v[116:117], v[116:117], v[164:165], v[236:237]
	v_pk_fma_f32 v[118:119], v[118:119], v[166:167], v[238:239]
	v_pk_fma_f32 v[112:113], v[112:113], v[168:169], v[240:241]
	v_pk_fma_f32 v[114:115], v[114:115], v[170:171], v[242:243]
	s_mov_b64 exec, s[8:9]
	v_pk_mul_f32 v[116:117], v[162:163], v[116:117]
	v_pk_mul_f32 v[118:119], v[162:163], v[118:119]
	v_pk_mul_f32 v[112:113], v[162:163], v[112:113]
	v_pk_mul_f32 v[114:115], v[162:163], v[114:115]
	v_mov_b32_e32 v159, v156
	v_cvt_pk_bf16_f32 v116, v116, v117
	v_cvt_pk_bf16_f32 v117, v118, v119
	v_cvt_pk_bf16_f32 v118, v112, v113
	v_cvt_pk_bf16_f32 v119, v114, v115
	global_store_dwordx4 v159, v[116:119], s[20:21]
	v_pk_mul_f32 v[108:109], v[108:109], v[248:249] op_sel:[0,1] op_sel_hi:[1,1]
	v_pk_mul_f32 v[110:111], v[110:111], v[248:249] op_sel:[0,1] op_sel_hi:[1,1]
	v_pk_mul_f32 v[104:105], v[104:105], v[248:249] op_sel:[0,1] op_sel_hi:[1,1]
	v_pk_mul_f32 v[106:107], v[106:107], v[248:249] op_sel:[0,1] op_sel_hi:[1,1]
	v_mov_b32_e32 v216, v108
	v_mov_b32_e32 v217, v108
	v_mov_b32_e32 v218, v109
	v_mov_b32_e32 v219, v109
	v_mov_b32_e32 v220, v110
	v_mov_b32_e32 v221, v110
	v_mov_b32_e32 v222, v111
	v_mov_b32_e32 v223, v111
	v_mov_b32_e32 v224, v104
	v_mov_b32_e32 v225, v104
	v_mov_b32_e32 v226, v105
	v_mov_b32_e32 v227, v105
	v_mov_b32_e32 v228, v106
	v_mov_b32_e32 v229, v106
	v_mov_b32_e32 v230, v107
	v_mov_b32_e32 v231, v107
	v_permlane16_swap_b32_e32 v216, v217
	v_permlane16_swap_b32_e32 v218, v219
	v_permlane16_swap_b32_e32 v220, v221
	v_permlane16_swap_b32_e32 v222, v223
	v_permlane16_swap_b32_e32 v224, v225
	v_permlane16_swap_b32_e32 v226, v227
	v_permlane16_swap_b32_e32 v228, v229
	v_permlane16_swap_b32_e32 v230, v231
	v_cndmask_b32_e64 v236, v217, v216, s[46:47]
	v_cndmask_b32_e64 v237, v219, v218, s[46:47]
	v_cndmask_b32_e64 v238, v221, v220, s[46:47]
	v_cndmask_b32_e64 v239, v223, v222, s[46:47]
	v_cndmask_b32_e64 v240, v225, v224, s[46:47]
	v_cndmask_b32_e64 v241, v227, v226, s[46:47]
	v_cndmask_b32_e64 v242, v229, v228, s[46:47]
	v_cndmask_b32_e64 v243, v231, v230, s[46:47]
	s_mov_b64 s[8:9], exec
	s_mov_b64 exec, s[52:53]
	v_pk_mul_f32 v[236:237], v[208:209], v[236:237]
	v_pk_mul_f32 v[238:239], v[210:211], v[238:239]
	v_pk_mul_f32 v[240:241], v[232:233], v[240:241]
	v_pk_mul_f32 v[242:243], v[234:235], v[242:243]
	v_pk_mul_f32 v[236:237], v[160:161], v[236:237]
	v_pk_mul_f32 v[238:239], v[160:161], v[238:239]
	v_pk_mul_f32 v[240:241], v[160:161], v[240:241]
	v_pk_mul_f32 v[242:243], v[160:161], v[242:243]
	v_pk_fma_f32 v[108:109], v[108:109], v[200:201], v[236:237]
	v_pk_fma_f32 v[110:111], v[110:111], v[202:203], v[238:239]
	v_pk_fma_f32 v[104:105], v[104:105], v[204:205], v[240:241]
	v_pk_fma_f32 v[106:107], v[106:107], v[206:207], v[242:243]
	s_mov_b64 exec, s[8:9]
	v_pk_mul_f32 v[108:109], v[162:163], v[108:109]
	v_pk_mul_f32 v[110:111], v[162:163], v[110:111]
	v_pk_mul_f32 v[104:105], v[162:163], v[104:105]
	v_pk_mul_f32 v[106:107], v[162:163], v[106:107]
	v_add_u32_e32 v159, 0x800, v155
	v_cvt_pk_bf16_f32 v108, v108, v109
	v_cvt_pk_bf16_f32 v109, v110, v111
	v_cvt_pk_bf16_f32 v110, v104, v105
	v_cvt_pk_bf16_f32 v111, v106, v107
	global_store_dwordx4 v159, v[108:111], s[20:21]
	v_pk_mul_f32 v[100:101], v[100:101], v[248:249] op_sel:[0,1] op_sel_hi:[1,1]
	v_pk_mul_f32 v[102:103], v[102:103], v[248:249] op_sel:[0,1] op_sel_hi:[1,1]
	v_pk_mul_f32 v[96:97], v[96:97], v[248:249] op_sel:[0,1] op_sel_hi:[1,1]
	v_pk_mul_f32 v[98:99], v[98:99], v[248:249] op_sel:[0,1] op_sel_hi:[1,1]
	v_mov_b32_e32 v216, v100
	v_mov_b32_e32 v217, v100
	v_mov_b32_e32 v218, v101
	v_mov_b32_e32 v219, v101
	v_mov_b32_e32 v220, v102
	v_mov_b32_e32 v221, v102
	v_mov_b32_e32 v222, v103
	v_mov_b32_e32 v223, v103
	v_mov_b32_e32 v224, v96
	v_mov_b32_e32 v225, v96
	v_mov_b32_e32 v226, v97
	v_mov_b32_e32 v227, v97
	v_mov_b32_e32 v228, v98
	v_mov_b32_e32 v229, v98
	v_mov_b32_e32 v230, v99
	v_mov_b32_e32 v231, v99
	v_permlane16_swap_b32_e32 v216, v217
	v_permlane16_swap_b32_e32 v218, v219
	v_permlane16_swap_b32_e32 v220, v221
	v_permlane16_swap_b32_e32 v222, v223
	v_permlane16_swap_b32_e32 v224, v225
	v_permlane16_swap_b32_e32 v226, v227
	v_permlane16_swap_b32_e32 v228, v229
	v_permlane16_swap_b32_e32 v230, v231
	v_cndmask_b32_e64 v236, v217, v216, s[46:47]
	v_cndmask_b32_e64 v237, v219, v218, s[46:47]
	v_cndmask_b32_e64 v238, v221, v220, s[46:47]
	v_cndmask_b32_e64 v239, v223, v222, s[46:47]
	v_cndmask_b32_e64 v240, v225, v224, s[46:47]
	v_cndmask_b32_e64 v241, v227, v226, s[46:47]
	v_cndmask_b32_e64 v242, v229, v228, s[46:47]
	v_cndmask_b32_e64 v243, v231, v230, s[46:47]
	s_mov_b64 s[8:9], exec
	s_mov_b64 exec, s[52:53]
	v_pk_mul_f32 v[236:237], v[208:209], v[236:237]
	v_pk_mul_f32 v[238:239], v[210:211], v[238:239]
	v_pk_mul_f32 v[240:241], v[232:233], v[240:241]
	v_pk_mul_f32 v[242:243], v[234:235], v[242:243]
	v_pk_mul_f32 v[236:237], v[160:161], v[236:237]
	v_pk_mul_f32 v[238:239], v[160:161], v[238:239]
	v_pk_mul_f32 v[240:241], v[160:161], v[240:241]
	v_pk_mul_f32 v[242:243], v[160:161], v[242:243]
	v_pk_fma_f32 v[100:101], v[100:101], v[200:201], v[236:237]
	v_pk_fma_f32 v[102:103], v[102:103], v[202:203], v[238:239]
	v_pk_fma_f32 v[96:97], v[96:97], v[204:205], v[240:241]
	v_pk_fma_f32 v[98:99], v[98:99], v[206:207], v[242:243]
	s_mov_b64 exec, s[8:9]
	v_pk_mul_f32 v[100:101], v[162:163], v[100:101]
	v_pk_mul_f32 v[102:103], v[162:163], v[102:103]
	v_pk_mul_f32 v[96:97], v[162:163], v[96:97]
	v_pk_mul_f32 v[98:99], v[162:163], v[98:99]
	v_add_u32_e32 v159, 0x800, v156
	v_cvt_pk_bf16_f32 v100, v100, v101
	v_cvt_pk_bf16_f32 v101, v102, v103
	v_cvt_pk_bf16_f32 v102, v96, v97
	v_cvt_pk_bf16_f32 v103, v98, v99
	global_store_dwordx4 v159, v[100:103], s[20:21]
	v_add_u32_e32 v158, 0x800, v157
	s_mov_b64 s[8:9], exec
	s_mov_b64 exec, s[52:53]
	global_load_dwordx4 v[164:167], v158, s[14:15] offset:0
	global_load_dwordx4 v[168:171], v158, s[14:15] offset:16
	global_load_dwordx4 v[192:195], v158, s[14:15] offset:32
	global_load_dwordx4 v[196:199], v158, s[14:15] offset:48
	global_load_dwordx4 v[200:203], v158, s[14:15] offset:1024
	global_load_dwordx4 v[204:207], v158, s[14:15] offset:1040
	global_load_dwordx4 v[208:211], v158, s[14:15] offset:1056
	global_load_dwordx4 v[232:235], v158, s[14:15] offset:1072
	s_mov_b64 exec, s[8:9]
	v_pk_mul_f32 v[92:93], v[92:93], v[250:251] op_sel_hi:[1,0]
	v_pk_mul_f32 v[94:95], v[94:95], v[250:251] op_sel_hi:[1,0]
	v_pk_mul_f32 v[88:89], v[88:89], v[250:251] op_sel_hi:[1,0]
	v_pk_mul_f32 v[90:91], v[90:91], v[250:251] op_sel_hi:[1,0]
	v_mov_b32_e32 v216, v92
	v_mov_b32_e32 v217, v92
	v_mov_b32_e32 v218, v93
	v_mov_b32_e32 v219, v93
	v_mov_b32_e32 v220, v94
	v_mov_b32_e32 v221, v94
	v_mov_b32_e32 v222, v95
	v_mov_b32_e32 v223, v95
	v_mov_b32_e32 v224, v88
	v_mov_b32_e32 v225, v88
	v_mov_b32_e32 v226, v89
	v_mov_b32_e32 v227, v89
	v_mov_b32_e32 v228, v90
	v_mov_b32_e32 v229, v90
	v_mov_b32_e32 v230, v91
	v_mov_b32_e32 v231, v91
	v_permlane16_swap_b32_e32 v216, v217
	v_permlane16_swap_b32_e32 v218, v219
	v_permlane16_swap_b32_e32 v220, v221
	v_permlane16_swap_b32_e32 v222, v223
	v_permlane16_swap_b32_e32 v224, v225
	v_permlane16_swap_b32_e32 v226, v227
	v_permlane16_swap_b32_e32 v228, v229
	v_permlane16_swap_b32_e32 v230, v231
	v_cndmask_b32_e64 v236, v217, v216, s[46:47]
	v_cndmask_b32_e64 v237, v219, v218, s[46:47]
	v_cndmask_b32_e64 v238, v221, v220, s[46:47]
	v_cndmask_b32_e64 v239, v223, v222, s[46:47]
	v_cndmask_b32_e64 v240, v225, v224, s[46:47]
	v_cndmask_b32_e64 v241, v227, v226, s[46:47]
	v_cndmask_b32_e64 v242, v229, v228, s[46:47]
	v_cndmask_b32_e64 v243, v231, v230, s[46:47]
	s_waitcnt vmcnt(0)
	s_mov_b64 s[8:9], exec
	s_mov_b64 exec, s[52:53]
	v_pk_mul_f32 v[236:237], v[192:193], v[236:237]
	v_pk_mul_f32 v[238:239], v[194:195], v[238:239]
	v_pk_mul_f32 v[240:241], v[196:197], v[240:241]
	v_pk_mul_f32 v[242:243], v[198:199], v[242:243]
	v_pk_mul_f32 v[236:237], v[160:161], v[236:237]
	v_pk_mul_f32 v[238:239], v[160:161], v[238:239]
	v_pk_mul_f32 v[240:241], v[160:161], v[240:241]
	v_pk_mul_f32 v[242:243], v[160:161], v[242:243]
	v_pk_fma_f32 v[92:93], v[92:93], v[164:165], v[236:237]
	v_pk_fma_f32 v[94:95], v[94:95], v[166:167], v[238:239]
	v_pk_fma_f32 v[88:89], v[88:89], v[168:169], v[240:241]
	v_pk_fma_f32 v[90:91], v[90:91], v[170:171], v[242:243]
	s_mov_b64 exec, s[8:9]
	v_pk_mul_f32 v[92:93], v[162:163], v[92:93]
	v_pk_mul_f32 v[94:95], v[162:163], v[94:95]
	v_pk_mul_f32 v[88:89], v[162:163], v[88:89]
	v_pk_mul_f32 v[90:91], v[162:163], v[90:91]
	v_add_u32_e32 v159, 0x1000, v155
	v_cvt_pk_bf16_f32 v92, v92, v93
	v_cvt_pk_bf16_f32 v93, v94, v95
	v_cvt_pk_bf16_f32 v94, v88, v89
	v_cvt_pk_bf16_f32 v95, v90, v91
	global_store_dwordx4 v159, v[92:95], s[20:21]
	v_pk_mul_f32 v[80:81], v[80:81], v[250:251] op_sel_hi:[1,0]
	v_pk_mul_f32 v[82:83], v[82:83], v[250:251] op_sel_hi:[1,0]
	v_pk_mul_f32 v[72:73], v[72:73], v[250:251] op_sel_hi:[1,0]
	v_pk_mul_f32 v[74:75], v[74:75], v[250:251] op_sel_hi:[1,0]
	v_mov_b32_e32 v216, v80
	v_mov_b32_e32 v217, v80
	v_mov_b32_e32 v218, v81
	v_mov_b32_e32 v219, v81
	v_mov_b32_e32 v220, v82
	v_mov_b32_e32 v221, v82
	v_mov_b32_e32 v222, v83
	v_mov_b32_e32 v223, v83
	v_mov_b32_e32 v224, v72
	v_mov_b32_e32 v225, v72
	v_mov_b32_e32 v226, v73
	v_mov_b32_e32 v227, v73
	v_mov_b32_e32 v228, v74
	v_mov_b32_e32 v229, v74
	v_mov_b32_e32 v230, v75
	v_mov_b32_e32 v231, v75
	v_permlane16_swap_b32_e32 v216, v217
	v_permlane16_swap_b32_e32 v218, v219
	v_permlane16_swap_b32_e32 v220, v221
	v_permlane16_swap_b32_e32 v222, v223
	v_permlane16_swap_b32_e32 v224, v225
	v_permlane16_swap_b32_e32 v226, v227
	v_permlane16_swap_b32_e32 v228, v229
	v_permlane16_swap_b32_e32 v230, v231
	v_cndmask_b32_e64 v236, v217, v216, s[46:47]
	v_cndmask_b32_e64 v237, v219, v218, s[46:47]
	v_cndmask_b32_e64 v238, v221, v220, s[46:47]
	v_cndmask_b32_e64 v239, v223, v222, s[46:47]
	v_cndmask_b32_e64 v240, v225, v224, s[46:47]
	v_cndmask_b32_e64 v241, v227, v226, s[46:47]
	v_cndmask_b32_e64 v242, v229, v228, s[46:47]
	v_cndmask_b32_e64 v243, v231, v230, s[46:47]
	s_mov_b64 s[8:9], exec
	s_mov_b64 exec, s[52:53]
	v_pk_mul_f32 v[236:237], v[192:193], v[236:237]
	v_pk_mul_f32 v[238:239], v[194:195], v[238:239]
	v_pk_mul_f32 v[240:241], v[196:197], v[240:241]
	v_pk_mul_f32 v[242:243], v[198:199], v[242:243]
	v_pk_mul_f32 v[236:237], v[160:161], v[236:237]
	v_pk_mul_f32 v[238:239], v[160:161], v[238:239]
	v_pk_mul_f32 v[240:241], v[160:161], v[240:241]
	v_pk_mul_f32 v[242:243], v[160:161], v[242:243]
	v_pk_fma_f32 v[80:81], v[80:81], v[164:165], v[236:237]
	v_pk_fma_f32 v[82:83], v[82:83], v[166:167], v[238:239]
	v_pk_fma_f32 v[72:73], v[72:73], v[168:169], v[240:241]
	v_pk_fma_f32 v[74:75], v[74:75], v[170:171], v[242:243]
	s_mov_b64 exec, s[8:9]
	v_pk_mul_f32 v[80:81], v[162:163], v[80:81]
	v_pk_mul_f32 v[82:83], v[162:163], v[82:83]
	v_pk_mul_f32 v[72:73], v[162:163], v[72:73]
	v_pk_mul_f32 v[74:75], v[162:163], v[74:75]
	v_add_u32_e32 v159, 0x1000, v156
	v_cvt_pk_bf16_f32 v80, v80, v81
	v_cvt_pk_bf16_f32 v81, v82, v83
	v_cvt_pk_bf16_f32 v82, v72, v73
	v_cvt_pk_bf16_f32 v83, v74, v75
	global_store_dwordx4 v159, v[80:83], s[20:21]
	v_pk_mul_f32 v[84:85], v[84:85], v[250:251] op_sel:[0,1] op_sel_hi:[1,1]
	v_pk_mul_f32 v[86:87], v[86:87], v[250:251] op_sel:[0,1] op_sel_hi:[1,1]
	v_pk_mul_f32 v[76:77], v[76:77], v[250:251] op_sel:[0,1] op_sel_hi:[1,1]
	v_pk_mul_f32 v[78:79], v[78:79], v[250:251] op_sel:[0,1] op_sel_hi:[1,1]
	v_mov_b32_e32 v216, v84
	v_mov_b32_e32 v217, v84
	v_mov_b32_e32 v218, v85
	v_mov_b32_e32 v219, v85
	v_mov_b32_e32 v220, v86
	v_mov_b32_e32 v221, v86
	v_mov_b32_e32 v222, v87
	v_mov_b32_e32 v223, v87
	v_mov_b32_e32 v224, v76
	v_mov_b32_e32 v225, v76
	v_mov_b32_e32 v226, v77
	v_mov_b32_e32 v227, v77
	v_mov_b32_e32 v228, v78
	v_mov_b32_e32 v229, v78
	v_mov_b32_e32 v230, v79
	v_mov_b32_e32 v231, v79
	v_permlane16_swap_b32_e32 v216, v217
	v_permlane16_swap_b32_e32 v218, v219
	v_permlane16_swap_b32_e32 v220, v221
	v_permlane16_swap_b32_e32 v222, v223
	v_permlane16_swap_b32_e32 v224, v225
	v_permlane16_swap_b32_e32 v226, v227
	v_permlane16_swap_b32_e32 v228, v229
	v_permlane16_swap_b32_e32 v230, v231
	v_cndmask_b32_e64 v236, v217, v216, s[46:47]
	v_cndmask_b32_e64 v237, v219, v218, s[46:47]
	v_cndmask_b32_e64 v238, v221, v220, s[46:47]
	v_cndmask_b32_e64 v239, v223, v222, s[46:47]
	v_cndmask_b32_e64 v240, v225, v224, s[46:47]
	v_cndmask_b32_e64 v241, v227, v226, s[46:47]
	v_cndmask_b32_e64 v242, v229, v228, s[46:47]
	v_cndmask_b32_e64 v243, v231, v230, s[46:47]
	s_mov_b64 s[8:9], exec
	s_mov_b64 exec, s[52:53]
	v_pk_mul_f32 v[236:237], v[208:209], v[236:237]
	v_pk_mul_f32 v[238:239], v[210:211], v[238:239]
	v_pk_mul_f32 v[240:241], v[232:233], v[240:241]
	v_pk_mul_f32 v[242:243], v[234:235], v[242:243]
	v_pk_mul_f32 v[236:237], v[160:161], v[236:237]
	v_pk_mul_f32 v[238:239], v[160:161], v[238:239]
	v_pk_mul_f32 v[240:241], v[160:161], v[240:241]
	v_pk_mul_f32 v[242:243], v[160:161], v[242:243]
	v_pk_fma_f32 v[84:85], v[84:85], v[200:201], v[236:237]
	v_pk_fma_f32 v[86:87], v[86:87], v[202:203], v[238:239]
	v_pk_fma_f32 v[76:77], v[76:77], v[204:205], v[240:241]
	v_pk_fma_f32 v[78:79], v[78:79], v[206:207], v[242:243]
	s_mov_b64 exec, s[8:9]
	v_pk_mul_f32 v[84:85], v[162:163], v[84:85]
	v_pk_mul_f32 v[86:87], v[162:163], v[86:87]
	v_pk_mul_f32 v[76:77], v[162:163], v[76:77]
	v_pk_mul_f32 v[78:79], v[162:163], v[78:79]
	v_add_u32_e32 v159, 0x1800, v155
	v_cvt_pk_bf16_f32 v84, v84, v85
	v_cvt_pk_bf16_f32 v85, v86, v87
	v_cvt_pk_bf16_f32 v86, v76, v77
	v_cvt_pk_bf16_f32 v87, v78, v79
	global_store_dwordx4 v159, v[84:87], s[20:21]
	v_pk_mul_f32 v[68:69], v[68:69], v[250:251] op_sel:[0,1] op_sel_hi:[1,1]
	v_pk_mul_f32 v[70:71], v[70:71], v[250:251] op_sel:[0,1] op_sel_hi:[1,1]
	v_pk_mul_f32 v[64:65], v[64:65], v[250:251] op_sel:[0,1] op_sel_hi:[1,1]
	v_pk_mul_f32 v[66:67], v[66:67], v[250:251] op_sel:[0,1] op_sel_hi:[1,1]
	v_mov_b32_e32 v216, v68
	v_mov_b32_e32 v217, v68
	v_mov_b32_e32 v218, v69
	v_mov_b32_e32 v219, v69
	v_mov_b32_e32 v220, v70
	v_mov_b32_e32 v221, v70
	v_mov_b32_e32 v222, v71
	v_mov_b32_e32 v223, v71
	v_mov_b32_e32 v224, v64
	v_mov_b32_e32 v225, v64
	v_mov_b32_e32 v226, v65
	v_mov_b32_e32 v227, v65
	v_mov_b32_e32 v228, v66
	v_mov_b32_e32 v229, v66
	v_mov_b32_e32 v230, v67
	v_mov_b32_e32 v231, v67
	v_permlane16_swap_b32_e32 v216, v217
	v_permlane16_swap_b32_e32 v218, v219
	v_permlane16_swap_b32_e32 v220, v221
	v_permlane16_swap_b32_e32 v222, v223
	v_permlane16_swap_b32_e32 v224, v225
	v_permlane16_swap_b32_e32 v226, v227
	v_permlane16_swap_b32_e32 v228, v229
	v_permlane16_swap_b32_e32 v230, v231
	v_cndmask_b32_e64 v236, v217, v216, s[46:47]
	v_cndmask_b32_e64 v237, v219, v218, s[46:47]
	v_cndmask_b32_e64 v238, v221, v220, s[46:47]
	v_cndmask_b32_e64 v239, v223, v222, s[46:47]
	v_cndmask_b32_e64 v240, v225, v224, s[46:47]
	v_cndmask_b32_e64 v241, v227, v226, s[46:47]
	v_cndmask_b32_e64 v242, v229, v228, s[46:47]
	v_cndmask_b32_e64 v243, v231, v230, s[46:47]
	s_mov_b64 s[8:9], exec
	s_mov_b64 exec, s[52:53]
	v_pk_mul_f32 v[236:237], v[208:209], v[236:237]
	v_pk_mul_f32 v[238:239], v[210:211], v[238:239]
	v_pk_mul_f32 v[240:241], v[232:233], v[240:241]
	v_pk_mul_f32 v[242:243], v[234:235], v[242:243]
	v_pk_mul_f32 v[236:237], v[160:161], v[236:237]
	v_pk_mul_f32 v[238:239], v[160:161], v[238:239]
	v_pk_mul_f32 v[240:241], v[160:161], v[240:241]
	v_pk_mul_f32 v[242:243], v[160:161], v[242:243]
	v_pk_fma_f32 v[68:69], v[68:69], v[200:201], v[236:237]
	v_pk_fma_f32 v[70:71], v[70:71], v[202:203], v[238:239]
	v_pk_fma_f32 v[64:65], v[64:65], v[204:205], v[240:241]
	v_pk_fma_f32 v[66:67], v[66:67], v[206:207], v[242:243]
	s_mov_b64 exec, s[8:9]
	v_pk_mul_f32 v[68:69], v[162:163], v[68:69]
	v_pk_mul_f32 v[70:71], v[162:163], v[70:71]
	v_pk_mul_f32 v[64:65], v[162:163], v[64:65]
	v_pk_mul_f32 v[66:67], v[162:163], v[66:67]
	v_add_u32_e32 v159, 0x1800, v156
	v_cvt_pk_bf16_f32 v68, v68, v69
	v_cvt_pk_bf16_f32 v69, v70, v71
	v_cvt_pk_bf16_f32 v70, v64, v65
	v_cvt_pk_bf16_f32 v71, v66, v67
	global_store_dwordx4 v159, v[68:71], s[20:21]
	v_add_u32_e32 v158, 0x2000, v157
	s_mov_b64 s[8:9], exec
	s_mov_b64 exec, s[52:53]
	global_load_dwordx4 v[164:167], v158, s[14:15] offset:0
	global_load_dwordx4 v[168:171], v158, s[14:15] offset:16
	global_load_dwordx4 v[192:195], v158, s[14:15] offset:32
	global_load_dwordx4 v[196:199], v158, s[14:15] offset:48
	global_load_dwordx4 v[200:203], v158, s[14:15] offset:1024
	global_load_dwordx4 v[204:207], v158, s[14:15] offset:1040
	global_load_dwordx4 v[208:211], v158, s[14:15] offset:1056
	global_load_dwordx4 v[232:235], v158, s[14:15] offset:1072
	s_mov_b64 exec, s[8:9]
	v_pk_mul_f32 v[60:61], v[60:61], v[252:253] op_sel_hi:[1,0]
	v_pk_mul_f32 v[62:63], v[62:63], v[252:253] op_sel_hi:[1,0]
	v_pk_mul_f32 v[56:57], v[56:57], v[252:253] op_sel_hi:[1,0]
	v_pk_mul_f32 v[58:59], v[58:59], v[252:253] op_sel_hi:[1,0]
	v_mov_b32_e32 v216, v60
	v_mov_b32_e32 v217, v60
	v_mov_b32_e32 v218, v61
	v_mov_b32_e32 v219, v61
	v_mov_b32_e32 v220, v62
	v_mov_b32_e32 v221, v62
	v_mov_b32_e32 v222, v63
	v_mov_b32_e32 v223, v63
	v_mov_b32_e32 v224, v56
	v_mov_b32_e32 v225, v56
	v_mov_b32_e32 v226, v57
	v_mov_b32_e32 v227, v57
	v_mov_b32_e32 v228, v58
	v_mov_b32_e32 v229, v58
	v_mov_b32_e32 v230, v59
	v_mov_b32_e32 v231, v59
	v_permlane16_swap_b32_e32 v216, v217
	v_permlane16_swap_b32_e32 v218, v219
	v_permlane16_swap_b32_e32 v220, v221
	v_permlane16_swap_b32_e32 v222, v223
	v_permlane16_swap_b32_e32 v224, v225
	v_permlane16_swap_b32_e32 v226, v227
	v_permlane16_swap_b32_e32 v228, v229
	v_permlane16_swap_b32_e32 v230, v231
	v_cndmask_b32_e64 v236, v217, v216, s[46:47]
	v_cndmask_b32_e64 v237, v219, v218, s[46:47]
	v_cndmask_b32_e64 v238, v221, v220, s[46:47]
	v_cndmask_b32_e64 v239, v223, v222, s[46:47]
	v_cndmask_b32_e64 v240, v225, v224, s[46:47]
	v_cndmask_b32_e64 v241, v227, v226, s[46:47]
	v_cndmask_b32_e64 v242, v229, v228, s[46:47]
	v_cndmask_b32_e64 v243, v231, v230, s[46:47]
	s_waitcnt vmcnt(0)
	s_mov_b64 s[8:9], exec
	s_mov_b64 exec, s[52:53]
	v_pk_mul_f32 v[236:237], v[192:193], v[236:237]
	v_pk_mul_f32 v[238:239], v[194:195], v[238:239]
	v_pk_mul_f32 v[240:241], v[196:197], v[240:241]
	v_pk_mul_f32 v[242:243], v[198:199], v[242:243]
	v_pk_mul_f32 v[236:237], v[160:161], v[236:237]
	v_pk_mul_f32 v[238:239], v[160:161], v[238:239]
	v_pk_mul_f32 v[240:241], v[160:161], v[240:241]
	v_pk_mul_f32 v[242:243], v[160:161], v[242:243]
	v_pk_fma_f32 v[60:61], v[60:61], v[164:165], v[236:237]
	v_pk_fma_f32 v[62:63], v[62:63], v[166:167], v[238:239]
	v_pk_fma_f32 v[56:57], v[56:57], v[168:169], v[240:241]
	v_pk_fma_f32 v[58:59], v[58:59], v[170:171], v[242:243]
	s_mov_b64 exec, s[8:9]
	v_pk_mul_f32 v[60:61], v[162:163], v[60:61]
	v_pk_mul_f32 v[62:63], v[162:163], v[62:63]
	v_pk_mul_f32 v[56:57], v[162:163], v[56:57]
	v_pk_mul_f32 v[58:59], v[162:163], v[58:59]
	v_add_u32_e32 v159, 0x4000, v155
	v_cvt_pk_bf16_f32 v60, v60, v61
	v_cvt_pk_bf16_f32 v61, v62, v63
	v_cvt_pk_bf16_f32 v62, v56, v57
	v_cvt_pk_bf16_f32 v63, v58, v59
	global_store_dwordx4 v159, v[60:63], s[20:21]
	v_pk_mul_f32 v[52:53], v[52:53], v[252:253] op_sel_hi:[1,0]
	v_pk_mul_f32 v[54:55], v[54:55], v[252:253] op_sel_hi:[1,0]
	v_pk_mul_f32 v[48:49], v[48:49], v[252:253] op_sel_hi:[1,0]
	v_pk_mul_f32 v[50:51], v[50:51], v[252:253] op_sel_hi:[1,0]
	v_mov_b32_e32 v216, v52
	v_mov_b32_e32 v217, v52
	v_mov_b32_e32 v218, v53
	v_mov_b32_e32 v219, v53
	v_mov_b32_e32 v220, v54
	v_mov_b32_e32 v221, v54
	v_mov_b32_e32 v222, v55
	v_mov_b32_e32 v223, v55
	v_mov_b32_e32 v224, v48
	v_mov_b32_e32 v225, v48
	v_mov_b32_e32 v226, v49
	v_mov_b32_e32 v227, v49
	v_mov_b32_e32 v228, v50
	v_mov_b32_e32 v229, v50
	v_mov_b32_e32 v230, v51
	v_mov_b32_e32 v231, v51
	v_permlane16_swap_b32_e32 v216, v217
	v_permlane16_swap_b32_e32 v218, v219
	v_permlane16_swap_b32_e32 v220, v221
	v_permlane16_swap_b32_e32 v222, v223
	v_permlane16_swap_b32_e32 v224, v225
	v_permlane16_swap_b32_e32 v226, v227
	v_permlane16_swap_b32_e32 v228, v229
	v_permlane16_swap_b32_e32 v230, v231
	v_cndmask_b32_e64 v236, v217, v216, s[46:47]
	v_cndmask_b32_e64 v237, v219, v218, s[46:47]
	v_cndmask_b32_e64 v238, v221, v220, s[46:47]
	v_cndmask_b32_e64 v239, v223, v222, s[46:47]
	v_cndmask_b32_e64 v240, v225, v224, s[46:47]
	v_cndmask_b32_e64 v241, v227, v226, s[46:47]
	v_cndmask_b32_e64 v242, v229, v228, s[46:47]
	v_cndmask_b32_e64 v243, v231, v230, s[46:47]
	s_mov_b64 s[8:9], exec
	s_mov_b64 exec, s[52:53]
	v_pk_mul_f32 v[236:237], v[192:193], v[236:237]
	v_pk_mul_f32 v[238:239], v[194:195], v[238:239]
	v_pk_mul_f32 v[240:241], v[196:197], v[240:241]
	v_pk_mul_f32 v[242:243], v[198:199], v[242:243]
	v_pk_mul_f32 v[236:237], v[160:161], v[236:237]
	v_pk_mul_f32 v[238:239], v[160:161], v[238:239]
	v_pk_mul_f32 v[240:241], v[160:161], v[240:241]
	v_pk_mul_f32 v[242:243], v[160:161], v[242:243]
	v_pk_fma_f32 v[52:53], v[52:53], v[164:165], v[236:237]
	v_pk_fma_f32 v[54:55], v[54:55], v[166:167], v[238:239]
	v_pk_fma_f32 v[48:49], v[48:49], v[168:169], v[240:241]
	v_pk_fma_f32 v[50:51], v[50:51], v[170:171], v[242:243]
	s_mov_b64 exec, s[8:9]
	v_pk_mul_f32 v[52:53], v[162:163], v[52:53]
	v_pk_mul_f32 v[54:55], v[162:163], v[54:55]
	v_pk_mul_f32 v[48:49], v[162:163], v[48:49]
	v_pk_mul_f32 v[50:51], v[162:163], v[50:51]
	v_add_u32_e32 v159, 0x4000, v156
	v_cvt_pk_bf16_f32 v52, v52, v53
	v_cvt_pk_bf16_f32 v53, v54, v55
	v_cvt_pk_bf16_f32 v54, v48, v49
	v_cvt_pk_bf16_f32 v55, v50, v51
	global_store_dwordx4 v159, v[52:55], s[20:21]
	v_pk_mul_f32 v[44:45], v[44:45], v[252:253] op_sel:[0,1] op_sel_hi:[1,1]
	v_pk_mul_f32 v[46:47], v[46:47], v[252:253] op_sel:[0,1] op_sel_hi:[1,1]
	v_pk_mul_f32 v[40:41], v[40:41], v[252:253] op_sel:[0,1] op_sel_hi:[1,1]
	v_pk_mul_f32 v[42:43], v[42:43], v[252:253] op_sel:[0,1] op_sel_hi:[1,1]
	v_mov_b32_e32 v216, v44
	v_mov_b32_e32 v217, v44
	v_mov_b32_e32 v218, v45
	v_mov_b32_e32 v219, v45
	v_mov_b32_e32 v220, v46
	v_mov_b32_e32 v221, v46
	v_mov_b32_e32 v222, v47
	v_mov_b32_e32 v223, v47
	v_mov_b32_e32 v224, v40
	v_mov_b32_e32 v225, v40
	v_mov_b32_e32 v226, v41
	v_mov_b32_e32 v227, v41
	v_mov_b32_e32 v228, v42
	v_mov_b32_e32 v229, v42
	v_mov_b32_e32 v230, v43
	v_mov_b32_e32 v231, v43
	v_permlane16_swap_b32_e32 v216, v217
	v_permlane16_swap_b32_e32 v218, v219
	v_permlane16_swap_b32_e32 v220, v221
	v_permlane16_swap_b32_e32 v222, v223
	v_permlane16_swap_b32_e32 v224, v225
	v_permlane16_swap_b32_e32 v226, v227
	v_permlane16_swap_b32_e32 v228, v229
	v_permlane16_swap_b32_e32 v230, v231
	v_cndmask_b32_e64 v236, v217, v216, s[46:47]
	v_cndmask_b32_e64 v237, v219, v218, s[46:47]
	v_cndmask_b32_e64 v238, v221, v220, s[46:47]
	v_cndmask_b32_e64 v239, v223, v222, s[46:47]
	v_cndmask_b32_e64 v240, v225, v224, s[46:47]
	v_cndmask_b32_e64 v241, v227, v226, s[46:47]
	v_cndmask_b32_e64 v242, v229, v228, s[46:47]
	v_cndmask_b32_e64 v243, v231, v230, s[46:47]
	s_mov_b64 s[8:9], exec
	s_mov_b64 exec, s[52:53]
	v_pk_mul_f32 v[236:237], v[208:209], v[236:237]
	v_pk_mul_f32 v[238:239], v[210:211], v[238:239]
	v_pk_mul_f32 v[240:241], v[232:233], v[240:241]
	v_pk_mul_f32 v[242:243], v[234:235], v[242:243]
	v_pk_mul_f32 v[236:237], v[160:161], v[236:237]
	v_pk_mul_f32 v[238:239], v[160:161], v[238:239]
	v_pk_mul_f32 v[240:241], v[160:161], v[240:241]
	v_pk_mul_f32 v[242:243], v[160:161], v[242:243]
	v_pk_fma_f32 v[44:45], v[44:45], v[200:201], v[236:237]
	v_pk_fma_f32 v[46:47], v[46:47], v[202:203], v[238:239]
	v_pk_fma_f32 v[40:41], v[40:41], v[204:205], v[240:241]
	v_pk_fma_f32 v[42:43], v[42:43], v[206:207], v[242:243]
	s_mov_b64 exec, s[8:9]
	v_pk_mul_f32 v[44:45], v[162:163], v[44:45]
	v_pk_mul_f32 v[46:47], v[162:163], v[46:47]
	v_pk_mul_f32 v[40:41], v[162:163], v[40:41]
	v_pk_mul_f32 v[42:43], v[162:163], v[42:43]
	v_add_u32_e32 v159, 0x4800, v155
	v_cvt_pk_bf16_f32 v44, v44, v45
	v_cvt_pk_bf16_f32 v45, v46, v47
	v_cvt_pk_bf16_f32 v46, v40, v41
	v_cvt_pk_bf16_f32 v47, v42, v43
	global_store_dwordx4 v159, v[44:47], s[20:21]
	v_pk_mul_f32 v[36:37], v[36:37], v[252:253] op_sel:[0,1] op_sel_hi:[1,1]
	v_pk_mul_f32 v[38:39], v[38:39], v[252:253] op_sel:[0,1] op_sel_hi:[1,1]
	v_pk_mul_f32 v[32:33], v[32:33], v[252:253] op_sel:[0,1] op_sel_hi:[1,1]
	v_pk_mul_f32 v[34:35], v[34:35], v[252:253] op_sel:[0,1] op_sel_hi:[1,1]
	v_mov_b32_e32 v216, v36
	v_mov_b32_e32 v217, v36
	v_mov_b32_e32 v218, v37
	v_mov_b32_e32 v219, v37
	v_mov_b32_e32 v220, v38
	v_mov_b32_e32 v221, v38
	v_mov_b32_e32 v222, v39
	v_mov_b32_e32 v223, v39
	v_mov_b32_e32 v224, v32
	v_mov_b32_e32 v225, v32
	v_mov_b32_e32 v226, v33
	v_mov_b32_e32 v227, v33
	v_mov_b32_e32 v228, v34
	v_mov_b32_e32 v229, v34
	v_mov_b32_e32 v230, v35
	v_mov_b32_e32 v231, v35
	v_permlane16_swap_b32_e32 v216, v217
	v_permlane16_swap_b32_e32 v218, v219
	v_permlane16_swap_b32_e32 v220, v221
	v_permlane16_swap_b32_e32 v222, v223
	v_permlane16_swap_b32_e32 v224, v225
	v_permlane16_swap_b32_e32 v226, v227
	v_permlane16_swap_b32_e32 v228, v229
	v_permlane16_swap_b32_e32 v230, v231
	v_cndmask_b32_e64 v236, v217, v216, s[46:47]
	v_cndmask_b32_e64 v237, v219, v218, s[46:47]
	v_cndmask_b32_e64 v238, v221, v220, s[46:47]
	v_cndmask_b32_e64 v239, v223, v222, s[46:47]
	v_cndmask_b32_e64 v240, v225, v224, s[46:47]
	v_cndmask_b32_e64 v241, v227, v226, s[46:47]
	v_cndmask_b32_e64 v242, v229, v228, s[46:47]
	v_cndmask_b32_e64 v243, v231, v230, s[46:47]
	s_mov_b64 s[8:9], exec
	s_mov_b64 exec, s[52:53]
	v_pk_mul_f32 v[236:237], v[208:209], v[236:237]
	v_pk_mul_f32 v[238:239], v[210:211], v[238:239]
	v_pk_mul_f32 v[240:241], v[232:233], v[240:241]
	v_pk_mul_f32 v[242:243], v[234:235], v[242:243]
	v_pk_mul_f32 v[236:237], v[160:161], v[236:237]
	v_pk_mul_f32 v[238:239], v[160:161], v[238:239]
	v_pk_mul_f32 v[240:241], v[160:161], v[240:241]
	v_pk_mul_f32 v[242:243], v[160:161], v[242:243]
	v_pk_fma_f32 v[36:37], v[36:37], v[200:201], v[236:237]
	v_pk_fma_f32 v[38:39], v[38:39], v[202:203], v[238:239]
	v_pk_fma_f32 v[32:33], v[32:33], v[204:205], v[240:241]
	v_pk_fma_f32 v[34:35], v[34:35], v[206:207], v[242:243]
	s_mov_b64 exec, s[8:9]
	v_pk_mul_f32 v[36:37], v[162:163], v[36:37]
	v_pk_mul_f32 v[38:39], v[162:163], v[38:39]
	v_pk_mul_f32 v[32:33], v[162:163], v[32:33]
	v_pk_mul_f32 v[34:35], v[162:163], v[34:35]
	v_add_u32_e32 v159, 0x4800, v156
	v_cvt_pk_bf16_f32 v36, v36, v37
	v_cvt_pk_bf16_f32 v37, v38, v39
	v_cvt_pk_bf16_f32 v38, v32, v33
	v_cvt_pk_bf16_f32 v39, v34, v35
	global_store_dwordx4 v159, v[36:39], s[20:21]
	v_add_u32_e32 v158, 0x2800, v157
	s_mov_b64 s[8:9], exec
	s_mov_b64 exec, s[52:53]
	global_load_dwordx4 v[164:167], v158, s[14:15] offset:0
	global_load_dwordx4 v[168:171], v158, s[14:15] offset:16
	global_load_dwordx4 v[192:195], v158, s[14:15] offset:32
	global_load_dwordx4 v[196:199], v158, s[14:15] offset:48
	global_load_dwordx4 v[200:203], v158, s[14:15] offset:1024
	global_load_dwordx4 v[204:207], v158, s[14:15] offset:1040
	global_load_dwordx4 v[208:211], v158, s[14:15] offset:1056
	global_load_dwordx4 v[232:235], v158, s[14:15] offset:1072
	s_mov_b64 exec, s[8:9]
	v_pk_mul_f32 v[28:29], v[28:29], v[254:255] op_sel_hi:[1,0]
	v_pk_mul_f32 v[30:31], v[30:31], v[254:255] op_sel_hi:[1,0]
	v_pk_mul_f32 v[24:25], v[24:25], v[254:255] op_sel_hi:[1,0]
	v_pk_mul_f32 v[26:27], v[26:27], v[254:255] op_sel_hi:[1,0]
	v_mov_b32_e32 v216, v28
	v_mov_b32_e32 v217, v28
	v_mov_b32_e32 v218, v29
	v_mov_b32_e32 v219, v29
	v_mov_b32_e32 v220, v30
	v_mov_b32_e32 v221, v30
	v_mov_b32_e32 v222, v31
	v_mov_b32_e32 v223, v31
	v_mov_b32_e32 v224, v24
	v_mov_b32_e32 v225, v24
	v_mov_b32_e32 v226, v25
	v_mov_b32_e32 v227, v25
	v_mov_b32_e32 v228, v26
	v_mov_b32_e32 v229, v26
	v_mov_b32_e32 v230, v27
	v_mov_b32_e32 v231, v27
	v_permlane16_swap_b32_e32 v216, v217
	v_permlane16_swap_b32_e32 v218, v219
	v_permlane16_swap_b32_e32 v220, v221
	v_permlane16_swap_b32_e32 v222, v223
	v_permlane16_swap_b32_e32 v224, v225
	v_permlane16_swap_b32_e32 v226, v227
	v_permlane16_swap_b32_e32 v228, v229
	v_permlane16_swap_b32_e32 v230, v231
	v_cndmask_b32_e64 v236, v217, v216, s[46:47]
	v_cndmask_b32_e64 v237, v219, v218, s[46:47]
	v_cndmask_b32_e64 v238, v221, v220, s[46:47]
	v_cndmask_b32_e64 v239, v223, v222, s[46:47]
	v_cndmask_b32_e64 v240, v225, v224, s[46:47]
	v_cndmask_b32_e64 v241, v227, v226, s[46:47]
	v_cndmask_b32_e64 v242, v229, v228, s[46:47]
	v_cndmask_b32_e64 v243, v231, v230, s[46:47]
	s_waitcnt vmcnt(0)
	s_mov_b64 s[8:9], exec
	s_mov_b64 exec, s[52:53]
	v_pk_mul_f32 v[236:237], v[192:193], v[236:237]
	v_pk_mul_f32 v[238:239], v[194:195], v[238:239]
	v_pk_mul_f32 v[240:241], v[196:197], v[240:241]
	v_pk_mul_f32 v[242:243], v[198:199], v[242:243]
	v_pk_mul_f32 v[236:237], v[160:161], v[236:237]
	v_pk_mul_f32 v[238:239], v[160:161], v[238:239]
	v_pk_mul_f32 v[240:241], v[160:161], v[240:241]
	v_pk_mul_f32 v[242:243], v[160:161], v[242:243]
	v_pk_fma_f32 v[28:29], v[28:29], v[164:165], v[236:237]
	v_pk_fma_f32 v[30:31], v[30:31], v[166:167], v[238:239]
	v_pk_fma_f32 v[24:25], v[24:25], v[168:169], v[240:241]
	v_pk_fma_f32 v[26:27], v[26:27], v[170:171], v[242:243]
	s_mov_b64 exec, s[8:9]
	v_pk_mul_f32 v[28:29], v[162:163], v[28:29]
	v_pk_mul_f32 v[30:31], v[162:163], v[30:31]
	v_pk_mul_f32 v[24:25], v[162:163], v[24:25]
	v_pk_mul_f32 v[26:27], v[162:163], v[26:27]
	v_add_u32_e32 v159, 0x5000, v155
	v_cvt_pk_bf16_f32 v28, v28, v29
	v_cvt_pk_bf16_f32 v29, v30, v31
	v_cvt_pk_bf16_f32 v30, v24, v25
	v_cvt_pk_bf16_f32 v31, v26, v27
	global_store_dwordx4 v159, v[28:31], s[20:21]
	v_pk_mul_f32 v[20:21], v[20:21], v[254:255] op_sel_hi:[1,0]
	v_pk_mul_f32 v[22:23], v[22:23], v[254:255] op_sel_hi:[1,0]
	v_pk_mul_f32 v[16:17], v[16:17], v[254:255] op_sel_hi:[1,0]
	v_pk_mul_f32 v[18:19], v[18:19], v[254:255] op_sel_hi:[1,0]
	v_mov_b32_e32 v216, v20
	v_mov_b32_e32 v217, v20
	v_mov_b32_e32 v218, v21
	v_mov_b32_e32 v219, v21
	v_mov_b32_e32 v220, v22
	v_mov_b32_e32 v221, v22
	v_mov_b32_e32 v222, v23
	v_mov_b32_e32 v223, v23
	v_mov_b32_e32 v224, v16
	v_mov_b32_e32 v225, v16
	v_mov_b32_e32 v226, v17
	v_mov_b32_e32 v227, v17
	v_mov_b32_e32 v228, v18
	v_mov_b32_e32 v229, v18
	v_mov_b32_e32 v230, v19
	v_mov_b32_e32 v231, v19
	v_permlane16_swap_b32_e32 v216, v217
	v_permlane16_swap_b32_e32 v218, v219
	v_permlane16_swap_b32_e32 v220, v221
	v_permlane16_swap_b32_e32 v222, v223
	v_permlane16_swap_b32_e32 v224, v225
	v_permlane16_swap_b32_e32 v226, v227
	v_permlane16_swap_b32_e32 v228, v229
	v_permlane16_swap_b32_e32 v230, v231
	v_cndmask_b32_e64 v236, v217, v216, s[46:47]
	v_cndmask_b32_e64 v237, v219, v218, s[46:47]
	v_cndmask_b32_e64 v238, v221, v220, s[46:47]
	v_cndmask_b32_e64 v239, v223, v222, s[46:47]
	v_cndmask_b32_e64 v240, v225, v224, s[46:47]
	v_cndmask_b32_e64 v241, v227, v226, s[46:47]
	v_cndmask_b32_e64 v242, v229, v228, s[46:47]
	v_cndmask_b32_e64 v243, v231, v230, s[46:47]
	s_mov_b64 s[8:9], exec
	s_mov_b64 exec, s[52:53]
	v_pk_mul_f32 v[236:237], v[192:193], v[236:237]
	v_pk_mul_f32 v[238:239], v[194:195], v[238:239]
	v_pk_mul_f32 v[240:241], v[196:197], v[240:241]
	v_pk_mul_f32 v[242:243], v[198:199], v[242:243]
	v_pk_mul_f32 v[236:237], v[160:161], v[236:237]
	v_pk_mul_f32 v[238:239], v[160:161], v[238:239]
	v_pk_mul_f32 v[240:241], v[160:161], v[240:241]
	v_pk_mul_f32 v[242:243], v[160:161], v[242:243]
	v_pk_fma_f32 v[20:21], v[20:21], v[164:165], v[236:237]
	v_pk_fma_f32 v[22:23], v[22:23], v[166:167], v[238:239]
	v_pk_fma_f32 v[16:17], v[16:17], v[168:169], v[240:241]
	v_pk_fma_f32 v[18:19], v[18:19], v[170:171], v[242:243]
	s_mov_b64 exec, s[8:9]
	v_pk_mul_f32 v[20:21], v[162:163], v[20:21]
	v_pk_mul_f32 v[22:23], v[162:163], v[22:23]
	v_pk_mul_f32 v[16:17], v[162:163], v[16:17]
	v_pk_mul_f32 v[18:19], v[162:163], v[18:19]
	v_add_u32_e32 v159, 0x5000, v156
	v_cvt_pk_bf16_f32 v20, v20, v21
	v_cvt_pk_bf16_f32 v21, v22, v23
	v_cvt_pk_bf16_f32 v22, v16, v17
	v_cvt_pk_bf16_f32 v23, v18, v19
	global_store_dwordx4 v159, v[20:23], s[20:21]
	v_pk_mul_f32 v[12:13], v[12:13], v[254:255] op_sel:[0,1] op_sel_hi:[1,1]
	v_pk_mul_f32 v[14:15], v[14:15], v[254:255] op_sel:[0,1] op_sel_hi:[1,1]
	v_pk_mul_f32 v[8:9], v[8:9], v[254:255] op_sel:[0,1] op_sel_hi:[1,1]
	v_pk_mul_f32 v[10:11], v[10:11], v[254:255] op_sel:[0,1] op_sel_hi:[1,1]
	v_mov_b32_e32 v216, v12
	v_mov_b32_e32 v217, v12
	v_mov_b32_e32 v218, v13
	v_mov_b32_e32 v219, v13
	v_mov_b32_e32 v220, v14
	v_mov_b32_e32 v221, v14
	v_mov_b32_e32 v222, v15
	v_mov_b32_e32 v223, v15
	v_mov_b32_e32 v224, v8
	v_mov_b32_e32 v225, v8
	v_mov_b32_e32 v226, v9
	v_mov_b32_e32 v227, v9
	v_mov_b32_e32 v228, v10
	v_mov_b32_e32 v229, v10
	v_mov_b32_e32 v230, v11
	v_mov_b32_e32 v231, v11
	v_permlane16_swap_b32_e32 v216, v217
	v_permlane16_swap_b32_e32 v218, v219
	v_permlane16_swap_b32_e32 v220, v221
	v_permlane16_swap_b32_e32 v222, v223
	v_permlane16_swap_b32_e32 v224, v225
	v_permlane16_swap_b32_e32 v226, v227
	v_permlane16_swap_b32_e32 v228, v229
	v_permlane16_swap_b32_e32 v230, v231
	v_cndmask_b32_e64 v236, v217, v216, s[46:47]
	v_cndmask_b32_e64 v237, v219, v218, s[46:47]
	v_cndmask_b32_e64 v238, v221, v220, s[46:47]
	v_cndmask_b32_e64 v239, v223, v222, s[46:47]
	v_cndmask_b32_e64 v240, v225, v224, s[46:47]
	v_cndmask_b32_e64 v241, v227, v226, s[46:47]
	v_cndmask_b32_e64 v242, v229, v228, s[46:47]
	v_cndmask_b32_e64 v243, v231, v230, s[46:47]
	s_mov_b64 s[8:9], exec
	s_mov_b64 exec, s[52:53]
	v_pk_mul_f32 v[236:237], v[208:209], v[236:237]
	v_pk_mul_f32 v[238:239], v[210:211], v[238:239]
	v_pk_mul_f32 v[240:241], v[232:233], v[240:241]
	v_pk_mul_f32 v[242:243], v[234:235], v[242:243]
	v_pk_mul_f32 v[236:237], v[160:161], v[236:237]
	v_pk_mul_f32 v[238:239], v[160:161], v[238:239]
	v_pk_mul_f32 v[240:241], v[160:161], v[240:241]
	v_pk_mul_f32 v[242:243], v[160:161], v[242:243]
	v_pk_fma_f32 v[12:13], v[12:13], v[200:201], v[236:237]
	v_pk_fma_f32 v[14:15], v[14:15], v[202:203], v[238:239]
	v_pk_fma_f32 v[8:9], v[8:9], v[204:205], v[240:241]
	v_pk_fma_f32 v[10:11], v[10:11], v[206:207], v[242:243]
	s_mov_b64 exec, s[8:9]
	v_pk_mul_f32 v[12:13], v[162:163], v[12:13]
	v_pk_mul_f32 v[14:15], v[162:163], v[14:15]
	v_pk_mul_f32 v[8:9], v[162:163], v[8:9]
	v_pk_mul_f32 v[10:11], v[162:163], v[10:11]
	v_add_u32_e32 v159, 0x5800, v155
	v_cvt_pk_bf16_f32 v12, v12, v13
	v_cvt_pk_bf16_f32 v13, v14, v15
	v_cvt_pk_bf16_f32 v14, v8, v9
	v_cvt_pk_bf16_f32 v15, v10, v11
	global_store_dwordx4 v159, v[12:15], s[20:21]
	v_pk_mul_f32 v[4:5], v[4:5], v[254:255] op_sel:[0,1] op_sel_hi:[1,1]
	v_pk_mul_f32 v[6:7], v[6:7], v[254:255] op_sel:[0,1] op_sel_hi:[1,1]
	v_pk_mul_f32 v[0:1], v[0:1], v[254:255] op_sel:[0,1] op_sel_hi:[1,1]
	v_pk_mul_f32 v[2:3], v[2:3], v[254:255] op_sel:[0,1] op_sel_hi:[1,1]
	v_mov_b32_e32 v216, v4
	v_mov_b32_e32 v217, v4
	v_mov_b32_e32 v218, v5
	v_mov_b32_e32 v219, v5
	v_mov_b32_e32 v220, v6
	v_mov_b32_e32 v221, v6
	v_mov_b32_e32 v222, v7
	v_mov_b32_e32 v223, v7
	v_mov_b32_e32 v224, v0
	v_mov_b32_e32 v225, v0
	v_mov_b32_e32 v226, v1
	v_mov_b32_e32 v227, v1
	v_mov_b32_e32 v228, v2
	v_mov_b32_e32 v229, v2
	v_mov_b32_e32 v230, v3
	v_mov_b32_e32 v231, v3
	v_permlane16_swap_b32_e32 v216, v217
	v_permlane16_swap_b32_e32 v218, v219
	v_permlane16_swap_b32_e32 v220, v221
	v_permlane16_swap_b32_e32 v222, v223
	v_permlane16_swap_b32_e32 v224, v225
	v_permlane16_swap_b32_e32 v226, v227
	v_permlane16_swap_b32_e32 v228, v229
	v_permlane16_swap_b32_e32 v230, v231
	v_cndmask_b32_e64 v236, v217, v216, s[46:47]
	v_cndmask_b32_e64 v237, v219, v218, s[46:47]
	v_cndmask_b32_e64 v238, v221, v220, s[46:47]
	v_cndmask_b32_e64 v239, v223, v222, s[46:47]
	v_cndmask_b32_e64 v240, v225, v224, s[46:47]
	v_cndmask_b32_e64 v241, v227, v226, s[46:47]
	v_cndmask_b32_e64 v242, v229, v228, s[46:47]
	v_cndmask_b32_e64 v243, v231, v230, s[46:47]
	s_mov_b64 s[8:9], exec
	s_mov_b64 exec, s[52:53]
	v_pk_mul_f32 v[236:237], v[208:209], v[236:237]
	v_pk_mul_f32 v[238:239], v[210:211], v[238:239]
	v_pk_mul_f32 v[240:241], v[232:233], v[240:241]
	v_pk_mul_f32 v[242:243], v[234:235], v[242:243]
	v_pk_mul_f32 v[236:237], v[160:161], v[236:237]
	v_pk_mul_f32 v[238:239], v[160:161], v[238:239]
	v_pk_mul_f32 v[240:241], v[160:161], v[240:241]
	v_pk_mul_f32 v[242:243], v[160:161], v[242:243]
	v_pk_fma_f32 v[4:5], v[4:5], v[200:201], v[236:237]
	v_pk_fma_f32 v[6:7], v[6:7], v[202:203], v[238:239]
	v_pk_fma_f32 v[0:1], v[0:1], v[204:205], v[240:241]
	v_pk_fma_f32 v[2:3], v[2:3], v[206:207], v[242:243]
	s_mov_b64 exec, s[8:9]
	v_pk_mul_f32 v[4:5], v[162:163], v[4:5]
	v_pk_mul_f32 v[6:7], v[162:163], v[6:7]
	v_pk_mul_f32 v[0:1], v[162:163], v[0:1]
	v_pk_mul_f32 v[2:3], v[162:163], v[2:3]
	v_add_u32_e32 v159, 0x5800, v156
	v_cvt_pk_bf16_f32 v4, v4, v5
	v_cvt_pk_bf16_f32 v5, v6, v7
	v_cvt_pk_bf16_f32 v6, v0, v1
	v_cvt_pk_bf16_f32 v7, v2, v3
	global_store_dwordx4 v159, v[4:7], s[20:21]
	s_branch .Lp1_done
.Lp1_norope:
	v_pk_mul_f32 v[124:125], v[124:125], v[248:249] op_sel_hi:[1,0]
	v_pk_mul_f32 v[126:127], v[126:127], v[248:249] op_sel_hi:[1,0]
	v_pk_mul_f32 v[120:121], v[120:121], v[248:249] op_sel_hi:[1,0]
	v_pk_mul_f32 v[122:123], v[122:123], v[248:249] op_sel_hi:[1,0]
	v_pk_mul_f32 v[124:125], v[162:163], v[124:125]
	v_pk_mul_f32 v[126:127], v[162:163], v[126:127]
	v_pk_mul_f32 v[120:121], v[162:163], v[120:121]
	v_pk_mul_f32 v[122:123], v[162:163], v[122:123]
	v_pk_mul_f32 v[116:117], v[116:117], v[248:249] op_sel_hi:[1,0]
	v_pk_mul_f32 v[118:119], v[118:119], v[248:249] op_sel_hi:[1,0]
	v_pk_mul_f32 v[112:113], v[112:113], v[248:249] op_sel_hi:[1,0]
	v_pk_mul_f32 v[114:115], v[114:115], v[248:249] op_sel_hi:[1,0]
	v_pk_mul_f32 v[116:117], v[162:163], v[116:117]
	v_pk_mul_f32 v[118:119], v[162:163], v[118:119]
	v_pk_mul_f32 v[112:113], v[162:163], v[112:113]
	v_pk_mul_f32 v[114:115], v[162:163], v[114:115]
	v_mov_b32_e32 v159, v155
	v_cvt_pk_bf16_f32 v124, v124, v125
	v_cvt_pk_bf16_f32 v125, v126, v127
	v_cvt_pk_bf16_f32 v126, v120, v121
	v_cvt_pk_bf16_f32 v127, v122, v123
	global_store_dwordx4 v159, v[124:127], s[20:21]
	s_nop 1
	v_mov_b32_e32 v159, v156
	v_cvt_pk_bf16_f32 v116, v116, v117
	v_cvt_pk_bf16_f32 v117, v118, v119
	v_cvt_pk_bf16_f32 v118, v112, v113
	v_cvt_pk_bf16_f32 v119, v114, v115
	global_store_dwordx4 v159, v[116:119], s[20:21]
	v_pk_mul_f32 v[108:109], v[108:109], v[248:249] op_sel:[0,1] op_sel_hi:[1,1]
	v_pk_mul_f32 v[110:111], v[110:111], v[248:249] op_sel:[0,1] op_sel_hi:[1,1]
	v_pk_mul_f32 v[104:105], v[104:105], v[248:249] op_sel:[0,1] op_sel_hi:[1,1]
	v_pk_mul_f32 v[106:107], v[106:107], v[248:249] op_sel:[0,1] op_sel_hi:[1,1]
	v_pk_mul_f32 v[108:109], v[162:163], v[108:109]
	v_pk_mul_f32 v[110:111], v[162:163], v[110:111]
	v_pk_mul_f32 v[104:105], v[162:163], v[104:105]
	v_pk_mul_f32 v[106:107], v[162:163], v[106:107]
	v_pk_mul_f32 v[100:101], v[100:101], v[248:249] op_sel:[0,1] op_sel_hi:[1,1]
	v_pk_mul_f32 v[102:103], v[102:103], v[248:249] op_sel:[0,1] op_sel_hi:[1,1]
	v_pk_mul_f32 v[96:97], v[96:97], v[248:249] op_sel:[0,1] op_sel_hi:[1,1]
	v_pk_mul_f32 v[98:99], v[98:99], v[248:249] op_sel:[0,1] op_sel_hi:[1,1]
	v_pk_mul_f32 v[100:101], v[162:163], v[100:101]
	v_pk_mul_f32 v[102:103], v[162:163], v[102:103]
	v_pk_mul_f32 v[96:97], v[162:163], v[96:97]
	v_pk_mul_f32 v[98:99], v[162:163], v[98:99]
	v_add_u32_e32 v159, 0x800, v155
	v_cvt_pk_bf16_f32 v108, v108, v109
	v_cvt_pk_bf16_f32 v109, v110, v111
	v_cvt_pk_bf16_f32 v110, v104, v105
	v_cvt_pk_bf16_f32 v111, v106, v107
	global_store_dwordx4 v159, v[108:111], s[20:21]
	s_nop 1
	v_add_u32_e32 v159, 0x800, v156
	v_cvt_pk_bf16_f32 v100, v100, v101
	v_cvt_pk_bf16_f32 v101, v102, v103
	v_cvt_pk_bf16_f32 v102, v96, v97
	v_cvt_pk_bf16_f32 v103, v98, v99
	global_store_dwordx4 v159, v[100:103], s[20:21]
	v_pk_mul_f32 v[92:93], v[92:93], v[250:251] op_sel_hi:[1,0]
	v_pk_mul_f32 v[94:95], v[94:95], v[250:251] op_sel_hi:[1,0]
	v_pk_mul_f32 v[88:89], v[88:89], v[250:251] op_sel_hi:[1,0]
	v_pk_mul_f32 v[90:91], v[90:91], v[250:251] op_sel_hi:[1,0]
	v_pk_mul_f32 v[92:93], v[162:163], v[92:93]
	v_pk_mul_f32 v[94:95], v[162:163], v[94:95]
	v_pk_mul_f32 v[88:89], v[162:163], v[88:89]
	v_pk_mul_f32 v[90:91], v[162:163], v[90:91]
	v_pk_mul_f32 v[80:81], v[80:81], v[250:251] op_sel_hi:[1,0]
	v_pk_mul_f32 v[82:83], v[82:83], v[250:251] op_sel_hi:[1,0]
	v_pk_mul_f32 v[72:73], v[72:73], v[250:251] op_sel_hi:[1,0]
	v_pk_mul_f32 v[74:75], v[74:75], v[250:251] op_sel_hi:[1,0]
	v_pk_mul_f32 v[80:81], v[162:163], v[80:81]
	v_pk_mul_f32 v[82:83], v[162:163], v[82:83]
	v_pk_mul_f32 v[72:73], v[162:163], v[72:73]
	v_pk_mul_f32 v[74:75], v[162:163], v[74:75]
	v_add_u32_e32 v159, 0x1000, v155
	v_cvt_pk_bf16_f32 v92, v92, v93
	v_cvt_pk_bf16_f32 v93, v94, v95
	v_cvt_pk_bf16_f32 v94, v88, v89
	v_cvt_pk_bf16_f32 v95, v90, v91
	global_store_dwordx4 v159, v[92:95], s[20:21]
	s_nop 1
	v_add_u32_e32 v159, 0x1000, v156
	v_cvt_pk_bf16_f32 v80, v80, v81
	v_cvt_pk_bf16_f32 v81, v82, v83
	v_cvt_pk_bf16_f32 v82, v72, v73
	v_cvt_pk_bf16_f32 v83, v74, v75
	global_store_dwordx4 v159, v[80:83], s[20:21]
	v_pk_mul_f32 v[84:85], v[84:85], v[250:251] op_sel:[0,1] op_sel_hi:[1,1]
	v_pk_mul_f32 v[86:87], v[86:87], v[250:251] op_sel:[0,1] op_sel_hi:[1,1]
	v_pk_mul_f32 v[76:77], v[76:77], v[250:251] op_sel:[0,1] op_sel_hi:[1,1]
	v_pk_mul_f32 v[78:79], v[78:79], v[250:251] op_sel:[0,1] op_sel_hi:[1,1]
	v_pk_mul_f32 v[84:85], v[162:163], v[84:85]
	v_pk_mul_f32 v[86:87], v[162:163], v[86:87]
	v_pk_mul_f32 v[76:77], v[162:163], v[76:77]
	v_pk_mul_f32 v[78:79], v[162:163], v[78:79]
	v_pk_mul_f32 v[68:69], v[68:69], v[250:251] op_sel:[0,1] op_sel_hi:[1,1]
	v_pk_mul_f32 v[70:71], v[70:71], v[250:251] op_sel:[0,1] op_sel_hi:[1,1]
	v_pk_mul_f32 v[64:65], v[64:65], v[250:251] op_sel:[0,1] op_sel_hi:[1,1]
	v_pk_mul_f32 v[66:67], v[66:67], v[250:251] op_sel:[0,1] op_sel_hi:[1,1]
	v_pk_mul_f32 v[68:69], v[162:163], v[68:69]
	v_pk_mul_f32 v[70:71], v[162:163], v[70:71]
	v_pk_mul_f32 v[64:65], v[162:163], v[64:65]
	v_pk_mul_f32 v[66:67], v[162:163], v[66:67]
	v_add_u32_e32 v159, 0x1800, v155
	v_cvt_pk_bf16_f32 v84, v84, v85
	v_cvt_pk_bf16_f32 v85, v86, v87
	v_cvt_pk_bf16_f32 v86, v76, v77
	v_cvt_pk_bf16_f32 v87, v78, v79
	global_store_dwordx4 v159, v[84:87], s[20:21]
	s_nop 1
	v_add_u32_e32 v159, 0x1800, v156
	v_cvt_pk_bf16_f32 v68, v68, v69
	v_cvt_pk_bf16_f32 v69, v70, v71
	v_cvt_pk_bf16_f32 v70, v64, v65
	v_cvt_pk_bf16_f32 v71, v66, v67
	global_store_dwordx4 v159, v[68:71], s[20:21]
	v_pk_mul_f32 v[60:61], v[60:61], v[252:253] op_sel_hi:[1,0]
	v_pk_mul_f32 v[62:63], v[62:63], v[252:253] op_sel_hi:[1,0]
	v_pk_mul_f32 v[56:57], v[56:57], v[252:253] op_sel_hi:[1,0]
	v_pk_mul_f32 v[58:59], v[58:59], v[252:253] op_sel_hi:[1,0]
	v_pk_mul_f32 v[60:61], v[162:163], v[60:61]
	v_pk_mul_f32 v[62:63], v[162:163], v[62:63]
	v_pk_mul_f32 v[56:57], v[162:163], v[56:57]
	v_pk_mul_f32 v[58:59], v[162:163], v[58:59]
	v_pk_mul_f32 v[52:53], v[52:53], v[252:253] op_sel_hi:[1,0]
	v_pk_mul_f32 v[54:55], v[54:55], v[252:253] op_sel_hi:[1,0]
	v_pk_mul_f32 v[48:49], v[48:49], v[252:253] op_sel_hi:[1,0]
	v_pk_mul_f32 v[50:51], v[50:51], v[252:253] op_sel_hi:[1,0]
	v_pk_mul_f32 v[52:53], v[162:163], v[52:53]
	v_pk_mul_f32 v[54:55], v[162:163], v[54:55]
	v_pk_mul_f32 v[48:49], v[162:163], v[48:49]
	v_pk_mul_f32 v[50:51], v[162:163], v[50:51]
	v_add_u32_e32 v159, 0x4000, v155
	v_cvt_pk_bf16_f32 v60, v60, v61
	v_cvt_pk_bf16_f32 v61, v62, v63
	v_cvt_pk_bf16_f32 v62, v56, v57
	v_cvt_pk_bf16_f32 v63, v58, v59
	global_store_dwordx4 v159, v[60:63], s[20:21]
	s_nop 1
	v_add_u32_e32 v159, 0x4000, v156
	v_cvt_pk_bf16_f32 v52, v52, v53
	v_cvt_pk_bf16_f32 v53, v54, v55
	v_cvt_pk_bf16_f32 v54, v48, v49
	v_cvt_pk_bf16_f32 v55, v50, v51
	global_store_dwordx4 v159, v[52:55], s[20:21]
	v_pk_mul_f32 v[44:45], v[44:45], v[252:253] op_sel:[0,1] op_sel_hi:[1,1]
	v_pk_mul_f32 v[46:47], v[46:47], v[252:253] op_sel:[0,1] op_sel_hi:[1,1]
	v_pk_mul_f32 v[40:41], v[40:41], v[252:253] op_sel:[0,1] op_sel_hi:[1,1]
	v_pk_mul_f32 v[42:43], v[42:43], v[252:253] op_sel:[0,1] op_sel_hi:[1,1]
	v_pk_mul_f32 v[44:45], v[162:163], v[44:45]
	v_pk_mul_f32 v[46:47], v[162:163], v[46:47]
	v_pk_mul_f32 v[40:41], v[162:163], v[40:41]
	v_pk_mul_f32 v[42:43], v[162:163], v[42:43]
	v_pk_mul_f32 v[36:37], v[36:37], v[252:253] op_sel:[0,1] op_sel_hi:[1,1]
	v_pk_mul_f32 v[38:39], v[38:39], v[252:253] op_sel:[0,1] op_sel_hi:[1,1]
	v_pk_mul_f32 v[32:33], v[32:33], v[252:253] op_sel:[0,1] op_sel_hi:[1,1]
	v_pk_mul_f32 v[34:35], v[34:35], v[252:253] op_sel:[0,1] op_sel_hi:[1,1]
	v_pk_mul_f32 v[36:37], v[162:163], v[36:37]
	v_pk_mul_f32 v[38:39], v[162:163], v[38:39]
	v_pk_mul_f32 v[32:33], v[162:163], v[32:33]
	v_pk_mul_f32 v[34:35], v[162:163], v[34:35]
	v_add_u32_e32 v159, 0x4800, v155
	v_cvt_pk_bf16_f32 v44, v44, v45
	v_cvt_pk_bf16_f32 v45, v46, v47
	v_cvt_pk_bf16_f32 v46, v40, v41
	v_cvt_pk_bf16_f32 v47, v42, v43
	global_store_dwordx4 v159, v[44:47], s[20:21]
	s_nop 1
	v_add_u32_e32 v159, 0x4800, v156
	v_cvt_pk_bf16_f32 v36, v36, v37
	v_cvt_pk_bf16_f32 v37, v38, v39
	v_cvt_pk_bf16_f32 v38, v32, v33
	v_cvt_pk_bf16_f32 v39, v34, v35
	global_store_dwordx4 v159, v[36:39], s[20:21]
	v_pk_mul_f32 v[28:29], v[28:29], v[254:255] op_sel_hi:[1,0]
	v_pk_mul_f32 v[30:31], v[30:31], v[254:255] op_sel_hi:[1,0]
	v_pk_mul_f32 v[24:25], v[24:25], v[254:255] op_sel_hi:[1,0]
	v_pk_mul_f32 v[26:27], v[26:27], v[254:255] op_sel_hi:[1,0]
	v_pk_mul_f32 v[28:29], v[162:163], v[28:29]
	v_pk_mul_f32 v[30:31], v[162:163], v[30:31]
	v_pk_mul_f32 v[24:25], v[162:163], v[24:25]
	v_pk_mul_f32 v[26:27], v[162:163], v[26:27]
	v_pk_mul_f32 v[20:21], v[20:21], v[254:255] op_sel_hi:[1,0]
	v_pk_mul_f32 v[22:23], v[22:23], v[254:255] op_sel_hi:[1,0]
	v_pk_mul_f32 v[16:17], v[16:17], v[254:255] op_sel_hi:[1,0]
	v_pk_mul_f32 v[18:19], v[18:19], v[254:255] op_sel_hi:[1,0]
	v_pk_mul_f32 v[20:21], v[162:163], v[20:21]
	v_pk_mul_f32 v[22:23], v[162:163], v[22:23]
	v_pk_mul_f32 v[16:17], v[162:163], v[16:17]
	v_pk_mul_f32 v[18:19], v[162:163], v[18:19]
	v_add_u32_e32 v159, 0x5000, v155
	v_cvt_pk_bf16_f32 v28, v28, v29
	v_cvt_pk_bf16_f32 v29, v30, v31
	v_cvt_pk_bf16_f32 v30, v24, v25
	v_cvt_pk_bf16_f32 v31, v26, v27
	global_store_dwordx4 v159, v[28:31], s[20:21]
	s_nop 1
	v_add_u32_e32 v159, 0x5000, v156
	v_cvt_pk_bf16_f32 v20, v20, v21
	v_cvt_pk_bf16_f32 v21, v22, v23
	v_cvt_pk_bf16_f32 v22, v16, v17
	v_cvt_pk_bf16_f32 v23, v18, v19
	global_store_dwordx4 v159, v[20:23], s[20:21]
	v_pk_mul_f32 v[12:13], v[12:13], v[254:255] op_sel:[0,1] op_sel_hi:[1,1]
	v_pk_mul_f32 v[14:15], v[14:15], v[254:255] op_sel:[0,1] op_sel_hi:[1,1]
	v_pk_mul_f32 v[8:9], v[8:9], v[254:255] op_sel:[0,1] op_sel_hi:[1,1]
	v_pk_mul_f32 v[10:11], v[10:11], v[254:255] op_sel:[0,1] op_sel_hi:[1,1]
	v_pk_mul_f32 v[12:13], v[162:163], v[12:13]
	v_pk_mul_f32 v[14:15], v[162:163], v[14:15]
	v_pk_mul_f32 v[8:9], v[162:163], v[8:9]
	v_pk_mul_f32 v[10:11], v[162:163], v[10:11]
	v_pk_mul_f32 v[4:5], v[4:5], v[254:255] op_sel:[0,1] op_sel_hi:[1,1]
	v_pk_mul_f32 v[6:7], v[6:7], v[254:255] op_sel:[0,1] op_sel_hi:[1,1]
	v_pk_mul_f32 v[0:1], v[0:1], v[254:255] op_sel:[0,1] op_sel_hi:[1,1]
	v_pk_mul_f32 v[2:3], v[2:3], v[254:255] op_sel:[0,1] op_sel_hi:[1,1]
	v_pk_mul_f32 v[4:5], v[162:163], v[4:5]
	v_pk_mul_f32 v[6:7], v[162:163], v[6:7]
	v_pk_mul_f32 v[0:1], v[162:163], v[0:1]
	v_pk_mul_f32 v[2:3], v[162:163], v[2:3]
	v_add_u32_e32 v159, 0x5800, v155
	v_cvt_pk_bf16_f32 v12, v12, v13
	v_cvt_pk_bf16_f32 v13, v14, v15
	v_cvt_pk_bf16_f32 v14, v8, v9
	v_cvt_pk_bf16_f32 v15, v10, v11
	global_store_dwordx4 v159, v[12:15], s[20:21]
	s_nop 1
	v_add_u32_e32 v159, 0x5800, v156
	v_cvt_pk_bf16_f32 v4, v4, v5
	v_cvt_pk_bf16_f32 v5, v6, v7
	v_cvt_pk_bf16_f32 v6, v0, v1
	v_cvt_pk_bf16_f32 v7, v2, v3
	global_store_dwordx4 v159, v[4:7], s[20:21]
.Lp1_done:
.LBB0_237:
	s_andn2_b64 vcc, exec, s[6:7]
	s_mov_b64 s[6:7], -1
	s_cbranch_vccnz .LBB0_163
	s_andn2_b64 vcc, exec, s[12:13]
	s_cbranch_vccnz .LBB0_162
	s_barrier
	s_branch .LBB0_162

.LBB0_533:
	s_add_i32 s97, s97, 1
	s_cmp_lg_u32 s97, 1
	s_cbranch_scc1 .Lp5_req_skip_f
	v_readlane_b32 s20, v244, 14
	v_readlane_b32 s21, v244, 15
	v_readlane_b32 s22, v244, 16
	v_readlane_b32 s23, v244, 17
	s_mul_i32 s16, s33, 0xfe
	v_and_b32_e32 v100, 15, v214
	s_add_i32 s16, s16, -1
	v_lshl_add_u32 v100, v100, 2, s3
	v_add_u32_e32 v100, s16, v100
	v_mov_b32_e32 v101, v100
	v_med3_i32 v101, v101, 0, v220
	v_lshlrev_b32_e32 v101, 2, v101
	v_add_u32_e32 v102, 1, v100
	v_med3_i32 v102, v102, 0, v220
	v_lshlrev_b32_e32 v102, 2, v102
	v_add_u32_e32 v103, 2, v100
	v_med3_i32 v103, v103, 0, v220
	v_lshlrev_b32_e32 v103, 2, v103
	v_add_u32_e32 v104, 3, v100
	v_med3_i32 v104, v104, 0, v220
	v_lshlrev_b32_e32 v104, 2, v104
	v_add_u32_e32 v105, 128, v100
	v_med3_i32 v105, v105, 0, v220
	v_lshlrev_b32_e32 v105, 2, v105
	v_add_u32_e32 v106, 129, v100
	v_med3_i32 v106, v106, 0, v220
	v_lshlrev_b32_e32 v106, 2, v106
	v_add_u32_e32 v107, 130, v100
	v_med3_i32 v107, v107, 0, v220
	v_lshlrev_b32_e32 v107, 2, v107
	v_add_u32_e32 v108, 131, v100
	v_med3_i32 v108, v108, 0, v220
	v_lshlrev_b32_e32 v108, 2, v108
	global_load_dword v248, v101, s[62:63]
	global_load_dword v249, v102, s[62:63]
	global_load_dword v250, v103, s[62:63]
	global_load_dword v251, v104, s[62:63]
	global_load_dword v252, v105, s[62:63]
	global_load_dword v253, v106, s[62:63]
	global_load_dword v254, v107, s[62:63]
	global_load_dword v255, v108, s[62:63]
	s_lshr_b32 s19, s3, 4
	s_lshr_b32 s16, s60, 5
	s_add_i32 s19, s19, s16
	s_add_i32 s17, s19, -6
	s_cmp_lt_u32 s19, 6
	s_cselect_b32 s20, s20, s22
	s_cselect_b32 s21, s21, s23
	s_cselect_b32 s16, s19, s17
	s_mul_i32 s16, s16, 0x2c00
	s_add_u32 s20, s20, s16
	s_addc_u32 s21, s21, 0
	v_and_b32_e32 v109, 63, v214
	s_lshl_b32 s16, s10, 9
	v_lshl_add_u32 v109, v109, 2, s16
	s_and_b32 s16, s97, 1
	s_lshl_b32 s16, s16, 12
	s_lshl_b32 s17, s19, 9
	s_add_i32 s16, s16, s17
	s_add_i32 m0, s16, 0x22400
	s_nop 0
	global_load_lds_dword v109, s[20:21]
	global_load_lds_dword v109, s[20:21] offset:256
.Lp5_req_skip_f:
	s_mul_i32 s6, s97, s83
	s_mul_hi_u32 s7, s97, s84
	s_add_i32 s7, s7, s6
	s_mul_i32 s6, s97, s84
	s_add_u32 s6, s6, s2
	s_addc_u32 s7, s7, s85
	v_cmp_gt_i64_e32 vcc, s[6:7], v[150:151]
	v_cmp_lt_i64_e64 s[8:9], s[6:7], v[148:149]
	s_cbranch_vccnz .LBB0_539
	s_ashr_i32 s7, s6, 31
	s_lshr_b32 s7, s7, 29
	s_add_i32 s11, s6, s7
	s_and_b32 s7, s11, -8
	s_sub_i32 s16, s6, s7
	s_cmp_gt_i32 s16, 3
	s_mov_b64 s[6:7], -1
	s_cbranch_scc0 .LBB0_536
	s_mul_i32 s6, s16, 0x215
	s_add_i32 s17, s6, 4
	s_mov_b64 s[6:7], 0

.LBB0_545:
	s_mul_i32 s28, s33, 0xfe
	s_add_i32 s8, s28, -1
	v_and_b32_e32 v223, 15, v214
	v_lshrrev_b32_e32 v225, 1, v214
	s_lshl_b32 s9, s3, 5
	v_and_or_b32 v225, v225, 24, s60
	s_add_i32 s9, s9, 0x20400
	v_lshl_or_b32 v226, s10, 7, v225
	v_lshl_add_u32 v227, v223, 2, s3
	v_lshl_add_u32 v229, v225, 2, s9
	v_add_u32_e32 v228, s8, v227
	v_lshlrev_b32_e32 v230, 1, v226
	v_mad_u32_u24 v230, v228, s61, v230
	s_and_b32 s11, s97, 1
	s_lshl_b32 s11, s11, 12
	s_add_i32 s11, s11, 0x22400
	v_lshl_add_u32 v226, v225, 2, s11
	ds_read_b128 v[176:179], v226 offset:0
	ds_read_b128 v[180:183], v226 offset:512
	ds_read_b128 v[184:187], v226 offset:1024
	ds_read_b128 v[188:191], v226 offset:1536
	ds_read_b128 v[192:195], v226 offset:2048
	ds_read_b128 v[196:199], v226 offset:2560
	ds_read_b128 v[200:203], v226 offset:3072
	ds_read_b128 v[204:207], v226 offset:3584
	s_lshr_b32 s11, s3, 6
	s_max_u32 s29, s11, 1
	s_lshl_b32 s29, s29, 11
	s_add_i32 s29, s29, 0x20000
	v_lshl_add_u32 v231, v225, 2, s29
	s_lshl_b32 s29, s11, 11
	s_add_i32 s29, s29, 0x21000
	v_lshl_add_u32 v232, v225, 2, s29
	s_addk_i32 s29, 0xfc00
	v_lshl_add_u32 v233, v225, 2, s29
	v_lshlrev_b32_e32 v234, 2, v225
	v_add_u32_e32 v234, 0x21c00, v234
	v_mov_b32_e32 v236, s94
	v_pk_mul_f32 v[48:49], v[48:49], v[248:249] op_sel_hi:[1,0]
	v_pk_mul_f32 v[50:51], v[50:51], v[248:249] op_sel_hi:[1,0]
	v_pk_mul_f32 v[24:25], v[24:25], v[248:249] op_sel_hi:[1,0]
	v_pk_mul_f32 v[26:27], v[26:27], v[248:249] op_sel_hi:[1,0]
	v_pk_mul_f32 v[52:53], v[52:53], v[248:249] op_sel_hi:[1,0]
	v_pk_mul_f32 v[54:55], v[54:55], v[248:249] op_sel_hi:[1,0]
	v_pk_mul_f32 v[28:29], v[28:29], v[248:249] op_sel_hi:[1,0]
	v_pk_mul_f32 v[30:31], v[30:31], v[248:249] op_sel_hi:[1,0]
	v_pk_mul_f32 v[124:125], v[124:125], v[248:249] op_sel:[0,1] op_sel_hi:[1,1]
	v_pk_mul_f32 v[126:127], v[126:127], v[248:249] op_sel:[0,1] op_sel_hi:[1,1]
	v_pk_mul_f32 v[120:121], v[120:121], v[248:249] op_sel:[0,1] op_sel_hi:[1,1]
	v_pk_mul_f32 v[122:123], v[122:123], v[248:249] op_sel:[0,1] op_sel_hi:[1,1]
	v_pk_mul_f32 v[116:117], v[116:117], v[248:249] op_sel:[0,1] op_sel_hi:[1,1]
	v_pk_mul_f32 v[118:119], v[118:119], v[248:249] op_sel:[0,1] op_sel_hi:[1,1]
	v_pk_mul_f32 v[108:109], v[108:109], v[248:249] op_sel:[0,1] op_sel_hi:[1,1]
	v_pk_mul_f32 v[110:111], v[110:111], v[248:249] op_sel:[0,1] op_sel_hi:[1,1]
	v_pk_mul_f32 v[112:113], v[112:113], v[250:251] op_sel_hi:[1,0]
	v_pk_mul_f32 v[114:115], v[114:115], v[250:251] op_sel_hi:[1,0]
	v_pk_mul_f32 v[104:105], v[104:105], v[250:251] op_sel_hi:[1,0]
	v_pk_mul_f32 v[106:107], v[106:107], v[250:251] op_sel_hi:[1,0]
	v_pk_mul_f32 v[100:101], v[100:101], v[250:251] op_sel_hi:[1,0]
	v_pk_mul_f32 v[102:103], v[102:103], v[250:251] op_sel_hi:[1,0]
	v_pk_mul_f32 v[96:97], v[96:97], v[250:251] op_sel_hi:[1,0]
	v_pk_mul_f32 v[98:99], v[98:99], v[250:251] op_sel_hi:[1,0]
	v_pk_mul_f32 v[60:61], v[60:61], v[250:251] op_sel:[0,1] op_sel_hi:[1,1]
	v_pk_mul_f32 v[62:63], v[62:63], v[250:251] op_sel:[0,1] op_sel_hi:[1,1]
	v_pk_mul_f32 v[16:17], v[16:17], v[250:251] op_sel:[0,1] op_sel_hi:[1,1]
	v_pk_mul_f32 v[18:19], v[18:19], v[250:251] op_sel:[0,1] op_sel_hi:[1,1]
	v_pk_mul_f32 v[44:45], v[44:45], v[250:251] op_sel:[0,1] op_sel_hi:[1,1]
	v_pk_mul_f32 v[46:47], v[46:47], v[250:251] op_sel:[0,1] op_sel_hi:[1,1]
	v_pk_mul_f32 v[20:21], v[20:21], v[250:251] op_sel:[0,1] op_sel_hi:[1,1]
	v_pk_mul_f32 v[22:23], v[22:23], v[250:251] op_sel:[0,1] op_sel_hi:[1,1]
	v_pk_mul_f32 v[12:13], v[12:13], v[252:253] op_sel_hi:[1,0]
	v_pk_mul_f32 v[14:15], v[14:15], v[252:253] op_sel_hi:[1,0]
	v_pk_mul_f32 v[8:9], v[8:9], v[252:253] op_sel_hi:[1,0]
	v_pk_mul_f32 v[10:11], v[10:11], v[252:253] op_sel_hi:[1,0]
	v_pk_mul_f32 v[40:41], v[40:41], v[252:253] op_sel_hi:[1,0]
	v_pk_mul_f32 v[42:43], v[42:43], v[252:253] op_sel_hi:[1,0]
	v_pk_mul_f32 v[36:37], v[36:37], v[252:253] op_sel_hi:[1,0]
	v_pk_mul_f32 v[38:39], v[38:39], v[252:253] op_sel_hi:[1,0]
	v_pk_mul_f32 v[92:93], v[92:93], v[252:253] op_sel:[0,1] op_sel_hi:[1,1]
	v_pk_mul_f32 v[94:95], v[94:95], v[252:253] op_sel:[0,1] op_sel_hi:[1,1]
	v_pk_mul_f32 v[88:89], v[88:89], v[252:253] op_sel:[0,1] op_sel_hi:[1,1]
	v_pk_mul_f32 v[90:91], v[90:91], v[252:253] op_sel:[0,1] op_sel_hi:[1,1]
	v_pk_mul_f32 v[84:85], v[84:85], v[252:253] op_sel:[0,1] op_sel_hi:[1,1]
	v_pk_mul_f32 v[86:87], v[86:87], v[252:253] op_sel:[0,1] op_sel_hi:[1,1]
	v_pk_mul_f32 v[76:77], v[76:77], v[252:253] op_sel:[0,1] op_sel_hi:[1,1]
	v_pk_mul_f32 v[78:79], v[78:79], v[252:253] op_sel:[0,1] op_sel_hi:[1,1]
	v_pk_mul_f32 v[80:81], v[80:81], v[254:255] op_sel_hi:[1,0]
	v_pk_mul_f32 v[82:83], v[82:83], v[254:255] op_sel_hi:[1,0]
	v_pk_mul_f32 v[72:73], v[72:73], v[254:255] op_sel_hi:[1,0]
	v_pk_mul_f32 v[74:75], v[74:75], v[254:255] op_sel_hi:[1,0]
	v_pk_mul_f32 v[68:69], v[68:69], v[254:255] op_sel_hi:[1,0]
	v_pk_mul_f32 v[70:71], v[70:71], v[254:255] op_sel_hi:[1,0]
	v_pk_mul_f32 v[64:65], v[64:65], v[254:255] op_sel_hi:[1,0]
	v_pk_mul_f32 v[66:67], v[66:67], v[254:255] op_sel_hi:[1,0]
	v_pk_mul_f32 v[4:5], v[4:5], v[254:255] op_sel:[0,1] op_sel_hi:[1,1]
	v_pk_mul_f32 v[6:7], v[6:7], v[254:255] op_sel:[0,1] op_sel_hi:[1,1]
	v_pk_mul_f32 v[0:1], v[0:1], v[254:255] op_sel:[0,1] op_sel_hi:[1,1]
	v_pk_mul_f32 v[2:3], v[2:3], v[254:255] op_sel:[0,1] op_sel_hi:[1,1]
	v_pk_mul_f32 v[32:33], v[32:33], v[254:255] op_sel:[0,1] op_sel_hi:[1,1]
	v_pk_mul_f32 v[34:35], v[34:35], v[254:255] op_sel:[0,1] op_sel_hi:[1,1]
	v_pk_mul_f32 v[128:129], v[128:129], v[254:255] op_sel:[0,1] op_sel_hi:[1,1]
	v_pk_mul_f32 v[130:131], v[130:131], v[254:255] op_sel:[0,1] op_sel_hi:[1,1]
	s_and_b64 vcc, exec, s[6:7]
	s_cbranch_vccnz .Lp5_req_skip_n
	v_readlane_b32 s12, v244, 14
	v_readlane_b32 s13, v244, 15
	v_readlane_b32 s14, v244, 16
	v_readlane_b32 s15, v244, 17
	s_mul_i32 s9, s76, 0xfe
	v_and_b32_e32 v152, 15, v214
	s_add_i32 s9, s9, -1
	v_lshl_add_u32 v152, v152, 2, s3
	v_add_u32_e32 v152, s9, v152
	v_mov_b32_e32 v153, v152
	v_med3_i32 v153, v153, 0, v220
	v_lshlrev_b32_e32 v153, 2, v153
	v_add_u32_e32 v154, 1, v152
	v_med3_i32 v154, v154, 0, v220
	v_lshlrev_b32_e32 v154, 2, v154
	v_add_u32_e32 v155, 2, v152
	v_med3_i32 v155, v155, 0, v220
	v_lshlrev_b32_e32 v155, 2, v155
	v_add_u32_e32 v156, 3, v152
	v_med3_i32 v156, v156, 0, v220
	v_lshlrev_b32_e32 v156, 2, v156
	v_add_u32_e32 v157, 128, v152
	v_med3_i32 v157, v157, 0, v220
	v_lshlrev_b32_e32 v157, 2, v157
	v_add_u32_e32 v158, 129, v152
	v_med3_i32 v158, v158, 0, v220
	v_lshlrev_b32_e32 v158, 2, v158
	v_add_u32_e32 v159, 130, v152
	v_med3_i32 v159, v159, 0, v220
	v_lshlrev_b32_e32 v159, 2, v159
	v_add_u32_e32 v160, 131, v152
	v_med3_i32 v160, v160, 0, v220
	v_lshlrev_b32_e32 v160, 2, v160
	global_load_dword v248, v153, s[62:63]
	global_load_dword v249, v154, s[62:63]
	global_load_dword v250, v155, s[62:63]
	global_load_dword v251, v156, s[62:63]
	global_load_dword v252, v157, s[62:63]
	global_load_dword v253, v158, s[62:63]
	global_load_dword v254, v159, s[62:63]
	global_load_dword v255, v160, s[62:63]
	s_lshr_b32 s29, s3, 4
	s_lshr_b32 s9, s60, 5
	s_add_i32 s29, s29, s9
	s_add_i32 s11, s29, -6
	s_cmp_lt_u32 s29, 6
	s_cselect_b32 s12, s12, s14
	s_cselect_b32 s13, s13, s15
	s_cselect_b32 s9, s29, s11
	s_mul_i32 s9, s9, 0x2c00
	s_add_u32 s12, s12, s9
	s_addc_u32 s13, s13, 0
	v_and_b32_e32 v161, 63, v214
	s_lshl_b32 s9, s72, 9
	v_lshl_add_u32 v161, v161, 2, s9
	s_add_i32 s9, s97, 1
	s_and_b32 s9, s9, 1
	s_lshl_b32 s9, s9, 12
	s_lshl_b32 s11, s29, 9
	s_add_i32 s9, s9, s11
	s_add_i32 m0, s9, 0x22400
	s_nop 0
	global_load_lds_dword v161, s[12:13]
	global_load_lds_dword v161, s[12:13] offset:256
.Lp5_req_skip_n:
	v_cmp_eq_u32_e32 vcc, 0, v223
	s_and_saveexec_b64 s[30:31], vcc
	ds_write_b128 v229, v[48:51] offset:0
	ds_write_b128 v229, v[24:27] offset:16
	ds_write_b128 v229, v[52:55] offset:512
	ds_write_b128 v229, v[28:31] offset:528
	ds_write_b128 v229, v[12:15] offset:4096
	ds_write_b128 v229, v[8:11] offset:4112
	ds_write_b128 v229, v[40:43] offset:4608
	ds_write_b128 v229, v[36:39] offset:4624
	s_mov_b64 exec, s[30:31]
	v_cmp_eq_u32_e32 vcc, 15, v223
	s_and_saveexec_b64 s[30:31], vcc
	ds_write_b128 v229, v[60:63] offset:1024
	ds_write_b128 v229, v[16:19] offset:1040
	ds_write_b128 v229, v[44:47] offset:1536
	ds_write_b128 v229, v[20:23] offset:1552
	ds_write_b128 v229, v[4:7] offset:5120
	ds_write_b128 v229, v[0:3] offset:5136
	ds_write_b128 v229, v[32:35] offset:5632
	ds_write_b128 v229, v[128:131] offset:5648
	s_mov_b64 exec, s[30:31]
	s_waitcnt lgkmcnt(0)
	s_barrier
	s_cmp_eq_u32 s33, 64
	s_cbranch_scc1 .Lp5_edge
	s_cmp_lt_i32 s33, 64
	s_cselect_b32 s9, 11, 14
	s_lshl_b32 s11, 1, s9
	s_add_i32 s11, s11, s28
	s_add_i32 s11, s11, -2
	s_ashr_i32 s11, s11, s9
	s_add_i32 s29, s28, 0xff
	s_ashr_i32 s29, s29, s9
	s_cmp_lt_i32 s29, s11
	s_cbranch_scc0 .Lp5_edge
	ds_read_b128 v[56:59], v231 offset:0
	ds_read_b128 v[132:135], v231 offset:512
	ds_read_b128 v[152:155], v233 offset:0
	ds_read_b128 v[156:159], v233 offset:512
	s_waitcnt lgkmcnt(0)
	v_mov_b32_dpp v56, v60 row_shr:1 row_mask:0xf bank_mask:0xf
	v_mov_b32_dpp v57, v61 row_shr:1 row_mask:0xf bank_mask:0xf
	v_mov_b32_dpp v58, v62 row_shr:1 row_mask:0xf bank_mask:0xf
	v_mov_b32_dpp v59, v63 row_shr:1 row_mask:0xf bank_mask:0xf
	v_mov_b32_dpp v132, v44 row_shr:1 row_mask:0xf bank_mask:0xf
	v_mov_b32_dpp v133, v45 row_shr:1 row_mask:0xf bank_mask:0xf
	v_mov_b32_dpp v134, v46 row_shr:1 row_mask:0xf bank_mask:0xf
	v_mov_b32_dpp v135, v47 row_shr:1 row_mask:0xf bank_mask:0xf
	v_mov_b32_dpp v152, v48 row_shl:1 row_mask:0xf bank_mask:0xf
	v_mov_b32_dpp v153, v49 row_shl:1 row_mask:0xf bank_mask:0xf
	v_mov_b32_dpp v154, v50 row_shl:1 row_mask:0xf bank_mask:0xf
	v_mov_b32_dpp v155, v51 row_shl:1 row_mask:0xf bank_mask:0xf
	v_mov_b32_dpp v156, v52 row_shl:1 row_mask:0xf bank_mask:0xf
	v_mov_b32_dpp v157, v53 row_shl:1 row_mask:0xf bank_mask:0xf
	v_mov_b32_dpp v158, v54 row_shl:1 row_mask:0xf bank_mask:0xf
	v_mov_b32_dpp v159, v55 row_shl:1 row_mask:0xf bank_mask:0xf
	v_pk_fma_f32 v[56:57], v[176:177], v[56:57], v[200:201]
	v_pk_fma_f32 v[58:59], v[178:179], v[58:59], v[202:203]
	v_pk_fma_f32 v[132:133], v[180:181], v[132:133], v[204:205]
	v_pk_fma_f32 v[134:135], v[182:183], v[134:135], v[206:207]
	v_pk_fma_f32 v[56:57], v[48:49], v[184:185], v[56:57]
	v_pk_fma_f32 v[58:59], v[50:51], v[186:187], v[58:59]
	v_pk_fma_f32 v[132:133], v[52:53], v[188:189], v[132:133]
	v_pk_fma_f32 v[134:135], v[54:55], v[190:191], v[134:135]
	v_pk_fma_f32 v[56:57], v[192:193], v[124:125], v[56:57]
	v_pk_fma_f32 v[58:59], v[194:195], v[126:127], v[58:59]
	v_pk_fma_f32 v[132:133], v[196:197], v[116:117], v[132:133]
	v_pk_fma_f32 v[134:135], v[198:199], v[118:119], v[134:135]
	v_and_b32_e32 v212, 0x7fffffff, v56
	v_and_b32_e32 v213, 0x7fffffff, v57
	v_and_b32_e32 v166, 0x7fffffff, v58
	v_and_b32_e32 v167, 0x7fffffff, v59
	v_pk_fma_f32 v[238:239], v[212:213], s[90:91], 1.0 op_sel_hi:[1,0,0]
	v_pk_fma_f32 v[168:169], v[166:167], s[90:91], 1.0 op_sel_hi:[1,0,0]
	v_pk_mul_f32 v[164:165], v[56:57], v[56:57]
	v_pk_mul_f32 v[172:173], v[58:59], v[58:59]
	v_rcp_f32_e32 v238, v238
	v_rcp_f32_e32 v239, v239
	v_rcp_f32_e32 v168, v168
	v_rcp_f32_e32 v169, v169
	v_pk_mul_f32 v[164:165], v[164:165], s[44:45] op_sel_hi:[1,0]
	v_pk_mul_f32 v[172:173], v[172:173], s[44:45] op_sel_hi:[1,0]
	v_pk_fma_f32 v[246:247], v[238:239], s[92:93], v[236:237] op_sel_hi:[1,0,0]
	v_pk_fma_f32 v[170:171], v[168:169], s[92:93], v[236:237] op_sel_hi:[1,0,0]
	v_exp_f32_e32 v164, v164
	v_exp_f32_e32 v165, v165
	v_exp_f32_e32 v172, v172
	v_exp_f32_e32 v173, v173
	v_pk_fma_f32 v[246:247], v[238:239], v[246:247], s[96:97] op_sel_hi:[1,1,0]
	v_pk_fma_f32 v[170:171], v[168:169], v[170:171], s[96:97] op_sel_hi:[1,1,0]
	v_pk_fma_f32 v[246:247], v[238:239], v[246:247], s[0:1] op_sel_hi:[1,1,0]
	v_pk_fma_f32 v[170:171], v[168:169], v[170:171], s[0:1] op_sel_hi:[1,1,0]
	v_pk_fma_f32 v[246:247], v[238:239], v[246:247], s[4:5] op_sel_hi:[1,1,0]
	v_pk_fma_f32 v[170:171], v[168:169], v[170:171], s[4:5] op_sel_hi:[1,1,0]
	v_pk_mul_f32 v[246:247], v[238:239], v[246:247]
	v_pk_mul_f32 v[170:171], v[168:169], v[170:171]
	v_max_f32_e32 v238, 0, v56
	v_max_f32_e32 v239, 0, v57
	v_max_f32_e32 v168, 0, v58
	v_max_f32_e32 v169, 0, v59
	v_pk_mul_f32 v[246:247], v[164:165], v[246:247]
	v_pk_mul_f32 v[170:171], v[172:173], v[170:171]
	v_pk_fma_f32 v[164:165], v[212:213], v[246:247], v[238:239] neg_lo:[1,0,0] neg_hi:[1,0,0]
	v_pk_fma_f32 v[172:173], v[166:167], v[170:171], v[168:169] neg_lo:[1,0,0] neg_hi:[1,0,0]
	v_pk_mul_f32 v[246:247], v[164:165], v[132:133]
	v_pk_mul_f32 v[170:171], v[172:173], v[134:135]
	v_cvt_pk_bf16_f32 v160, v246, v247
	v_cvt_pk_bf16_f32 v161, v170, v171
	v_pk_fma_f32 v[48:49], v[176:177], v[48:49], v[200:201]
	v_pk_fma_f32 v[50:51], v[178:179], v[50:51], v[202:203]
	v_pk_fma_f32 v[52:53], v[180:181], v[52:53], v[204:205]
	v_pk_fma_f32 v[54:55], v[182:183], v[54:55], v[206:207]
	v_pk_fma_f32 v[48:49], v[124:125], v[184:185], v[48:49]
	v_pk_fma_f32 v[50:51], v[126:127], v[186:187], v[50:51]
	v_pk_fma_f32 v[52:53], v[116:117], v[188:189], v[52:53]
	v_pk_fma_f32 v[54:55], v[118:119], v[190:191], v[54:55]
	v_pk_fma_f32 v[48:49], v[192:193], v[112:113], v[48:49]
	v_pk_fma_f32 v[50:51], v[194:195], v[114:115], v[50:51]
	v_pk_fma_f32 v[52:53], v[196:197], v[100:101], v[52:53]
	v_pk_fma_f32 v[54:55], v[198:199], v[102:103], v[54:55]
	v_and_b32_e32 v212, 0x7fffffff, v48
	v_and_b32_e32 v213, 0x7fffffff, v49
	v_and_b32_e32 v134, 0x7fffffff, v50
	v_and_b32_e32 v135, 0x7fffffff, v51
	v_pk_fma_f32 v[238:239], v[212:213], s[90:91], 1.0 op_sel_hi:[1,0,0]
	v_pk_fma_f32 v[164:165], v[134:135], s[90:91], 1.0 op_sel_hi:[1,0,0]
	v_pk_mul_f32 v[132:133], v[48:49], v[48:49]
	v_pk_mul_f32 v[168:169], v[50:51], v[50:51]
	v_rcp_f32_e32 v238, v238
	v_rcp_f32_e32 v239, v239
	v_rcp_f32_e32 v164, v164
	v_rcp_f32_e32 v165, v165
	v_pk_mul_f32 v[132:133], v[132:133], s[44:45] op_sel_hi:[1,0]
	v_pk_mul_f32 v[168:169], v[168:169], s[44:45] op_sel_hi:[1,0]
	v_pk_fma_f32 v[246:247], v[238:239], s[92:93], v[236:237] op_sel_hi:[1,0,0]
	v_pk_fma_f32 v[166:167], v[164:165], s[92:93], v[236:237] op_sel_hi:[1,0,0]
	v_exp_f32_e32 v132, v132
	v_exp_f32_e32 v133, v133
	v_exp_f32_e32 v168, v168
	v_exp_f32_e32 v169, v169
	v_pk_fma_f32 v[246:247], v[238:239], v[246:247], s[96:97] op_sel_hi:[1,1,0]
	v_pk_fma_f32 v[166:167], v[164:165], v[166:167], s[96:97] op_sel_hi:[1,1,0]
	v_pk_fma_f32 v[246:247], v[238:239], v[246:247], s[0:1] op_sel_hi:[1,1,0]
	v_pk_fma_f32 v[166:167], v[164:165], v[166:167], s[0:1] op_sel_hi:[1,1,0]
	v_pk_fma_f32 v[246:247], v[238:239], v[246:247], s[4:5] op_sel_hi:[1,1,0]
	v_pk_fma_f32 v[166:167], v[164:165], v[166:167], s[4:5] op_sel_hi:[1,1,0]
	v_pk_mul_f32 v[246:247], v[238:239], v[246:247]
	v_pk_mul_f32 v[166:167], v[164:165], v[166:167]
	v_max_f32_e32 v238, 0, v48
	v_max_f32_e32 v239, 0, v49
	v_max_f32_e32 v164, 0, v50
	v_max_f32_e32 v165, 0, v51
	v_pk_mul_f32 v[246:247], v[132:133], v[246:247]
	v_pk_mul_f32 v[166:167], v[168:169], v[166:167]
	v_pk_fma_f32 v[132:133], v[212:213], v[246:247], v[238:239] neg_lo:[1,0,0] neg_hi:[1,0,0]
	v_pk_fma_f32 v[168:169], v[134:135], v[166:167], v[164:165] neg_lo:[1,0,0] neg_hi:[1,0,0]
	v_pk_mul_f32 v[246:247], v[132:133], v[52:53]
	v_pk_mul_f32 v[166:167], v[168:169], v[54:55]
	v_cvt_pk_bf16_f32 v56, v246, v247
	v_cvt_pk_bf16_f32 v57, v166, v167
	v_pk_fma_f32 v[124:125], v[176:177], v[124:125], v[200:201]
	v_pk_fma_f32 v[126:127], v[178:179], v[126:127], v[202:203]
	v_pk_fma_f32 v[116:117], v[180:181], v[116:117], v[204:205]
	v_pk_fma_f32 v[118:119], v[182:183], v[118:119], v[206:207]
	v_pk_fma_f32 v[124:125], v[112:113], v[184:185], v[124:125]
	v_pk_fma_f32 v[126:127], v[114:115], v[186:187], v[126:127]
	v_pk_fma_f32 v[116:117], v[100:101], v[188:189], v[116:117]
	v_pk_fma_f32 v[118:119], v[102:103], v[190:191], v[118:119]
	v_pk_fma_f32 v[124:125], v[192:193], v[60:61], v[124:125]
	v_pk_fma_f32 v[126:127], v[194:195], v[62:63], v[126:127]
	v_pk_fma_f32 v[116:117], v[196:197], v[44:45], v[116:117]
	v_pk_fma_f32 v[118:119], v[198:199], v[46:47], v[118:119]
	v_and_b32_e32 v212, 0x7fffffff, v124
	v_and_b32_e32 v213, 0x7fffffff, v125
	v_and_b32_e32 v54, 0x7fffffff, v126
	v_and_b32_e32 v55, 0x7fffffff, v127
	v_pk_fma_f32 v[238:239], v[212:213], s[90:91], 1.0 op_sel_hi:[1,0,0]
	v_pk_fma_f32 v[132:133], v[54:55], s[90:91], 1.0 op_sel_hi:[1,0,0]
	v_pk_mul_f32 v[52:53], v[124:125], v[124:125]
	v_pk_mul_f32 v[164:165], v[126:127], v[126:127]
	v_rcp_f32_e32 v238, v238
	v_rcp_f32_e32 v239, v239
	v_rcp_f32_e32 v132, v132
	v_rcp_f32_e32 v133, v133
	v_pk_mul_f32 v[52:53], v[52:53], s[44:45] op_sel_hi:[1,0]
	v_pk_mul_f32 v[164:165], v[164:165], s[44:45] op_sel_hi:[1,0]
	v_pk_fma_f32 v[246:247], v[238:239], s[92:93], v[236:237] op_sel_hi:[1,0,0]
	v_pk_fma_f32 v[134:135], v[132:133], s[92:93], v[236:237] op_sel_hi:[1,0,0]
	v_exp_f32_e32 v52, v52
	v_exp_f32_e32 v53, v53
	v_exp_f32_e32 v164, v164
	v_exp_f32_e32 v165, v165
	v_pk_fma_f32 v[246:247], v[238:239], v[246:247], s[96:97] op_sel_hi:[1,1,0]
	v_pk_fma_f32 v[134:135], v[132:133], v[134:135], s[96:97] op_sel_hi:[1,1,0]
	v_pk_fma_f32 v[246:247], v[238:239], v[246:247], s[0:1] op_sel_hi:[1,1,0]
	v_pk_fma_f32 v[134:135], v[132:133], v[134:135], s[0:1] op_sel_hi:[1,1,0]
	v_pk_fma_f32 v[246:247], v[238:239], v[246:247], s[4:5] op_sel_hi:[1,1,0]
	v_pk_fma_f32 v[134:135], v[132:133], v[134:135], s[4:5] op_sel_hi:[1,1,0]
	v_pk_mul_f32 v[246:247], v[238:239], v[246:247]
	v_pk_mul_f32 v[134:135], v[132:133], v[134:135]
	v_max_f32_e32 v238, 0, v124
	v_max_f32_e32 v239, 0, v125
	v_max_f32_e32 v132, 0, v126
	v_max_f32_e32 v133, 0, v127
	v_pk_mul_f32 v[246:247], v[52:53], v[246:247]
	v_pk_mul_f32 v[134:135], v[164:165], v[134:135]
	v_pk_fma_f32 v[52:53], v[212:213], v[246:247], v[238:239] neg_lo:[1,0,0] neg_hi:[1,0,0]
	v_pk_fma_f32 v[164:165], v[54:55], v[134:135], v[132:133] neg_lo:[1,0,0] neg_hi:[1,0,0]
	v_pk_mul_f32 v[246:247], v[52:53], v[116:117]
	v_pk_mul_f32 v[134:135], v[164:165], v[118:119]
	v_cvt_pk_bf16_f32 v48, v246, v247
	v_cvt_pk_bf16_f32 v49, v134, v135
	v_pk_fma_f32 v[112:113], v[176:177], v[112:113], v[200:201]
	v_pk_fma_f32 v[114:115], v[178:179], v[114:115], v[202:203]
	v_pk_fma_f32 v[100:101], v[180:181], v[100:101], v[204:205]
	v_pk_fma_f32 v[102:103], v[182:183], v[102:103], v[206:207]
	v_pk_fma_f32 v[112:113], v[60:61], v[184:185], v[112:113]
	v_pk_fma_f32 v[114:115], v[62:63], v[186:187], v[114:115]
	v_pk_fma_f32 v[100:101], v[44:45], v[188:189], v[100:101]
	v_pk_fma_f32 v[102:103], v[46:47], v[190:191], v[102:103]
	v_pk_fma_f32 v[112:113], v[192:193], v[152:153], v[112:113]
	v_pk_fma_f32 v[114:115], v[194:195], v[154:155], v[114:115]
	v_pk_fma_f32 v[100:101], v[196:197], v[156:157], v[100:101]
	v_pk_fma_f32 v[102:103], v[198:199], v[158:159], v[102:103]
	v_and_b32_e32 v212, 0x7fffffff, v112
	v_and_b32_e32 v213, 0x7fffffff, v113
	v_and_b32_e32 v118, 0x7fffffff, v114
	v_and_b32_e32 v119, 0x7fffffff, v115
	v_pk_fma_f32 v[238:239], v[212:213], s[90:91], 1.0 op_sel_hi:[1,0,0]
	v_pk_fma_f32 v[124:125], v[118:119], s[90:91], 1.0 op_sel_hi:[1,0,0]
	v_pk_mul_f32 v[116:117], v[112:113], v[112:113]
	v_pk_mul_f32 v[132:133], v[114:115], v[114:115]
	v_rcp_f32_e32 v238, v238
	v_rcp_f32_e32 v239, v239
	v_rcp_f32_e32 v124, v124
	v_rcp_f32_e32 v125, v125
	v_pk_mul_f32 v[116:117], v[116:117], s[44:45] op_sel_hi:[1,0]
	v_pk_mul_f32 v[132:133], v[132:133], s[44:45] op_sel_hi:[1,0]
	v_pk_fma_f32 v[246:247], v[238:239], s[92:93], v[236:237] op_sel_hi:[1,0,0]
	v_pk_fma_f32 v[126:127], v[124:125], s[92:93], v[236:237] op_sel_hi:[1,0,0]
	v_exp_f32_e32 v116, v116
	v_exp_f32_e32 v117, v117
	v_exp_f32_e32 v132, v132
	v_exp_f32_e32 v133, v133
	v_pk_fma_f32 v[246:247], v[238:239], v[246:247], s[96:97] op_sel_hi:[1,1,0]
	v_pk_fma_f32 v[126:127], v[124:125], v[126:127], s[96:97] op_sel_hi:[1,1,0]
	v_pk_fma_f32 v[246:247], v[238:239], v[246:247], s[0:1] op_sel_hi:[1,1,0]
	v_pk_fma_f32 v[126:127], v[124:125], v[126:127], s[0:1] op_sel_hi:[1,1,0]
	v_pk_fma_f32 v[246:247], v[238:239], v[246:247], s[4:5] op_sel_hi:[1,1,0]
	v_pk_fma_f32 v[126:127], v[124:125], v[126:127], s[4:5] op_sel_hi:[1,1,0]
	v_pk_mul_f32 v[246:247], v[238:239], v[246:247]
	v_pk_mul_f32 v[126:127], v[124:125], v[126:127]
	v_max_f32_e32 v238, 0, v112
	v_max_f32_e32 v239, 0, v113
	v_max_f32_e32 v124, 0, v114
	v_max_f32_e32 v125, 0, v115
	v_pk_mul_f32 v[246:247], v[116:117], v[246:247]
	v_pk_mul_f32 v[126:127], v[132:133], v[126:127]
	v_pk_fma_f32 v[116:117], v[212:213], v[246:247], v[238:239] neg_lo:[1,0,0] neg_hi:[1,0,0]
	v_pk_fma_f32 v[132:133], v[118:119], v[126:127], v[124:125] neg_lo:[1,0,0] neg_hi:[1,0,0]
	v_pk_mul_f32 v[246:247], v[116:117], v[100:101]
	v_pk_mul_f32 v[126:127], v[132:133], v[102:103]
	v_cvt_pk_bf16_f32 v52, v246, v247
	v_cvt_pk_bf16_f32 v53, v126, v127
	ds_read_b128 v[44:47], v232 offset:0
	ds_read_b128 v[60:63], v232 offset:512
	ds_read_b128 v[100:103], v234 offset:0
	ds_read_b128 v[112:115], v234 offset:512
	s_waitcnt lgkmcnt(0)
	v_mov_b32_dpp v44, v4 row_shr:1 row_mask:0xf bank_mask:0xf
	v_mov_b32_dpp v45, v5 row_shr:1 row_mask:0xf bank_mask:0xf
	v_mov_b32_dpp v46, v6 row_shr:1 row_mask:0xf bank_mask:0xf
	v_mov_b32_dpp v47, v7 row_shr:1 row_mask:0xf bank_mask:0xf
	v_mov_b32_dpp v60, v32 row_shr:1 row_mask:0xf bank_mask:0xf
	v_mov_b32_dpp v61, v33 row_shr:1 row_mask:0xf bank_mask:0xf
	v_mov_b32_dpp v62, v34 row_shr:1 row_mask:0xf bank_mask:0xf
	v_mov_b32_dpp v63, v35 row_shr:1 row_mask:0xf bank_mask:0xf
	v_mov_b32_dpp v100, v12 row_shl:1 row_mask:0xf bank_mask:0xf
	v_mov_b32_dpp v101, v13 row_shl:1 row_mask:0xf bank_mask:0xf
	v_mov_b32_dpp v102, v14 row_shl:1 row_mask:0xf bank_mask:0xf
	v_mov_b32_dpp v103, v15 row_shl:1 row_mask:0xf bank_mask:0xf
	v_mov_b32_dpp v112, v40 row_shl:1 row_mask:0xf bank_mask:0xf
	v_mov_b32_dpp v113, v41 row_shl:1 row_mask:0xf bank_mask:0xf
	v_mov_b32_dpp v114, v42 row_shl:1 row_mask:0xf bank_mask:0xf
	v_mov_b32_dpp v115, v43 row_shl:1 row_mask:0xf bank_mask:0xf
	v_pk_fma_f32 v[44:45], v[176:177], v[44:45], v[200:201]
	v_pk_fma_f32 v[46:47], v[178:179], v[46:47], v[202:203]
	v_pk_fma_f32 v[60:61], v[180:181], v[60:61], v[204:205]
	v_pk_fma_f32 v[62:63], v[182:183], v[62:63], v[206:207]
	v_pk_fma_f32 v[44:45], v[12:13], v[184:185], v[44:45]
	v_pk_fma_f32 v[46:47], v[14:15], v[186:187], v[46:47]
	v_pk_fma_f32 v[60:61], v[40:41], v[188:189], v[60:61]
	v_pk_fma_f32 v[62:63], v[42:43], v[190:191], v[62:63]
	v_pk_fma_f32 v[44:45], v[192:193], v[92:93], v[44:45]
	v_pk_fma_f32 v[46:47], v[194:195], v[94:95], v[46:47]
	v_pk_fma_f32 v[60:61], v[196:197], v[84:85], v[60:61]
	v_pk_fma_f32 v[62:63], v[198:199], v[86:87], v[62:63]
	v_and_b32_e32 v212, 0x7fffffff, v44
	v_and_b32_e32 v213, 0x7fffffff, v45
	v_and_b32_e32 v126, 0x7fffffff, v46
	v_and_b32_e32 v127, 0x7fffffff, v47
	v_pk_fma_f32 v[238:239], v[212:213], s[90:91], 1.0 op_sel_hi:[1,0,0]
	v_pk_fma_f32 v[132:133], v[126:127], s[90:91], 1.0 op_sel_hi:[1,0,0]
	v_pk_mul_f32 v[124:125], v[44:45], v[44:45]
	v_pk_mul_f32 v[152:153], v[46:47], v[46:47]
	v_rcp_f32_e32 v238, v238
	v_rcp_f32_e32 v239, v239
	v_rcp_f32_e32 v132, v132
	v_rcp_f32_e32 v133, v133
	v_pk_mul_f32 v[124:125], v[124:125], s[44:45] op_sel_hi:[1,0]
	v_pk_mul_f32 v[152:153], v[152:153], s[44:45] op_sel_hi:[1,0]
	v_pk_fma_f32 v[246:247], v[238:239], s[92:93], v[236:237] op_sel_hi:[1,0,0]
	v_pk_fma_f32 v[134:135], v[132:133], s[92:93], v[236:237] op_sel_hi:[1,0,0]
	v_exp_f32_e32 v124, v124
	v_exp_f32_e32 v125, v125
	v_exp_f32_e32 v152, v152
	v_exp_f32_e32 v153, v153
	v_pk_fma_f32 v[246:247], v[238:239], v[246:247], s[96:97] op_sel_hi:[1,1,0]
	v_pk_fma_f32 v[134:135], v[132:133], v[134:135], s[96:97] op_sel_hi:[1,1,0]
	v_pk_fma_f32 v[246:247], v[238:239], v[246:247], s[0:1] op_sel_hi:[1,1,0]
	v_pk_fma_f32 v[134:135], v[132:133], v[134:135], s[0:1] op_sel_hi:[1,1,0]
	v_pk_fma_f32 v[246:247], v[238:239], v[246:247], s[4:5] op_sel_hi:[1,1,0]
	v_pk_fma_f32 v[134:135], v[132:133], v[134:135], s[4:5] op_sel_hi:[1,1,0]
	v_pk_mul_f32 v[246:247], v[238:239], v[246:247]
	v_pk_mul_f32 v[134:135], v[132:133], v[134:135]
	v_max_f32_e32 v238, 0, v44
	v_max_f32_e32 v239, 0, v45
	v_max_f32_e32 v132, 0, v46
	v_max_f32_e32 v133, 0, v47
	v_pk_mul_f32 v[246:247], v[124:125], v[246:247]
	v_pk_mul_f32 v[134:135], v[152:153], v[134:135]
	v_pk_fma_f32 v[124:125], v[212:213], v[246:247], v[238:239] neg_lo:[1,0,0] neg_hi:[1,0,0]
	v_pk_fma_f32 v[152:153], v[126:127], v[134:135], v[132:133] neg_lo:[1,0,0] neg_hi:[1,0,0]
	v_pk_mul_f32 v[246:247], v[124:125], v[60:61]
	v_pk_mul_f32 v[134:135], v[152:153], v[62:63]
	v_cvt_pk_bf16_f32 v116, v246, v247
	v_cvt_pk_bf16_f32 v117, v134, v135
	v_pk_fma_f32 v[12:13], v[176:177], v[12:13], v[200:201]
	v_pk_fma_f32 v[14:15], v[178:179], v[14:15], v[202:203]
	v_pk_fma_f32 v[40:41], v[180:181], v[40:41], v[204:205]
	v_pk_fma_f32 v[42:43], v[182:183], v[42:43], v[206:207]
	v_pk_fma_f32 v[12:13], v[92:93], v[184:185], v[12:13]
	v_pk_fma_f32 v[14:15], v[94:95], v[186:187], v[14:15]
	v_pk_fma_f32 v[40:41], v[84:85], v[188:189], v[40:41]
	v_pk_fma_f32 v[42:43], v[86:87], v[190:191], v[42:43]
	v_pk_fma_f32 v[12:13], v[192:193], v[80:81], v[12:13]
	v_pk_fma_f32 v[14:15], v[194:195], v[82:83], v[14:15]
	v_pk_fma_f32 v[40:41], v[196:197], v[68:69], v[40:41]
	v_pk_fma_f32 v[42:43], v[198:199], v[70:71], v[42:43]
	v_and_b32_e32 v212, 0x7fffffff, v12
	v_and_b32_e32 v213, 0x7fffffff, v13
	v_and_b32_e32 v62, 0x7fffffff, v14
	v_and_b32_e32 v63, 0x7fffffff, v15
	v_pk_fma_f32 v[238:239], v[212:213], s[90:91], 1.0 op_sel_hi:[1,0,0]
	v_pk_fma_f32 v[124:125], v[62:63], s[90:91], 1.0 op_sel_hi:[1,0,0]
	v_pk_mul_f32 v[60:61], v[12:13], v[12:13]
	v_pk_mul_f32 v[132:133], v[14:15], v[14:15]
	v_rcp_f32_e32 v238, v238
	v_rcp_f32_e32 v239, v239
	v_rcp_f32_e32 v124, v124
	v_rcp_f32_e32 v125, v125
	v_pk_mul_f32 v[60:61], v[60:61], s[44:45] op_sel_hi:[1,0]
	v_pk_mul_f32 v[132:133], v[132:133], s[44:45] op_sel_hi:[1,0]
	v_pk_fma_f32 v[246:247], v[238:239], s[92:93], v[236:237] op_sel_hi:[1,0,0]
	v_pk_fma_f32 v[126:127], v[124:125], s[92:93], v[236:237] op_sel_hi:[1,0,0]
	v_exp_f32_e32 v60, v60
	v_exp_f32_e32 v61, v61
	v_exp_f32_e32 v132, v132
	v_exp_f32_e32 v133, v133
	v_pk_fma_f32 v[246:247], v[238:239], v[246:247], s[96:97] op_sel_hi:[1,1,0]
	v_pk_fma_f32 v[126:127], v[124:125], v[126:127], s[96:97] op_sel_hi:[1,1,0]
	v_pk_fma_f32 v[246:247], v[238:239], v[246:247], s[0:1] op_sel_hi:[1,1,0]
	v_pk_fma_f32 v[126:127], v[124:125], v[126:127], s[0:1] op_sel_hi:[1,1,0]
	v_pk_fma_f32 v[246:247], v[238:239], v[246:247], s[4:5] op_sel_hi:[1,1,0]
	v_pk_fma_f32 v[126:127], v[124:125], v[126:127], s[4:5] op_sel_hi:[1,1,0]
	v_pk_mul_f32 v[246:247], v[238:239], v[246:247]
	v_pk_mul_f32 v[126:127], v[124:125], v[126:127]
	v_max_f32_e32 v238, 0, v12
	v_max_f32_e32 v239, 0, v13
	v_max_f32_e32 v124, 0, v14
	v_max_f32_e32 v125, 0, v15
	v_pk_mul_f32 v[246:247], v[60:61], v[246:247]
	v_pk_mul_f32 v[126:127], v[132:133], v[126:127]
	v_pk_fma_f32 v[60:61], v[212:213], v[246:247], v[238:239] neg_lo:[1,0,0] neg_hi:[1,0,0]
	v_pk_fma_f32 v[132:133], v[62:63], v[126:127], v[124:125] neg_lo:[1,0,0] neg_hi:[1,0,0]
	v_pk_mul_f32 v[246:247], v[60:61], v[40:41]
	v_pk_mul_f32 v[126:127], v[132:133], v[42:43]
	v_cvt_pk_bf16_f32 v44, v246, v247
	v_cvt_pk_bf16_f32 v45, v126, v127
	v_pk_fma_f32 v[92:93], v[176:177], v[92:93], v[200:201]
	v_pk_fma_f32 v[94:95], v[178:179], v[94:95], v[202:203]
	v_pk_fma_f32 v[84:85], v[180:181], v[84:85], v[204:205]
	v_pk_fma_f32 v[86:87], v[182:183], v[86:87], v[206:207]
	v_pk_fma_f32 v[92:93], v[80:81], v[184:185], v[92:93]
	v_pk_fma_f32 v[94:95], v[82:83], v[186:187], v[94:95]
	v_pk_fma_f32 v[84:85], v[68:69], v[188:189], v[84:85]
	v_pk_fma_f32 v[86:87], v[70:71], v[190:191], v[86:87]
	v_pk_fma_f32 v[92:93], v[192:193], v[4:5], v[92:93]
	v_pk_fma_f32 v[94:95], v[194:195], v[6:7], v[94:95]
	v_pk_fma_f32 v[84:85], v[196:197], v[32:33], v[84:85]
	v_pk_fma_f32 v[86:87], v[198:199], v[34:35], v[86:87]
	v_and_b32_e32 v212, 0x7fffffff, v92
	v_and_b32_e32 v213, 0x7fffffff, v93
	v_and_b32_e32 v42, 0x7fffffff, v94
	v_and_b32_e32 v43, 0x7fffffff, v95
	v_pk_fma_f32 v[238:239], v[212:213], s[90:91], 1.0 op_sel_hi:[1,0,0]
	v_pk_fma_f32 v[60:61], v[42:43], s[90:91], 1.0 op_sel_hi:[1,0,0]
	v_pk_mul_f32 v[40:41], v[92:93], v[92:93]
	v_pk_mul_f32 v[124:125], v[94:95], v[94:95]
	v_rcp_f32_e32 v238, v238
	v_rcp_f32_e32 v239, v239
	v_rcp_f32_e32 v60, v60
	v_rcp_f32_e32 v61, v61
	v_pk_mul_f32 v[40:41], v[40:41], s[44:45] op_sel_hi:[1,0]
	v_pk_mul_f32 v[124:125], v[124:125], s[44:45] op_sel_hi:[1,0]
	v_pk_fma_f32 v[246:247], v[238:239], s[92:93], v[236:237] op_sel_hi:[1,0,0]
	v_pk_fma_f32 v[62:63], v[60:61], s[92:93], v[236:237] op_sel_hi:[1,0,0]
	v_exp_f32_e32 v40, v40
	v_exp_f32_e32 v41, v41
	v_exp_f32_e32 v124, v124
	v_exp_f32_e32 v125, v125
	v_pk_fma_f32 v[246:247], v[238:239], v[246:247], s[96:97] op_sel_hi:[1,1,0]
	v_pk_fma_f32 v[62:63], v[60:61], v[62:63], s[96:97] op_sel_hi:[1,1,0]
	v_pk_fma_f32 v[246:247], v[238:239], v[246:247], s[0:1] op_sel_hi:[1,1,0]
	v_pk_fma_f32 v[62:63], v[60:61], v[62:63], s[0:1] op_sel_hi:[1,1,0]
	v_pk_fma_f32 v[246:247], v[238:239], v[246:247], s[4:5] op_sel_hi:[1,1,0]
	v_pk_fma_f32 v[62:63], v[60:61], v[62:63], s[4:5] op_sel_hi:[1,1,0]
	v_pk_mul_f32 v[246:247], v[238:239], v[246:247]
	v_pk_mul_f32 v[62:63], v[60:61], v[62:63]
	v_max_f32_e32 v238, 0, v92
	v_max_f32_e32 v239, 0, v93
	v_max_f32_e32 v60, 0, v94
	v_max_f32_e32 v61, 0, v95
	v_pk_mul_f32 v[246:247], v[40:41], v[246:247]
	v_pk_mul_f32 v[62:63], v[124:125], v[62:63]
	v_pk_fma_f32 v[40:41], v[212:213], v[246:247], v[238:239] neg_lo:[1,0,0] neg_hi:[1,0,0]
	v_pk_fma_f32 v[124:125], v[42:43], v[62:63], v[60:61] neg_lo:[1,0,0] neg_hi:[1,0,0]
	v_pk_mul_f32 v[246:247], v[40:41], v[84:85]
	v_pk_mul_f32 v[62:63], v[124:125], v[86:87]
	v_cvt_pk_bf16_f32 v12, v246, v247
	v_cvt_pk_bf16_f32 v13, v62, v63
	ds_read_b128 v[40:43], v226 offset:16
	ds_read_b128 v[60:63], v226 offset:528
	ds_read_b128 v[84:87], v226 offset:1040
	ds_read_b128 v[92:95], v226 offset:1552
	ds_read_b128 v[124:127], v226 offset:2064
	ds_read_b128 v[132:135], v226 offset:2576
	ds_read_b128 v[152:155], v226 offset:3088
	ds_read_b128 v[156:159], v226 offset:3600
	v_pk_fma_f32 v[80:81], v[176:177], v[80:81], v[200:201]
	v_pk_fma_f32 v[82:83], v[178:179], v[82:83], v[202:203]
	v_pk_fma_f32 v[68:69], v[180:181], v[68:69], v[204:205]
	v_pk_fma_f32 v[70:71], v[182:183], v[70:71], v[206:207]
	v_pk_fma_f32 v[80:81], v[4:5], v[184:185], v[80:81]
	v_pk_fma_f32 v[82:83], v[6:7], v[186:187], v[82:83]
	v_pk_fma_f32 v[68:69], v[32:33], v[188:189], v[68:69]
	v_pk_fma_f32 v[70:71], v[34:35], v[190:191], v[70:71]
	v_pk_fma_f32 v[80:81], v[192:193], v[100:101], v[80:81]
	v_pk_fma_f32 v[82:83], v[194:195], v[102:103], v[82:83]
	v_pk_fma_f32 v[68:69], v[196:197], v[112:113], v[68:69]
	v_pk_fma_f32 v[70:71], v[198:199], v[114:115], v[70:71]
	v_and_b32_e32 v212, 0x7fffffff, v80
	v_and_b32_e32 v213, 0x7fffffff, v81
	v_and_b32_e32 v170, 0x7fffffff, v82
	v_and_b32_e32 v171, 0x7fffffff, v83
	v_pk_fma_f32 v[238:239], v[212:213], s[90:91], 1.0 op_sel_hi:[1,0,0]
	v_pk_fma_f32 v[172:173], v[170:171], s[90:91], 1.0 op_sel_hi:[1,0,0]
	v_pk_mul_f32 v[168:169], v[80:81], v[80:81]
	v_pk_mul_f32 v[208:209], v[82:83], v[82:83]
	v_rcp_f32_e32 v238, v238
	v_rcp_f32_e32 v239, v239
	v_rcp_f32_e32 v172, v172
	v_rcp_f32_e32 v173, v173
	v_pk_mul_f32 v[168:169], v[168:169], s[44:45] op_sel_hi:[1,0]
	v_pk_mul_f32 v[208:209], v[208:209], s[44:45] op_sel_hi:[1,0]
	v_pk_fma_f32 v[246:247], v[238:239], s[92:93], v[236:237] op_sel_hi:[1,0,0]
	v_pk_fma_f32 v[174:175], v[172:173], s[92:93], v[236:237] op_sel_hi:[1,0,0]
	v_exp_f32_e32 v168, v168
	v_exp_f32_e32 v169, v169
	v_exp_f32_e32 v208, v208
	v_exp_f32_e32 v209, v209
	v_pk_fma_f32 v[246:247], v[238:239], v[246:247], s[96:97] op_sel_hi:[1,1,0]
	v_pk_fma_f32 v[174:175], v[172:173], v[174:175], s[96:97] op_sel_hi:[1,1,0]
	v_pk_fma_f32 v[246:247], v[238:239], v[246:247], s[0:1] op_sel_hi:[1,1,0]
	v_pk_fma_f32 v[174:175], v[172:173], v[174:175], s[0:1] op_sel_hi:[1,1,0]
	v_pk_fma_f32 v[246:247], v[238:239], v[246:247], s[4:5] op_sel_hi:[1,1,0]
	v_pk_fma_f32 v[174:175], v[172:173], v[174:175], s[4:5] op_sel_hi:[1,1,0]
	v_pk_mul_f32 v[246:247], v[238:239], v[246:247]
	v_pk_mul_f32 v[174:175], v[172:173], v[174:175]
	v_max_f32_e32 v238, 0, v80
	v_max_f32_e32 v239, 0, v81
	v_max_f32_e32 v172, 0, v82
	v_max_f32_e32 v173, 0, v83
	v_pk_mul_f32 v[246:247], v[168:169], v[246:247]
	v_pk_mul_f32 v[174:175], v[208:209], v[174:175]
	v_pk_fma_f32 v[168:169], v[212:213], v[246:247], v[238:239] neg_lo:[1,0,0] neg_hi:[1,0,0]
	v_pk_fma_f32 v[208:209], v[170:171], v[174:175], v[172:173] neg_lo:[1,0,0] neg_hi:[1,0,0]
	v_pk_mul_f32 v[246:247], v[168:169], v[68:69]
	v_pk_mul_f32 v[174:175], v[208:209], v[70:71]
	v_cvt_pk_bf16_f32 v164, v246, v247
	v_cvt_pk_bf16_f32 v165, v174, v175
	ds_read_b128 v[4:7], v231 offset:16
	ds_read_b128 v[32:35], v231 offset:528
	ds_read_b128 v[68:71], v233 offset:16
	ds_read_b128 v[80:83], v233 offset:528
	s_waitcnt lgkmcnt(0)
	v_mov_b32_dpp v4, v16 row_shr:1 row_mask:0xf bank_mask:0xf
	v_mov_b32_dpp v5, v17 row_shr:1 row_mask:0xf bank_mask:0xf
	v_mov_b32_dpp v6, v18 row_shr:1 row_mask:0xf bank_mask:0xf
	v_mov_b32_dpp v7, v19 row_shr:1 row_mask:0xf bank_mask:0xf
	v_mov_b32_dpp v32, v20 row_shr:1 row_mask:0xf bank_mask:0xf
	v_mov_b32_dpp v33, v21 row_shr:1 row_mask:0xf bank_mask:0xf
	v_mov_b32_dpp v34, v22 row_shr:1 row_mask:0xf bank_mask:0xf
	v_mov_b32_dpp v35, v23 row_shr:1 row_mask:0xf bank_mask:0xf
	v_mov_b32_dpp v68, v24 row_shl:1 row_mask:0xf bank_mask:0xf
	v_mov_b32_dpp v69, v25 row_shl:1 row_mask:0xf bank_mask:0xf
	v_mov_b32_dpp v70, v26 row_shl:1 row_mask:0xf bank_mask:0xf
	v_mov_b32_dpp v71, v27 row_shl:1 row_mask:0xf bank_mask:0xf
	v_mov_b32_dpp v80, v28 row_shl:1 row_mask:0xf bank_mask:0xf
	v_mov_b32_dpp v81, v29 row_shl:1 row_mask:0xf bank_mask:0xf
	v_mov_b32_dpp v82, v30 row_shl:1 row_mask:0xf bank_mask:0xf
	v_mov_b32_dpp v83, v31 row_shl:1 row_mask:0xf bank_mask:0xf
	v_pk_fma_f32 v[4:5], v[40:41], v[4:5], v[152:153]
	v_pk_fma_f32 v[6:7], v[42:43], v[6:7], v[154:155]
	v_pk_fma_f32 v[32:33], v[60:61], v[32:33], v[156:157]
	v_pk_fma_f32 v[34:35], v[62:63], v[34:35], v[158:159]
	v_pk_fma_f32 v[4:5], v[24:25], v[84:85], v[4:5]
	v_pk_fma_f32 v[6:7], v[26:27], v[86:87], v[6:7]
	v_pk_fma_f32 v[32:33], v[28:29], v[92:93], v[32:33]
	v_pk_fma_f32 v[34:35], v[30:31], v[94:95], v[34:35]
	v_pk_fma_f32 v[4:5], v[124:125], v[120:121], v[4:5]
	v_pk_fma_f32 v[6:7], v[126:127], v[122:123], v[6:7]
	v_pk_fma_f32 v[32:33], v[132:133], v[108:109], v[32:33]
	v_pk_fma_f32 v[34:35], v[134:135], v[110:111], v[34:35]
	v_and_b32_e32 v212, 0x7fffffff, v4
	v_and_b32_e32 v213, 0x7fffffff, v5
	v_and_b32_e32 v102, 0x7fffffff, v6
	v_and_b32_e32 v103, 0x7fffffff, v7
	v_pk_fma_f32 v[238:239], v[212:213], s[90:91], 1.0 op_sel_hi:[1,0,0]
	v_pk_fma_f32 v[112:113], v[102:103], s[90:91], 1.0 op_sel_hi:[1,0,0]
	v_pk_mul_f32 v[100:101], v[4:5], v[4:5]
	v_pk_mul_f32 v[168:169], v[6:7], v[6:7]
	v_rcp_f32_e32 v238, v238
	v_rcp_f32_e32 v239, v239
	v_rcp_f32_e32 v112, v112
	v_rcp_f32_e32 v113, v113
	v_pk_mul_f32 v[100:101], v[100:101], s[44:45] op_sel_hi:[1,0]
	v_pk_mul_f32 v[168:169], v[168:169], s[44:45] op_sel_hi:[1,0]
	v_pk_fma_f32 v[246:247], v[238:239], s[92:93], v[236:237] op_sel_hi:[1,0,0]
	v_pk_fma_f32 v[114:115], v[112:113], s[92:93], v[236:237] op_sel_hi:[1,0,0]
	v_exp_f32_e32 v100, v100
	v_exp_f32_e32 v101, v101
	v_exp_f32_e32 v168, v168
	v_exp_f32_e32 v169, v169
	v_pk_fma_f32 v[246:247], v[238:239], v[246:247], s[96:97] op_sel_hi:[1,1,0]
	v_pk_fma_f32 v[114:115], v[112:113], v[114:115], s[96:97] op_sel_hi:[1,1,0]
	v_pk_fma_f32 v[246:247], v[238:239], v[246:247], s[0:1] op_sel_hi:[1,1,0]
	v_pk_fma_f32 v[114:115], v[112:113], v[114:115], s[0:1] op_sel_hi:[1,1,0]
	v_pk_fma_f32 v[246:247], v[238:239], v[246:247], s[4:5] op_sel_hi:[1,1,0]
	v_pk_fma_f32 v[114:115], v[112:113], v[114:115], s[4:5] op_sel_hi:[1,1,0]
	v_pk_mul_f32 v[246:247], v[238:239], v[246:247]
	v_pk_mul_f32 v[114:115], v[112:113], v[114:115]
	v_max_f32_e32 v238, 0, v4
	v_max_f32_e32 v239, 0, v5
	v_max_f32_e32 v112, 0, v6
	v_max_f32_e32 v113, 0, v7
	v_pk_mul_f32 v[246:247], v[100:101], v[246:247]
	v_pk_mul_f32 v[114:115], v[168:169], v[114:115]
	v_pk_fma_f32 v[100:101], v[212:213], v[246:247], v[238:239] neg_lo:[1,0,0] neg_hi:[1,0,0]
	v_pk_fma_f32 v[168:169], v[102:103], v[114:115], v[112:113] neg_lo:[1,0,0] neg_hi:[1,0,0]
	v_pk_mul_f32 v[246:247], v[100:101], v[32:33]
	v_pk_mul_f32 v[114:115], v[168:169], v[34:35]
	v_cvt_pk_bf16_f32 v162, v246, v247
	v_cvt_pk_bf16_f32 v163, v114, v115
	v_add_u32_e32 v235, -1, v227
	v_mov_b32_e32 v245, v228
	v_cmp_gt_u32_e64 s[38:39], s64, v235
	v_cmp_gt_u32_e32 vcc, s88, v245
	v_mov_b32_e32 v235, v230
	s_and_b64 s[38:39], s[38:39], vcc
	s_and_saveexec_b64 s[30:31], s[38:39]
	global_store_dwordx4 v235, v[160:163], s[50:51]
	s_mov_b64 exec, s[30:31]
	s_nop 1
	v_pk_fma_f32 v[24:25], v[40:41], v[24:25], v[152:153]
	v_pk_fma_f32 v[26:27], v[42:43], v[26:27], v[154:155]
	v_pk_fma_f32 v[28:29], v[60:61], v[28:29], v[156:157]
	v_pk_fma_f32 v[30:31], v[62:63], v[30:31], v[158:159]
	v_pk_fma_f32 v[24:25], v[120:121], v[84:85], v[24:25]
	v_pk_fma_f32 v[26:27], v[122:123], v[86:87], v[26:27]
	v_pk_fma_f32 v[28:29], v[108:109], v[92:93], v[28:29]
	v_pk_fma_f32 v[30:31], v[110:111], v[94:95], v[30:31]
	v_pk_fma_f32 v[24:25], v[124:125], v[104:105], v[24:25]
	v_pk_fma_f32 v[26:27], v[126:127], v[106:107], v[26:27]
	v_pk_fma_f32 v[28:29], v[132:133], v[96:97], v[28:29]
	v_pk_fma_f32 v[30:31], v[134:135], v[98:99], v[30:31]
	v_and_b32_e32 v212, 0x7fffffff, v24
	v_and_b32_e32 v213, 0x7fffffff, v25
	v_and_b32_e32 v6, 0x7fffffff, v26
	v_and_b32_e32 v7, 0x7fffffff, v27
	v_pk_fma_f32 v[238:239], v[212:213], s[90:91], 1.0 op_sel_hi:[1,0,0]
	v_pk_fma_f32 v[32:33], v[6:7], s[90:91], 1.0 op_sel_hi:[1,0,0]
	v_pk_mul_f32 v[4:5], v[24:25], v[24:25]
	v_pk_mul_f32 v[100:101], v[26:27], v[26:27]
	v_rcp_f32_e32 v238, v238
	v_rcp_f32_e32 v239, v239
	v_rcp_f32_e32 v32, v32
	v_rcp_f32_e32 v33, v33
	v_pk_mul_f32 v[4:5], v[4:5], s[44:45] op_sel_hi:[1,0]
	v_pk_mul_f32 v[100:101], v[100:101], s[44:45] op_sel_hi:[1,0]
	v_pk_fma_f32 v[246:247], v[238:239], s[92:93], v[236:237] op_sel_hi:[1,0,0]
	v_pk_fma_f32 v[34:35], v[32:33], s[92:93], v[236:237] op_sel_hi:[1,0,0]
	v_exp_f32_e32 v4, v4
	v_exp_f32_e32 v5, v5
	v_exp_f32_e32 v100, v100
	v_exp_f32_e32 v101, v101
	v_pk_fma_f32 v[246:247], v[238:239], v[246:247], s[96:97] op_sel_hi:[1,1,0]
	v_pk_fma_f32 v[34:35], v[32:33], v[34:35], s[96:97] op_sel_hi:[1,1,0]
	v_pk_fma_f32 v[246:247], v[238:239], v[246:247], s[0:1] op_sel_hi:[1,1,0]
	v_pk_fma_f32 v[34:35], v[32:33], v[34:35], s[0:1] op_sel_hi:[1,1,0]
	v_pk_fma_f32 v[246:247], v[238:239], v[246:247], s[4:5] op_sel_hi:[1,1,0]
	v_pk_fma_f32 v[34:35], v[32:33], v[34:35], s[4:5] op_sel_hi:[1,1,0]
	v_pk_mul_f32 v[246:247], v[238:239], v[246:247]
	v_pk_mul_f32 v[34:35], v[32:33], v[34:35]
	v_max_f32_e32 v238, 0, v24
	v_max_f32_e32 v239, 0, v25
	v_max_f32_e32 v32, 0, v26
	v_max_f32_e32 v33, 0, v27
	v_pk_mul_f32 v[246:247], v[4:5], v[246:247]
	v_pk_mul_f32 v[34:35], v[100:101], v[34:35]
	v_pk_fma_f32 v[4:5], v[212:213], v[246:247], v[238:239] neg_lo:[1,0,0] neg_hi:[1,0,0]
	v_pk_fma_f32 v[100:101], v[6:7], v[34:35], v[32:33] neg_lo:[1,0,0] neg_hi:[1,0,0]
	v_pk_mul_f32 v[246:247], v[4:5], v[28:29]
	v_pk_mul_f32 v[34:35], v[100:101], v[30:31]
	v_cvt_pk_bf16_f32 v58, v246, v247
	v_cvt_pk_bf16_f32 v59, v34, v35
	v_add_u32_e32 v235, 0, v227
	v_add_u32_e32 v245, 1, v228
	v_cmp_gt_u32_e64 s[38:39], s64, v235
	v_cmp_gt_u32_e32 vcc, s88, v245
	v_add_u32_e32 v235, 5632, v230
	s_and_b64 s[38:39], s[38:39], vcc
	s_and_saveexec_b64 s[30:31], s[38:39]
	global_store_dwordx4 v235, v[56:59], s[50:51]
	s_mov_b64 exec, s[30:31]
	s_nop 1
	v_pk_fma_f32 v[120:121], v[40:41], v[120:121], v[152:153]
	v_pk_fma_f32 v[122:123], v[42:43], v[122:123], v[154:155]
	v_pk_fma_f32 v[108:109], v[60:61], v[108:109], v[156:157]
	v_pk_fma_f32 v[110:111], v[62:63], v[110:111], v[158:159]
	v_pk_fma_f32 v[120:121], v[104:105], v[84:85], v[120:121]
	v_pk_fma_f32 v[122:123], v[106:107], v[86:87], v[122:123]
	v_pk_fma_f32 v[108:109], v[96:97], v[92:93], v[108:109]
	v_pk_fma_f32 v[110:111], v[98:99], v[94:95], v[110:111]
	v_pk_fma_f32 v[120:121], v[124:125], v[16:17], v[120:121]
	v_pk_fma_f32 v[122:123], v[126:127], v[18:19], v[122:123]
	v_pk_fma_f32 v[108:109], v[132:133], v[20:21], v[108:109]
	v_pk_fma_f32 v[110:111], v[134:135], v[22:23], v[110:111]
	v_and_b32_e32 v212, 0x7fffffff, v120
	v_and_b32_e32 v213, 0x7fffffff, v121
	v_and_b32_e32 v6, 0x7fffffff, v122
	v_and_b32_e32 v7, 0x7fffffff, v123
	v_pk_fma_f32 v[238:239], v[212:213], s[90:91], 1.0 op_sel_hi:[1,0,0]
	v_pk_fma_f32 v[24:25], v[6:7], s[90:91], 1.0 op_sel_hi:[1,0,0]
	v_pk_mul_f32 v[4:5], v[120:121], v[120:121]
	v_pk_mul_f32 v[28:29], v[122:123], v[122:123]
	v_rcp_f32_e32 v238, v238
	v_rcp_f32_e32 v239, v239
	v_rcp_f32_e32 v24, v24
	v_rcp_f32_e32 v25, v25
	v_pk_mul_f32 v[4:5], v[4:5], s[44:45] op_sel_hi:[1,0]
	v_pk_mul_f32 v[28:29], v[28:29], s[44:45] op_sel_hi:[1,0]
	v_pk_fma_f32 v[246:247], v[238:239], s[92:93], v[236:237] op_sel_hi:[1,0,0]
	v_pk_fma_f32 v[26:27], v[24:25], s[92:93], v[236:237] op_sel_hi:[1,0,0]
	v_exp_f32_e32 v4, v4
	v_exp_f32_e32 v5, v5
	v_exp_f32_e32 v28, v28
	v_exp_f32_e32 v29, v29
	v_pk_fma_f32 v[246:247], v[238:239], v[246:247], s[96:97] op_sel_hi:[1,1,0]
	v_pk_fma_f32 v[26:27], v[24:25], v[26:27], s[96:97] op_sel_hi:[1,1,0]
	v_pk_fma_f32 v[246:247], v[238:239], v[246:247], s[0:1] op_sel_hi:[1,1,0]
	v_pk_fma_f32 v[26:27], v[24:25], v[26:27], s[0:1] op_sel_hi:[1,1,0]
	v_pk_fma_f32 v[246:247], v[238:239], v[246:247], s[4:5] op_sel_hi:[1,1,0]
	v_pk_fma_f32 v[26:27], v[24:25], v[26:27], s[4:5] op_sel_hi:[1,1,0]
	v_pk_mul_f32 v[246:247], v[238:239], v[246:247]
	v_pk_mul_f32 v[26:27], v[24:25], v[26:27]
	v_max_f32_e32 v238, 0, v120
	v_max_f32_e32 v239, 0, v121
	v_max_f32_e32 v24, 0, v122
	v_max_f32_e32 v25, 0, v123
	v_pk_mul_f32 v[246:247], v[4:5], v[246:247]
	v_pk_mul_f32 v[26:27], v[28:29], v[26:27]
	v_pk_fma_f32 v[4:5], v[212:213], v[246:247], v[238:239] neg_lo:[1,0,0] neg_hi:[1,0,0]
	v_pk_fma_f32 v[28:29], v[6:7], v[26:27], v[24:25] neg_lo:[1,0,0] neg_hi:[1,0,0]
	v_pk_mul_f32 v[246:247], v[4:5], v[108:109]
	v_pk_mul_f32 v[26:27], v[28:29], v[110:111]
	v_cvt_pk_bf16_f32 v50, v246, v247
	v_cvt_pk_bf16_f32 v51, v26, v27
	v_add_u32_e32 v235, 1, v227
	v_add_u32_e32 v245, 2, v228
	v_cmp_gt_u32_e64 s[38:39], s64, v235
	v_cmp_gt_u32_e32 vcc, s88, v245
	v_add_u32_e32 v235, 11264, v230
	s_and_b64 s[38:39], s[38:39], vcc
	s_and_saveexec_b64 s[30:31], s[38:39]
	global_store_dwordx4 v235, v[48:51], s[50:51]
	s_mov_b64 exec, s[30:31]
	s_nop 1
	v_pk_fma_f32 v[104:105], v[40:41], v[104:105], v[152:153]
	v_pk_fma_f32 v[106:107], v[42:43], v[106:107], v[154:155]
	v_pk_fma_f32 v[96:97], v[60:61], v[96:97], v[156:157]
	v_pk_fma_f32 v[98:99], v[62:63], v[98:99], v[158:159]
	v_pk_fma_f32 v[104:105], v[16:17], v[84:85], v[104:105]
	v_pk_fma_f32 v[106:107], v[18:19], v[86:87], v[106:107]
	v_pk_fma_f32 v[96:97], v[20:21], v[92:93], v[96:97]
	v_pk_fma_f32 v[98:99], v[22:23], v[94:95], v[98:99]
	v_pk_fma_f32 v[104:105], v[124:125], v[68:69], v[104:105]
	v_pk_fma_f32 v[106:107], v[126:127], v[70:71], v[106:107]
	v_pk_fma_f32 v[96:97], v[132:133], v[80:81], v[96:97]
	v_pk_fma_f32 v[98:99], v[134:135], v[82:83], v[98:99]
	v_and_b32_e32 v212, 0x7fffffff, v104
	v_and_b32_e32 v213, 0x7fffffff, v105
	v_and_b32_e32 v6, 0x7fffffff, v106
	v_and_b32_e32 v7, 0x7fffffff, v107
	v_pk_fma_f32 v[238:239], v[212:213], s[90:91], 1.0 op_sel_hi:[1,0,0]
	v_pk_fma_f32 v[24:25], v[6:7], s[90:91], 1.0 op_sel_hi:[1,0,0]
	v_pk_mul_f32 v[4:5], v[104:105], v[104:105]
	v_pk_mul_f32 v[28:29], v[106:107], v[106:107]
	v_rcp_f32_e32 v238, v238
	v_rcp_f32_e32 v239, v239
	v_rcp_f32_e32 v24, v24
	v_rcp_f32_e32 v25, v25
	v_pk_mul_f32 v[4:5], v[4:5], s[44:45] op_sel_hi:[1,0]
	v_pk_mul_f32 v[28:29], v[28:29], s[44:45] op_sel_hi:[1,0]
	v_pk_fma_f32 v[246:247], v[238:239], s[92:93], v[236:237] op_sel_hi:[1,0,0]
	v_pk_fma_f32 v[26:27], v[24:25], s[92:93], v[236:237] op_sel_hi:[1,0,0]
	v_exp_f32_e32 v4, v4
	v_exp_f32_e32 v5, v5
	v_exp_f32_e32 v28, v28
	v_exp_f32_e32 v29, v29
	v_pk_fma_f32 v[246:247], v[238:239], v[246:247], s[96:97] op_sel_hi:[1,1,0]
	v_pk_fma_f32 v[26:27], v[24:25], v[26:27], s[96:97] op_sel_hi:[1,1,0]
	v_pk_fma_f32 v[246:247], v[238:239], v[246:247], s[0:1] op_sel_hi:[1,1,0]
	v_pk_fma_f32 v[26:27], v[24:25], v[26:27], s[0:1] op_sel_hi:[1,1,0]
	v_pk_fma_f32 v[246:247], v[238:239], v[246:247], s[4:5] op_sel_hi:[1,1,0]
	v_pk_fma_f32 v[26:27], v[24:25], v[26:27], s[4:5] op_sel_hi:[1,1,0]
	v_pk_mul_f32 v[246:247], v[238:239], v[246:247]
	v_pk_mul_f32 v[26:27], v[24:25], v[26:27]
	v_max_f32_e32 v238, 0, v104
	v_max_f32_e32 v239, 0, v105
	v_max_f32_e32 v24, 0, v106
	v_max_f32_e32 v25, 0, v107
	v_pk_mul_f32 v[246:247], v[4:5], v[246:247]
	v_pk_mul_f32 v[26:27], v[28:29], v[26:27]
	v_pk_fma_f32 v[4:5], v[212:213], v[246:247], v[238:239] neg_lo:[1,0,0] neg_hi:[1,0,0]
	v_pk_fma_f32 v[28:29], v[6:7], v[26:27], v[24:25] neg_lo:[1,0,0] neg_hi:[1,0,0]
	v_pk_mul_f32 v[246:247], v[4:5], v[96:97]
	v_pk_mul_f32 v[26:27], v[28:29], v[98:99]
	v_cvt_pk_bf16_f32 v54, v246, v247
	v_cvt_pk_bf16_f32 v55, v26, v27
	v_add_u32_e32 v235, 2, v227
	v_add_u32_e32 v245, 3, v228
	v_cmp_gt_u32_e64 s[38:39], s64, v235
	v_cmp_gt_u32_e32 vcc, s88, v245
	v_add_u32_e32 v235, 16896, v230
	s_and_b64 s[38:39], s[38:39], vcc
	s_and_saveexec_b64 s[30:31], s[38:39]
	global_store_dwordx4 v235, v[52:55], s[50:51]
	s_mov_b64 exec, s[30:31]
	s_nop 1
	ds_read_b128 v[4:7], v232 offset:16
	ds_read_b128 v[16:19], v232 offset:528
	ds_read_b128 v[20:23], v234 offset:16
	ds_read_b128 v[24:27], v234 offset:528
	s_waitcnt lgkmcnt(0)
	v_mov_b32_dpp v4, v0 row_shr:1 row_mask:0xf bank_mask:0xf
	v_mov_b32_dpp v5, v1 row_shr:1 row_mask:0xf bank_mask:0xf
	v_mov_b32_dpp v6, v2 row_shr:1 row_mask:0xf bank_mask:0xf
	v_mov_b32_dpp v7, v3 row_shr:1 row_mask:0xf bank_mask:0xf
	v_mov_b32_dpp v16, v128 row_shr:1 row_mask:0xf bank_mask:0xf
	v_mov_b32_dpp v17, v129 row_shr:1 row_mask:0xf bank_mask:0xf
	v_mov_b32_dpp v18, v130 row_shr:1 row_mask:0xf bank_mask:0xf
	v_mov_b32_dpp v19, v131 row_shr:1 row_mask:0xf bank_mask:0xf
	v_mov_b32_dpp v20, v8 row_shl:1 row_mask:0xf bank_mask:0xf
	v_mov_b32_dpp v21, v9 row_shl:1 row_mask:0xf bank_mask:0xf
	v_mov_b32_dpp v22, v10 row_shl:1 row_mask:0xf bank_mask:0xf
	v_mov_b32_dpp v23, v11 row_shl:1 row_mask:0xf bank_mask:0xf
	v_mov_b32_dpp v24, v36 row_shl:1 row_mask:0xf bank_mask:0xf
	v_mov_b32_dpp v25, v37 row_shl:1 row_mask:0xf bank_mask:0xf
	v_mov_b32_dpp v26, v38 row_shl:1 row_mask:0xf bank_mask:0xf
	v_mov_b32_dpp v27, v39 row_shl:1 row_mask:0xf bank_mask:0xf
	v_pk_fma_f32 v[4:5], v[40:41], v[4:5], v[152:153]
	v_pk_fma_f32 v[6:7], v[42:43], v[6:7], v[154:155]
	v_pk_fma_f32 v[16:17], v[60:61], v[16:17], v[156:157]
	v_pk_fma_f32 v[18:19], v[62:63], v[18:19], v[158:159]
	v_pk_fma_f32 v[4:5], v[8:9], v[84:85], v[4:5]
	v_pk_fma_f32 v[6:7], v[10:11], v[86:87], v[6:7]
	v_pk_fma_f32 v[16:17], v[36:37], v[92:93], v[16:17]
	v_pk_fma_f32 v[18:19], v[38:39], v[94:95], v[18:19]
	v_pk_fma_f32 v[4:5], v[124:125], v[88:89], v[4:5]
	v_pk_fma_f32 v[6:7], v[126:127], v[90:91], v[6:7]
	v_pk_fma_f32 v[16:17], v[132:133], v[76:77], v[16:17]
	v_pk_fma_f32 v[18:19], v[134:135], v[78:79], v[18:19]
	v_and_b32_e32 v212, 0x7fffffff, v4
	v_and_b32_e32 v213, 0x7fffffff, v5
	v_and_b32_e32 v30, 0x7fffffff, v6
	v_and_b32_e32 v31, 0x7fffffff, v7
	v_pk_fma_f32 v[238:239], v[212:213], s[90:91], 1.0 op_sel_hi:[1,0,0]
	v_pk_fma_f32 v[32:33], v[30:31], s[90:91], 1.0 op_sel_hi:[1,0,0]
	v_pk_mul_f32 v[28:29], v[4:5], v[4:5]
	v_pk_mul_f32 v[48:49], v[6:7], v[6:7]
	v_rcp_f32_e32 v238, v238
	v_rcp_f32_e32 v239, v239
	v_rcp_f32_e32 v32, v32
	v_rcp_f32_e32 v33, v33
	v_pk_mul_f32 v[28:29], v[28:29], s[44:45] op_sel_hi:[1,0]
	v_pk_mul_f32 v[48:49], v[48:49], s[44:45] op_sel_hi:[1,0]
	v_pk_fma_f32 v[246:247], v[238:239], s[92:93], v[236:237] op_sel_hi:[1,0,0]
	v_pk_fma_f32 v[34:35], v[32:33], s[92:93], v[236:237] op_sel_hi:[1,0,0]
	v_exp_f32_e32 v28, v28
	v_exp_f32_e32 v29, v29
	v_exp_f32_e32 v48, v48
	v_exp_f32_e32 v49, v49
	v_pk_fma_f32 v[246:247], v[238:239], v[246:247], s[96:97] op_sel_hi:[1,1,0]
	v_pk_fma_f32 v[34:35], v[32:33], v[34:35], s[96:97] op_sel_hi:[1,1,0]
	v_pk_fma_f32 v[246:247], v[238:239], v[246:247], s[0:1] op_sel_hi:[1,1,0]
	v_pk_fma_f32 v[34:35], v[32:33], v[34:35], s[0:1] op_sel_hi:[1,1,0]
	v_pk_fma_f32 v[246:247], v[238:239], v[246:247], s[4:5] op_sel_hi:[1,1,0]
	v_pk_fma_f32 v[34:35], v[32:33], v[34:35], s[4:5] op_sel_hi:[1,1,0]
	v_pk_mul_f32 v[246:247], v[238:239], v[246:247]
	v_pk_mul_f32 v[34:35], v[32:33], v[34:35]
	v_max_f32_e32 v238, 0, v4
	v_max_f32_e32 v239, 0, v5
	v_max_f32_e32 v32, 0, v6
	v_max_f32_e32 v33, 0, v7
	v_pk_mul_f32 v[246:247], v[28:29], v[246:247]
	v_pk_mul_f32 v[34:35], v[48:49], v[34:35]
	v_pk_fma_f32 v[28:29], v[212:213], v[246:247], v[238:239] neg_lo:[1,0,0] neg_hi:[1,0,0]
	v_pk_fma_f32 v[48:49], v[30:31], v[34:35], v[32:33] neg_lo:[1,0,0] neg_hi:[1,0,0]
	v_pk_mul_f32 v[246:247], v[28:29], v[16:17]
	v_pk_mul_f32 v[34:35], v[48:49], v[18:19]
	v_cvt_pk_bf16_f32 v118, v246, v247
	v_cvt_pk_bf16_f32 v119, v34, v35
	v_add_u32_e32 v235, 127, v227
	v_add_u32_e32 v245, 128, v228
	v_cmp_gt_u32_e64 s[38:39], s64, v235
	v_cmp_gt_u32_e32 vcc, s88, v245
	v_add_u32_e32 v235, 720896, v230
	s_and_b64 s[38:39], s[38:39], vcc
	s_and_saveexec_b64 s[30:31], s[38:39]
	global_store_dwordx4 v235, v[116:119], s[50:51]
	s_mov_b64 exec, s[30:31]
	s_nop 1
	v_pk_fma_f32 v[8:9], v[40:41], v[8:9], v[152:153]
	v_pk_fma_f32 v[10:11], v[42:43], v[10:11], v[154:155]
	v_pk_fma_f32 v[36:37], v[60:61], v[36:37], v[156:157]
	v_pk_fma_f32 v[38:39], v[62:63], v[38:39], v[158:159]
	v_pk_fma_f32 v[8:9], v[88:89], v[84:85], v[8:9]
	v_pk_fma_f32 v[10:11], v[90:91], v[86:87], v[10:11]
	v_pk_fma_f32 v[36:37], v[76:77], v[92:93], v[36:37]
	v_pk_fma_f32 v[38:39], v[78:79], v[94:95], v[38:39]
	v_pk_fma_f32 v[8:9], v[124:125], v[72:73], v[8:9]
	v_pk_fma_f32 v[10:11], v[126:127], v[74:75], v[10:11]
	v_pk_fma_f32 v[36:37], v[132:133], v[64:65], v[36:37]
	v_pk_fma_f32 v[38:39], v[134:135], v[66:67], v[38:39]
	v_and_b32_e32 v212, 0x7fffffff, v8
	v_and_b32_e32 v213, 0x7fffffff, v9
	v_and_b32_e32 v6, 0x7fffffff, v10
	v_and_b32_e32 v7, 0x7fffffff, v11
	v_pk_fma_f32 v[238:239], v[212:213], s[90:91], 1.0 op_sel_hi:[1,0,0]
	v_pk_fma_f32 v[16:17], v[6:7], s[90:91], 1.0 op_sel_hi:[1,0,0]
	v_pk_mul_f32 v[4:5], v[8:9], v[8:9]
	v_pk_mul_f32 v[28:29], v[10:11], v[10:11]
	v_rcp_f32_e32 v238, v238
	v_rcp_f32_e32 v239, v239
	v_rcp_f32_e32 v16, v16
	v_rcp_f32_e32 v17, v17
	v_pk_mul_f32 v[4:5], v[4:5], s[44:45] op_sel_hi:[1,0]
	v_pk_mul_f32 v[28:29], v[28:29], s[44:45] op_sel_hi:[1,0]
	v_pk_fma_f32 v[246:247], v[238:239], s[92:93], v[236:237] op_sel_hi:[1,0,0]
	v_pk_fma_f32 v[18:19], v[16:17], s[92:93], v[236:237] op_sel_hi:[1,0,0]
	v_exp_f32_e32 v4, v4
	v_exp_f32_e32 v5, v5
	v_exp_f32_e32 v28, v28
	v_exp_f32_e32 v29, v29
	v_pk_fma_f32 v[246:247], v[238:239], v[246:247], s[96:97] op_sel_hi:[1,1,0]
	v_pk_fma_f32 v[18:19], v[16:17], v[18:19], s[96:97] op_sel_hi:[1,1,0]
	v_pk_fma_f32 v[246:247], v[238:239], v[246:247], s[0:1] op_sel_hi:[1,1,0]
	v_pk_fma_f32 v[18:19], v[16:17], v[18:19], s[0:1] op_sel_hi:[1,1,0]
	v_pk_fma_f32 v[246:247], v[238:239], v[246:247], s[4:5] op_sel_hi:[1,1,0]
	v_pk_fma_f32 v[18:19], v[16:17], v[18:19], s[4:5] op_sel_hi:[1,1,0]
	v_pk_mul_f32 v[246:247], v[238:239], v[246:247]
	v_pk_mul_f32 v[18:19], v[16:17], v[18:19]
	v_max_f32_e32 v238, 0, v8
	v_max_f32_e32 v239, 0, v9
	v_max_f32_e32 v16, 0, v10
	v_max_f32_e32 v17, 0, v11
	v_pk_mul_f32 v[246:247], v[4:5], v[246:247]
	v_pk_mul_f32 v[18:19], v[28:29], v[18:19]
	v_pk_fma_f32 v[4:5], v[212:213], v[246:247], v[238:239] neg_lo:[1,0,0] neg_hi:[1,0,0]
	v_pk_fma_f32 v[28:29], v[6:7], v[18:19], v[16:17] neg_lo:[1,0,0] neg_hi:[1,0,0]
	v_pk_mul_f32 v[246:247], v[4:5], v[36:37]
	v_pk_mul_f32 v[18:19], v[28:29], v[38:39]
	v_cvt_pk_bf16_f32 v46, v246, v247
	v_cvt_pk_bf16_f32 v47, v18, v19
	v_add_u32_e32 v235, 128, v227
	v_add_u32_e32 v245, 129, v228
	v_cmp_gt_u32_e64 s[38:39], s64, v235
	v_cmp_gt_u32_e32 vcc, s88, v245
	v_add_u32_e32 v235, 726528, v230
	s_and_b64 s[38:39], s[38:39], vcc
	s_and_saveexec_b64 s[30:31], s[38:39]
	global_store_dwordx4 v235, v[44:47], s[50:51]
	s_mov_b64 exec, s[30:31]
	s_nop 1
	v_pk_fma_f32 v[88:89], v[40:41], v[88:89], v[152:153]
	v_pk_fma_f32 v[90:91], v[42:43], v[90:91], v[154:155]
	v_pk_fma_f32 v[76:77], v[60:61], v[76:77], v[156:157]
	v_pk_fma_f32 v[78:79], v[62:63], v[78:79], v[158:159]
	v_pk_fma_f32 v[88:89], v[72:73], v[84:85], v[88:89]
	v_pk_fma_f32 v[90:91], v[74:75], v[86:87], v[90:91]
	v_pk_fma_f32 v[76:77], v[64:65], v[92:93], v[76:77]
	v_pk_fma_f32 v[78:79], v[66:67], v[94:95], v[78:79]
	v_pk_fma_f32 v[88:89], v[124:125], v[0:1], v[88:89]
	v_pk_fma_f32 v[90:91], v[126:127], v[2:3], v[90:91]
	v_pk_fma_f32 v[76:77], v[132:133], v[128:129], v[76:77]
	v_pk_fma_f32 v[78:79], v[134:135], v[130:131], v[78:79]
	v_and_b32_e32 v212, 0x7fffffff, v88
	v_and_b32_e32 v213, 0x7fffffff, v89
	v_and_b32_e32 v6, 0x7fffffff, v90
	v_and_b32_e32 v7, 0x7fffffff, v91
	v_pk_fma_f32 v[238:239], v[212:213], s[90:91], 1.0 op_sel_hi:[1,0,0]
	v_pk_fma_f32 v[8:9], v[6:7], s[90:91], 1.0 op_sel_hi:[1,0,0]
	v_pk_mul_f32 v[4:5], v[88:89], v[88:89]
	v_pk_mul_f32 v[16:17], v[90:91], v[90:91]
	v_rcp_f32_e32 v238, v238
	v_rcp_f32_e32 v239, v239
	v_rcp_f32_e32 v8, v8
	v_rcp_f32_e32 v9, v9
	v_pk_mul_f32 v[4:5], v[4:5], s[44:45] op_sel_hi:[1,0]
	v_pk_mul_f32 v[16:17], v[16:17], s[44:45] op_sel_hi:[1,0]
	v_pk_fma_f32 v[246:247], v[238:239], s[92:93], v[236:237] op_sel_hi:[1,0,0]
	v_pk_fma_f32 v[10:11], v[8:9], s[92:93], v[236:237] op_sel_hi:[1,0,0]
	v_exp_f32_e32 v4, v4
	v_exp_f32_e32 v5, v5
	v_exp_f32_e32 v16, v16
	v_exp_f32_e32 v17, v17
	v_pk_fma_f32 v[246:247], v[238:239], v[246:247], s[96:97] op_sel_hi:[1,1,0]
	v_pk_fma_f32 v[10:11], v[8:9], v[10:11], s[96:97] op_sel_hi:[1,1,0]
	v_pk_fma_f32 v[246:247], v[238:239], v[246:247], s[0:1] op_sel_hi:[1,1,0]
	v_pk_fma_f32 v[10:11], v[8:9], v[10:11], s[0:1] op_sel_hi:[1,1,0]
	v_pk_fma_f32 v[246:247], v[238:239], v[246:247], s[4:5] op_sel_hi:[1,1,0]
	v_pk_fma_f32 v[10:11], v[8:9], v[10:11], s[4:5] op_sel_hi:[1,1,0]
	v_pk_mul_f32 v[246:247], v[238:239], v[246:247]
	v_pk_mul_f32 v[10:11], v[8:9], v[10:11]
	v_max_f32_e32 v238, 0, v88
	v_max_f32_e32 v239, 0, v89
	v_max_f32_e32 v8, 0, v90
	v_max_f32_e32 v9, 0, v91
	v_pk_mul_f32 v[246:247], v[4:5], v[246:247]
	v_pk_mul_f32 v[10:11], v[16:17], v[10:11]
	v_pk_fma_f32 v[4:5], v[212:213], v[246:247], v[238:239] neg_lo:[1,0,0] neg_hi:[1,0,0]
	v_pk_fma_f32 v[16:17], v[6:7], v[10:11], v[8:9] neg_lo:[1,0,0] neg_hi:[1,0,0]
	v_pk_mul_f32 v[246:247], v[4:5], v[76:77]
	v_pk_mul_f32 v[10:11], v[16:17], v[78:79]
	v_cvt_pk_bf16_f32 v14, v246, v247
	v_cvt_pk_bf16_f32 v15, v10, v11
	v_add_u32_e32 v235, 129, v227
	v_add_u32_e32 v245, 130, v228
	v_cmp_gt_u32_e64 s[38:39], s64, v235
	v_cmp_gt_u32_e32 vcc, s88, v245
	v_add_u32_e32 v235, 732160, v230
	s_and_b64 s[38:39], s[38:39], vcc
	s_and_saveexec_b64 s[30:31], s[38:39]
	global_store_dwordx4 v235, v[12:15], s[50:51]
	s_mov_b64 exec, s[30:31]
	s_nop 1
	v_pk_fma_f32 v[72:73], v[40:41], v[72:73], v[152:153]
	v_pk_fma_f32 v[74:75], v[42:43], v[74:75], v[154:155]
	v_pk_fma_f32 v[64:65], v[60:61], v[64:65], v[156:157]
	v_pk_fma_f32 v[66:67], v[62:63], v[66:67], v[158:159]
	v_pk_fma_f32 v[72:73], v[0:1], v[84:85], v[72:73]
	v_pk_fma_f32 v[74:75], v[2:3], v[86:87], v[74:75]
	v_pk_fma_f32 v[64:65], v[128:129], v[92:93], v[64:65]
	v_pk_fma_f32 v[66:67], v[130:131], v[94:95], v[66:67]
	v_pk_fma_f32 v[72:73], v[124:125], v[20:21], v[72:73]
	v_pk_fma_f32 v[74:75], v[126:127], v[22:23], v[74:75]
	v_pk_fma_f32 v[64:65], v[132:133], v[24:25], v[64:65]
	v_pk_fma_f32 v[66:67], v[134:135], v[26:27], v[66:67]
	v_and_b32_e32 v212, 0x7fffffff, v72
	v_and_b32_e32 v213, 0x7fffffff, v73
	v_and_b32_e32 v6, 0x7fffffff, v74
	v_and_b32_e32 v7, 0x7fffffff, v75
	v_pk_fma_f32 v[238:239], v[212:213], s[90:91], 1.0 op_sel_hi:[1,0,0]
	v_pk_fma_f32 v[8:9], v[6:7], s[90:91], 1.0 op_sel_hi:[1,0,0]
	v_pk_mul_f32 v[4:5], v[72:73], v[72:73]
	v_pk_mul_f32 v[12:13], v[74:75], v[74:75]
	v_rcp_f32_e32 v238, v238
	v_rcp_f32_e32 v239, v239
	v_rcp_f32_e32 v8, v8
	v_rcp_f32_e32 v9, v9
	v_pk_mul_f32 v[4:5], v[4:5], s[44:45] op_sel_hi:[1,0]
	v_pk_mul_f32 v[12:13], v[12:13], s[44:45] op_sel_hi:[1,0]
	v_pk_fma_f32 v[246:247], v[238:239], s[92:93], v[236:237] op_sel_hi:[1,0,0]
	v_pk_fma_f32 v[10:11], v[8:9], s[92:93], v[236:237] op_sel_hi:[1,0,0]
	v_exp_f32_e32 v4, v4
	v_exp_f32_e32 v5, v5
	v_exp_f32_e32 v12, v12
	v_exp_f32_e32 v13, v13
	v_pk_fma_f32 v[246:247], v[238:239], v[246:247], s[96:97] op_sel_hi:[1,1,0]
	v_pk_fma_f32 v[10:11], v[8:9], v[10:11], s[96:97] op_sel_hi:[1,1,0]
	v_pk_fma_f32 v[246:247], v[238:239], v[246:247], s[0:1] op_sel_hi:[1,1,0]
	v_pk_fma_f32 v[10:11], v[8:9], v[10:11], s[0:1] op_sel_hi:[1,1,0]
	v_pk_fma_f32 v[246:247], v[238:239], v[246:247], s[4:5] op_sel_hi:[1,1,0]
	v_pk_fma_f32 v[10:11], v[8:9], v[10:11], s[4:5] op_sel_hi:[1,1,0]
	v_pk_mul_f32 v[246:247], v[238:239], v[246:247]
	v_pk_mul_f32 v[10:11], v[8:9], v[10:11]
	v_max_f32_e32 v238, 0, v72
	v_max_f32_e32 v239, 0, v73
	v_max_f32_e32 v8, 0, v74
	v_max_f32_e32 v9, 0, v75
	v_pk_mul_f32 v[246:247], v[4:5], v[246:247]
	v_pk_mul_f32 v[10:11], v[12:13], v[10:11]
	v_pk_fma_f32 v[4:5], v[212:213], v[246:247], v[238:239] neg_lo:[1,0,0] neg_hi:[1,0,0]
	v_pk_fma_f32 v[12:13], v[6:7], v[10:11], v[8:9] neg_lo:[1,0,0] neg_hi:[1,0,0]
	v_pk_mul_f32 v[246:247], v[4:5], v[64:65]
	v_pk_mul_f32 v[10:11], v[12:13], v[66:67]
	v_cvt_pk_bf16_f32 v166, v246, v247
	v_cvt_pk_bf16_f32 v167, v10, v11
	v_add_u32_e32 v235, 130, v227
	v_add_u32_e32 v245, 131, v228
	v_cmp_gt_u32_e64 s[38:39], s64, v235
	v_cmp_gt_u32_e32 vcc, s88, v245
	v_add_u32_e32 v235, 737792, v230
	s_and_b64 s[38:39], s[38:39], vcc
	s_and_saveexec_b64 s[30:31], s[38:39]
	global_store_dwordx4 v235, v[164:167], s[50:51]
	s_mov_b64 exec, s[30:31]
	s_nop 1
	s_branch .Lp5_done
